# intra-chunk retention phase: y tile stores staged through LDS into coalesced dwordx4 stores
# speedup vs baseline: 1.0180x; 1.0049x over previous
; #define MFMA32(a, b, c) __builtin_amdgcn_mfma_f32_32x32x16_bf16((a), (b), (c), 0, 0, 0)
; DI float log2_gamma(float x) { return -__builtin_amdgcn_logf(1.0f + __builtin_amdgcn_exp2f(-1.4426950408889634f * x)); }
; template <bool DRY, bool H1>
; DI void intra_phase(LAS unsigned char* lds, const Params& p) {
;     ...
;   for (int item = blockIdx.x; item < 512; item += gridDim.x) {
;     const int hd = item & 3, tb = (item >> 2) * 128;
;     const float lgf = log2_gamma(p.dec_f[hd]), lgb = log2_gamma(p.dec_b[hd]);
;     const int icol = 32 * ib + r;
;     {
;       bf16x8 qf[16];
;       const unsigned qo = (unsigned)(item) * 65536u + (unsigned)ib * 16384u + (unsigned)lane * 16u;
; #pragma unroll
;       for (int s = 0; s < 16; ++s) qf[s] = ldg16(qr, qo + 1024u * s);
; #pragma unroll
;       for (int jj = 0; jj < 2; ++jj) {
;         const int jt = 2 * wh + jj;
;         f32x16 pt;
; #pragma unroll
;         for (int i = 0; i < 16; ++i) pt[i] = 0.f;
;         const unsigned ko = (unsigned)(item) * 65536u + (unsigned)jt * 16384u + (unsigned)lane * 16u;
; #pragma unroll
;         for (int s = 0; s < 16; ++s) pt = MFMA32(ldg16(kr, ko + 1024u * s), qf[s], pt);
.LBB0_18:
	s_lshl_b32 s0, s2, 16
	v_or_b32_e32 v8, s0, v131
	v_add_u32_e32 v106, v8, v135
	global_load_dwordx4 v[0:3], v106, s[4:5]
	v_or_b32_e32 v110, s0, v132
	global_load_dwordx4 v[4:7], v110, s[92:93]
	v_or_b32_e32 v12, 0x400, v106
	global_load_dwordx4 v[32:35], v12, s[4:5]
	v_add_u32_e32 v114, v8, v168
	v_or_b32_e32 v88, 0x1400, v114
	v_or_b32_e32 v94, 0x1800, v106
	global_load_dwordx4 v[8:11], v114, s[4:5]
	v_or_b32_e32 v98, 0x1800, v114
	s_and_b32 s94, s2, 3
	s_lshl_b32 s0, s94, 2
	v_or_b32_e32 v102, 0x2c00, v110
	v_or_b32_e32 v117, 0x2800, v114
	v_or_b32_e32 v107, 0x3400, v110
	v_or_b32_e32 v118, 0x3000, v114
	v_or_b32_e32 v119, 0x3400, v114
	v_or_b32_e32 v120, 0x3800, v114
	v_or_b32_e32 v121, 0x3c00, v114
	s_waitcnt vmcnt(2)
	v_mfma_f32_32x32x16_bf16 v[16:31], v[0:3], v[4:7], 0
	v_or_b32_e32 v0, 0x1400, v110
	global_load_dwordx4 v[84:87], v0, s[92:93]
	v_or_b32_e32 v12, 0x400, v110
	global_load_dwordx4 v[36:39], v12, s[92:93]
	v_or_b32_e32 v12, 0x400, v114
	global_load_dwordx4 v[40:43], v12, s[4:5]
	s_nop 0
	global_load_dwordx4 v[88:91], v88, s[4:5]
	v_or_b32_e32 v12, 0x800, v106
	global_load_dwordx4 v[44:47], v12, s[4:5]
	s_waitcnt vmcnt(3)
	v_mfma_f32_32x32x16_bf16 v[16:31], v[32:35], v[36:39], v[16:31]
	global_load_dwordx4 v[32:35], v94, s[4:5]
	v_or_b32_e32 v12, 0x800, v110
	global_load_dwordx4 v[48:51], v12, s[92:93]
	v_or_b32_e32 v12, 0x800, v114
	global_load_dwordx4 v[52:55], v12, s[4:5]
	v_or_b32_e32 v94, 0x1800, v110
	global_load_dwordx4 v[94:97], v94, s[92:93]
	s_waitcnt vmcnt(2)
	v_mfma_f32_32x32x16_bf16 v[16:31], v[44:47], v[48:51], v[16:31]
	v_or_b32_e32 v44, 0x1c00, v110
	global_load_dwordx4 v[44:47], v44, s[92:93]
	v_or_b32_e32 v12, 0xc00, v106
	global_load_dwordx4 v[56:59], v12, s[4:5]
	v_or_b32_e32 v12, 0xc00, v110
	global_load_dwordx4 v[60:63], v12, s[92:93]
	v_or_b32_e32 v12, 0xc00, v114
	global_load_dwordx4 v[64:67], v12, s[4:5]
	s_waitcnt vmcnt(1)
	v_mfma_f32_32x32x16_bf16 v[16:31], v[56:59], v[60:63], v[16:31]
	v_or_b32_e32 v56, 0x2000, v110
	global_load_dwordx4 v[56:59], v56, s[92:93]
	v_or_b32_e32 v12, 0x1000, v106
	global_load_dwordx4 v[68:71], v12, s[4:5]
	v_or_b32_e32 v12, 0x1000, v110
	global_load_dwordx4 v[72:75], v12, s[92:93]
	v_or_b32_e32 v12, 0x1000, v114
	global_load_dwordx4 v[76:79], v12, s[4:5]
	v_or_b32_e32 v12, 0x1400, v106
	global_load_dwordx4 v[80:83], v12, s[4:5]
	v_mfma_f32_32x32x16_bf16 v[0:15], v[8:11], v[4:7], 0
	v_mfma_f32_32x32x16_bf16 v[0:15], v[40:43], v[36:39], v[0:15]
	global_load_dwordx4 v[36:39], v98, s[4:5]
	v_or_b32_e32 v40, 0x1c00, v106
	v_or_b32_e32 v98, 0x1c00, v114
	global_load_dwordx4 v[40:43], v40, s[4:5]
	v_mfma_f32_32x32x16_bf16 v[0:15], v[52:55], v[48:51], v[0:15]
	global_load_dwordx4 v[48:51], v98, s[4:5]
	v_mov_b32_e32 v98, s0
	v_readlane_b32 s0, v255, 17
	v_readlane_b32 s1, v255, 18
	v_or_b32_e32 v52, 0x2000, v106
	s_load_dwordx8 s[8:15], s[0:1], 0x40
	global_load_dwordx4 v[52:55], v52, s[4:5]
	s_waitcnt lgkmcnt(0)
	global_load_dword v115, v98, s[12:13]
	global_load_dword v116, v98, s[14:15]
	v_or_b32_e32 v98, 0x2000, v114
	s_waitcnt vmcnt(11)
	v_mfma_f32_32x32x16_bf16 v[0:15], v[64:67], v[60:63], v[0:15]
	global_load_dwordx4 v[60:63], v98, s[4:5]
	v_or_b32_e32 v64, 0x2400, v106
	global_load_dwordx4 v[64:67], v64, s[4:5]
	v_readlane_b32 s0, v255, 49
	v_readlane_b32 s1, v255, 50
	s_waitcnt vmcnt(10)
	v_mfma_f32_32x32x16_bf16 v[16:31], v[68:71], v[72:75], v[16:31]
	v_or_b32_e32 v68, 0x2400, v110
	global_load_dwordx4 v[68:71], v68, s[92:93]
	s_waitcnt vmcnt(10)
	v_mfma_f32_32x32x16_bf16 v[0:15], v[76:79], v[72:75], v[0:15]
	v_or_b32_e32 v76, 0x2800, v106
	global_load_dwordx4 v[76:79], v76, s[4:5]
	s_waitcnt vmcnt(10)
	v_mfma_f32_32x32x16_bf16 v[16:31], v[80:83], v[84:87], v[16:31]
	v_mfma_f32_32x32x16_bf16 v[0:15], v[88:91], v[84:87], v[0:15]
	global_load_dwordx4 v[84:87], v102, s[92:93]
	v_or_b32_e32 v88, 0x3000, v106
	global_load_dwordx4 v[88:91], v88, s[4:5]
	v_mfma_f32_32x32x16_bf16 v[16:31], v[32:35], v[94:97], v[16:31]
	s_waitcnt vmcnt(11)
	v_mfma_f32_32x32x16_bf16 v[0:15], v[36:39], v[94:97], v[0:15]
	global_load_dwordx4 v[36:39], v107, s[92:93]
	v_or_b32_e32 v107, 0x3800, v110
	v_or_b32_e32 v94, 0x3800, v106
	global_load_dwordx4 v[94:97], v94, s[4:5]
	s_waitcnt vmcnt(12)
	v_mfma_f32_32x32x16_bf16 v[16:31], v[40:43], v[44:47], v[16:31]
	global_load_dwordx4 v[40:43], v107, s[92:93]
	s_waitcnt vmcnt(12)
	v_mfma_f32_32x32x16_bf16 v[0:15], v[48:51], v[44:47], v[0:15]
	global_load_dwordx4 v[44:47], v117, s[4:5]
	v_or_b32_e32 v102, 0x3000, v110
	global_load_dwordx4 v[32:35], v102, s[92:93]
	v_or_b32_e32 v102, 0x3400, v106
	global_load_dwordx4 v[102:105], v102, s[4:5]
	v_or_b32_e32 v98, 0x2400, v114
	global_load_dwordx4 v[72:75], v98, s[4:5]
	v_or_b32_e32 v98, 0x2800, v110
	global_load_dwordx4 v[80:83], v98, s[92:93]
	v_or_b32_e32 v98, 0x2c00, v106
	global_load_dwordx4 v[98:101], v98, s[4:5]
	v_or_b32_e32 v48, 0x2c00, v114
	global_load_dwordx4 v[48:51], v48, s[4:5]
	v_or_b32_e32 v106, 0x3c00, v106
	v_or_b32_e32 v110, 0x3c00, v110
	s_waitcnt vmcnt(18)
	v_mfma_f32_32x32x16_bf16 v[16:31], v[52:55], v[56:59], v[16:31]
	s_waitcnt vmcnt(17)
	v_mul_f32_e32 v52, 0xbfb8aa3b, v115
	s_waitcnt vmcnt(16)
	v_mul_f32_e32 v53, 0xbfb8aa3b, v116
	global_load_dwordx4 v[106:109], v106, s[4:5]
	v_exp_f32_e32 v122, v52
	global_load_dwordx4 v[110:113], v110, s[92:93]
	v_exp_f32_e32 v123, v53
	global_load_dwordx4 v[52:55], v118, s[4:5]
	global_load_dwordx4 v[114:117], v119, s[4:5]
	s_waitcnt vmcnt(19)
	v_mfma_f32_32x32x16_bf16 v[0:15], v[60:63], v[56:59], v[0:15]
	v_add_f32_e32 v118, 1.0, v122
	v_add_f32_e32 v56, 1.0, v123
	v_log_f32_e32 v119, v56
	global_load_dwordx4 v[56:59], v120, s[4:5]
	global_load_dwordx4 v[60:63], v121, s[4:5]
	v_log_f32_e32 v118, v118
	v_mul_f32_e64 v121, v136, -v119
	s_waitcnt vmcnt(19)
; #define LAS __attribute__((address_space(3)))
; #define MFMA32(a, b, c) __builtin_amdgcn_mfma_f32_32x32x16_bf16((a), (b), (c), 0, 0, 0)
; #define EX2(x) __builtin_amdgcn_exp2f(x)
; template <bool DRY, bool H1>
; DI void intra_phase(LAS unsigned char* lds, const Params& p) {
;     ...
;       for (int jj = 0; jj < 2; ++jj) {
;         const int jt = 2 * wh + jj;
;         f32x16 pt;
; #pragma unroll
;         for (int i = 0; i < 16; ++i) pt[i] = 0.f;
;         const unsigned ko = (unsigned)(item) * 65536u + (unsigned)jt * 16384u + (unsigned)lane * 16u;
; #pragma unroll
;         for (int s = 0; s < 16; ++s) pt = MFMA32(ldg16(kr, ko + 1024u * s), qf[s], pt);
; #pragma unroll
;         for (int gq = 0; gq < 4; ++gq) {
;           float f[4];
; #pragma unroll
;           for (int e = 0; e < 4; ++e) {
;             const int df = icol - (32 * jt + 8 * gq + 4 * h + e);
;             f[e] = pt[4 * gq + e] * EX2(df >= 0 ? lgf * (float)df : lgb * (float)(-df));
;           }
;           u32x2 a; a.x = rne_pk(f[0], f[1]); a.y = rne_pk(f[2], f[3]);
;           *(LAS u32x2*)(Pimg + icol * 272 + (32 * jt + 8 * gq + 4 * h) * 2) = a;
;         }
;       }
;     }
;     __syncthreads();
	v_mfma_f32_32x32x16_bf16 v[16:31], v[64:67], v[68:71], v[16:31]
	v_mul_f32_e64 v120, v137, -v118
	v_mul_f32_e64 v64, v139, -v118
	v_mul_f32_e64 v65, v138, -v119
	v_mul_f32_e64 v66, v141, -v118
	v_mul_f32_e64 v67, v140, -v119
	v_mul_f32_e64 v122, v143, -v118
	v_mul_f32_e64 v123, v142, -v119
	v_mul_f32_e64 v124, v145, -v118
	v_cndmask_b32_e64 v65, v64, v65, s[74:75]
	v_cndmask_b32_e64 v66, v66, v67, s[76:77]
	v_cndmask_b32_e32 v67, v122, v123, vcc
	v_exp_f32_e32 v65, v65
	v_exp_f32_e32 v66, v66
	s_waitcnt vmcnt(8)
	v_mfma_f32_32x32x16_bf16 v[16:31], v[76:79], v[80:83], v[16:31]
	v_exp_f32_e32 v67, v67
	v_mul_f32_e64 v76, v152, -v119
	v_mul_f32_e64 v77, v155, -v118
	v_mul_f32_e64 v78, v154, -v119
	v_mul_f32_e64 v79, v157, -v118
	v_mul_f32_e64 v125, v156, -v119
	v_mul_f32_e64 v126, v159, -v118
	s_waitcnt vmcnt(7)
	v_mfma_f32_32x32x16_bf16 v[16:31], v[98:101], v[84:87], v[16:31]
	v_mul_f32_e64 v98, v158, -v119
	v_mul_f32_e64 v99, v161, -v118
	v_mul_f32_e64 v100, v160, -v119
	v_mul_f32_e64 v101, v163, -v118
	v_mul_f32_e64 v127, v162, -v119
	v_mul_f32_e64 v128, v165, -v118
	v_mul_f32_e64 v129, v164, -v119
	v_mfma_f32_32x32x16_bf16 v[0:15], v[72:75], v[68:71], v[0:15]
	v_mul_f32_e64 v68, v144, -v119
	v_mul_f32_e64 v69, v147, -v118
	v_mul_f32_e64 v70, v146, -v119
	v_mul_f32_e64 v71, v149, -v118
	v_mul_f32_e64 v72, v148, -v119
	v_mul_f32_e64 v73, v151, -v118
	v_mul_f32_e64 v74, v150, -v119
	v_mfma_f32_32x32x16_bf16 v[16:31], v[88:91], v[32:35], v[16:31]
	v_cndmask_b32_e64 v88, v120, v121, s[0:1]
	v_readlane_b32 s0, v255, 51
	v_readlane_b32 s1, v255, 52
	v_cndmask_b32_e64 v69, v69, v70, s[16:17]
	v_cndmask_b32_e64 v70, v71, v72, s[18:19]
	v_cndmask_b32_e64 v68, v124, v68, s[0:1]
	v_cndmask_b32_e64 v71, v73, v74, s[20:21]
	v_mfma_f32_32x32x16_bf16 v[0:15], v[44:47], v[80:83], v[0:15]
	v_exp_f32_e32 v64, v88
	v_exp_f32_e32 v68, v68
	v_exp_f32_e32 v69, v69
	v_exp_f32_e32 v70, v70
	v_exp_f32_e32 v71, v71
	v_mul_f32_e64 v75, v153, -v118
	v_cndmask_b32_e64 v72, v75, v76, s[22:23]
	v_mfma_f32_32x32x16_bf16 v[16:31], v[102:105], v[36:39], v[16:31]
	v_cndmask_b32_e64 v73, v77, v78, s[24:25]
	v_cndmask_b32_e64 v74, v79, v125, s[26:27]
	v_cndmask_b32_e64 v75, v126, v98, s[28:29]
	v_cndmask_b32_e64 v76, v99, v100, s[30:31]
	v_cndmask_b32_e64 v77, v101, v127, s[34:35]
	v_exp_f32_e32 v72, v72
	v_exp_f32_e32 v73, v73
	s_waitcnt vmcnt(6)
	v_mfma_f32_32x32x16_bf16 v[0:15], v[48:51], v[84:87], v[0:15]
	v_exp_f32_e32 v74, v74
	v_exp_f32_e32 v75, v75
	v_exp_f32_e32 v76, v76
	v_exp_f32_e32 v77, v77
	s_lshl_b32 s0, s2, 5
	s_and_b32 s0, s0, 0xffffff80
	v_mfma_f32_32x32x16_bf16 v[16:31], v[94:97], v[40:43], v[16:31]
	v_lshl_add_u32 v95, s2, 17, v133
	v_or_b32_e32 v94, s0, v130
	s_lshl_b32 s0, s94, 10
	s_waitcnt vmcnt(3)
	v_mfma_f32_32x32x16_bf16 v[0:15], v[52:55], v[32:35], v[0:15]
	v_mfma_f32_32x32x16_bf16 v[16:31], v[106:109], v[110:113], v[16:31]
	s_waitcnt vmcnt(2)
	v_mfma_f32_32x32x16_bf16 v[0:15], v[114:117], v[36:39], v[0:15]
	s_nop 9
	v_mul_f32_e64 v16, v64, v16
	v_mul_f32_e64 v17, v65, v17
	v_mul_f32_e64 v18, v66, v18
	v_mul_f32_e64 v19, v67, v19
	v_mul_f32_e64 v20, v68, v20
	v_mul_f32_e64 v21, v69, v21
	v_pk_mul_f32 v[22:23], v[70:71], v[22:23]
	v_cvt_pk_bf16_f32 v16, v16, v17
	v_cvt_pk_bf16_f32 v17, v18, v19
	v_cvt_pk_bf16_f32 v18, v20, v21
	v_cvt_pk_bf16_f32 v19, v22, v23
	s_waitcnt vmcnt(1)
	v_mfma_f32_32x32x16_bf16 v[0:15], v[56:59], v[40:43], v[0:15]
	ds_write2_b64 v218, v[16:17], v[18:19] offset1:2
	v_mul_f32_e64 v17, v167, -v118
	v_mul_f32_e64 v18, v166, -v119
	v_cndmask_b32_e64 v16, v128, v129, s[36:37]
	v_cndmask_b32_e64 v17, v17, v18, s[38:39]
	v_exp_f32_e32 v16, v16
	v_exp_f32_e32 v17, v17
	v_pk_mul_f32 v[24:25], v[72:73], v[24:25]
	v_pk_mul_f32 v[26:27], v[74:75], v[26:27]
	v_pk_mul_f32 v[18:19], v[76:77], v[28:29]
	v_pk_mul_f32 v[16:17], v[16:17], v[30:31]
	v_cvt_pk_bf16_f32 v20, v24, v25
	v_cvt_pk_bf16_f32 v21, v26, v27
	v_cvt_pk_bf16_f32 v18, v18, v19
	v_cvt_pk_bf16_f32 v19, v16, v17
	v_mul_f32_e64 v16, v170, -v118
	v_mul_f32_e64 v17, v169, -v119
	s_waitcnt vmcnt(0)
	v_mfma_f32_32x32x16_bf16 v[0:15], v[60:63], v[110:113], v[0:15]
	ds_write2_b64 v218, v[20:21], v[18:19] offset0:4 offset1:6
	v_cndmask_b32_e64 v16, v16, v17, s[40:41]
	v_mul_f32_e64 v17, v172, -v118
	v_mul_f32_e64 v18, v171, -v119
	v_cndmask_b32_e64 v17, v17, v18, s[42:43]
	v_mul_f32_e64 v18, v174, -v118
	v_mul_f32_e64 v19, v173, -v119
	v_cndmask_b32_e64 v18, v18, v19, s[44:45]
	v_mul_f32_e64 v19, v176, -v118
	v_mul_f32_e64 v20, v175, -v119
	v_exp_f32_e32 v16, v16
	v_exp_f32_e32 v17, v17
	v_cndmask_b32_e64 v19, v19, v20, s[46:47]
	v_exp_f32_e32 v18, v18
	v_exp_f32_e32 v19, v19
	v_pk_mul_f32 v[0:1], v[16:17], v[0:1]
	v_mul_f32_e64 v16, v179, -v118
	v_mul_f32_e64 v17, v178, -v119
	v_pk_mul_f32 v[2:3], v[18:19], v[2:3]
	v_cndmask_b32_e64 v16, v16, v17, s[48:49]
	v_mul_f32_e64 v17, v181, -v118
	v_mul_f32_e64 v18, v180, -v119
	v_cndmask_b32_e64 v17, v17, v18, s[50:51]
	v_mul_f32_e64 v18, v183, -v118
	v_mul_f32_e64 v19, v182, -v119
	v_cndmask_b32_e64 v18, v18, v19, s[52:53]
	v_mul_f32_e64 v19, v185, -v118
	v_mul_f32_e64 v20, v184, -v119
	v_exp_f32_e32 v16, v16
	v_exp_f32_e32 v17, v17
	v_cndmask_b32_e64 v19, v19, v20, s[54:55]
	v_exp_f32_e32 v18, v18
	v_exp_f32_e32 v19, v19
	v_cvt_pk_bf16_f32 v0, v0, v1
	v_cvt_pk_bf16_f32 v1, v2, v3
	v_pk_mul_f32 v[2:3], v[16:17], v[4:5]
	v_pk_mul_f32 v[4:5], v[18:19], v[6:7]
	v_cvt_pk_bf16_f32 v2, v2, v3
	v_mul_f32_e64 v3, v187, -v118
	v_mul_f32_e64 v6, v186, -v119
	v_cndmask_b32_e64 v3, v3, v6, s[56:57]
	v_exp_f32_e32 v6, v3
	v_mul_f32_e64 v3, v189, -v118
	v_mul_f32_e64 v7, v188, -v119
	v_cndmask_b32_e64 v3, v3, v7, s[58:59]
	v_exp_f32_e32 v7, v3
	v_mul_f32_e64 v3, v191, -v118
	v_mul_f32_e64 v16, v190, -v119
	v_cndmask_b32_e64 v3, v3, v16, s[60:61]
	v_exp_f32_e32 v16, v3
	v_mul_f32_e64 v3, v193, -v118
	v_mul_f32_e64 v17, v192, -v119
	v_cndmask_b32_e64 v3, v3, v17, s[62:63]
	v_exp_f32_e32 v17, v3
	v_cvt_pk_bf16_f32 v3, v4, v5
	v_mul_f32_e64 v4, v195, -v118
	v_mul_f32_e64 v5, v194, -v119
	ds_write2_b64 v219, v[0:1], v[2:3] offset1:2
	v_pk_mul_f32 v[0:1], v[6:7], v[8:9]
	v_cndmask_b32_e64 v4, v4, v5, s[64:65]
	v_mul_f32_e64 v5, v197, -v118
	v_mul_f32_e64 v6, v196, -v119
	v_cndmask_b32_e64 v5, v5, v6, s[66:67]
	v_mul_f32_e64 v6, v199, -v118
	v_mul_f32_e64 v7, v198, -v119
	v_cndmask_b32_e64 v6, v6, v7, s[68:69]
	v_mul_f32_e64 v7, v201, -v118
	v_mul_f32_e64 v8, v200, -v119
	v_cndmask_b32_e64 v7, v7, v8, s[70:71]
	v_exp_f32_e32 v4, v4
	v_exp_f32_e32 v5, v5
	v_exp_f32_e32 v6, v6
	v_exp_f32_e32 v7, v7
	v_pk_mul_f32 v[2:3], v[16:17], v[10:11]
	v_cvt_pk_bf16_f32 v0, v0, v1
	v_cvt_pk_bf16_f32 v1, v2, v3
	v_pk_mul_f32 v[2:3], v[4:5], v[12:13]
	v_pk_mul_f32 v[4:5], v[6:7], v[14:15]
	v_cvt_pk_bf16_f32 v2, v2, v3
	v_cvt_pk_bf16_f32 v3, v4, v5
	ds_write2_b64 v219, v[0:1], v[2:3] offset0:4 offset1:6
	s_waitcnt lgkmcnt(0)
	s_barrier
; #define LAS __attribute__((address_space(3)))
; DI unsigned cvt_pk_bf16(float lo, float hi) { unsigned r; asm volatile("v_cvt_pk_bf16_f32 %0, %1, %2" : "=v"(r) : "v"(lo), "v"(hi)); return r; }
; template <bool DRY, bool H1>
; DI void intra_phase(LAS unsigned char* lds, const Params& p) {
;     ...
;       bf16x8 pf[8];
; #pragma unroll
;       for (int s = 0; s < 8; ++s) pf[s] = *(const LAS bf16x8*)(Pimg + icol * 272 + (16 * s + 8 * h) * 2);
;       float sq2 = 0.f;
;       const unsigned vo = (unsigned)(item) * 131072u + (unsigned)(8 * wh) * 8192u + (unsigned)lane * 16u;
;       const unsigned yo = (unsigned)((tb + icol) * 2048 + hd * 512 + 256 * wh + 4 * h) * 2u;
;       bf16x8 va[2][8]; u32x2 yold[2][4], yol2[2][4];
; #pragma unroll
;       for (int gq = 0; gq < 4; ++gq) { yol2[0][gq] = (u32x2){0u, 0u}; yol2[1][gq] = (u32x2){0u, 0u}; }
; #pragma unroll
;       for (int s = 0; s < 8; ++s) va[0][s] = ldg16(vT, vo + 1024u * s);
; #pragma unroll
;       for (int gq = 0; gq < 4; ++gq) { yold[0][gq] = *(const u32x2*)((const char*)y + (yo + 16u * gq)); if constexpr (H1) yol2[0][gq] = *(const u32x2*)((const char*)yb + (yo + 16u * gq)); }
; #pragma unroll
;       for (int t = 0; t < 8; ++t) {
;         if (t < 7) {
; #pragma unroll
;           for (int s = 0; s < 8; ++s) va[(t + 1) & 1][s] = ldg16(vT, vo + (unsigned)(t + 1) * 8192u + 1024u * s);
; #pragma unroll
;           for (int gq = 0; gq < 4; ++gq) { yold[(t + 1) & 1][gq] = *(const u32x2*)((const char*)y + (yo + 64u * (t + 1) + 16u * gq)); if constexpr (H1) yol2[(t + 1) & 1][gq] = *(const u32x2*)((const char*)yb + (yo + 64u * (t + 1) + 16u * gq)); }
;         }
;         f32x16 yt;
; #pragma unroll
;         for (int i = 0; i < 16; ++i) yt[i] = 0.f;
; #pragma unroll
;         for (int s = 0; s < 8; ++s) yt = MFMA32(va[t & 1][s], pf[s], yt);
; #pragma unroll
;         for (int gq = 0; gq < 4; ++gq) {
;           const u32x2 ov = yold[t & 1][gq], o2 = yol2[t & 1][gq];
;           const float v0 = bf_lo(ov.x) + bf_lo(o2.x) + yt[4 * gq], v1 = bf_hi(ov.x) + bf_hi(o2.x) + yt[4 * gq + 1], v2 = bf_lo(ov.y) + bf_lo(o2.y) + yt[4 * gq + 2], v3 = bf_hi(ov.y) + bf_hi(o2.y) + yt[4 * gq + 3];
;           sq2 += v0 * v0 + v1 * v1 + v2 * v2 + v3 * v3;
;           u32x2 a; a.x = cvt_pk_bf16(v0, v1); a.y = cvt_pk_bf16(v2, v3); if (!DRY || v0 == 12345.678f) *(u32x2*)((char*)y + (yo + 64u * t + 16u * gq)) = a;
;         }
	global_load_dwordx4 v[0:3], v95, s[82:83]
	v_or_b32_e32 v4, 0x400, v95
	global_load_dwordx4 v[16:19], v4, s[82:83]
	v_or_b32_e32 v4, 0x800, v95
	global_load_dwordx4 v[20:23], v4, s[82:83]
	v_or_b32_e32 v4, 0xc00, v95
	global_load_dwordx4 v[48:51], v4, s[82:83]
	v_or_b32_e32 v4, 0x1000, v95
	global_load_dwordx4 v[52:55], v4, s[82:83]
	v_or_b32_e32 v4, 0x1400, v95
	global_load_dwordx4 v[56:59], v4, s[82:83]
	v_or_b32_e32 v4, 0x1800, v95
	global_load_dwordx4 v[60:63], v4, s[82:83]
	v_or_b32_e32 v4, 0x1c00, v95
	global_load_dwordx4 v[64:67], v4, s[82:83]
	ds_read_b128 v[40:43], v220
	ds_read_b128 v[36:39], v220 offset:32
	v_lshlrev_b32_e32 v4, 12, v94
	v_add3_u32 v203, v217, s0, v4
	s_waitcnt vmcnt(7) lgkmcnt(1)
	v_mfma_f32_32x32x16_bf16 v[0:15], v[0:3], v[40:43], 0
	v_or_b32_e32 v120, 16, v203
	global_load_dwordx2 v[72:73], v203, s[96:97]
	global_load_dwordx2 v[76:77], v203, s[6:7]
	global_load_dwordx2 v[96:97], v120, s[96:97]
	global_load_dwordx2 v[98:99], v120, s[6:7]
	v_or_b32_e32 v121, 32, v203
	v_or_b32_e32 v122, 48, v203
	v_or_b32_e32 v68, 0x2400, v95
	v_or_b32_e32 v69, 0x2c00, v95
	s_waitcnt vmcnt(10) lgkmcnt(0)
	v_mfma_f32_32x32x16_bf16 v[0:15], v[16:19], v[36:39], v[0:15]
	ds_read_b128 v[44:47], v220 offset:64
	ds_read_b128 v[16:19], v220 offset:96
	v_or_b32_e32 v206, 64, v203
	v_or_b32_e32 v207, 0x50, v203
	v_or_b32_e32 v208, 0x60, v203
	v_or_b32_e32 v209, 0x70, v203
	s_waitcnt vmcnt(9) lgkmcnt(1)
	v_mfma_f32_32x32x16_bf16 v[0:15], v[20:23], v[44:47], v[0:15]
	ds_read_b128 v[20:23], v220 offset:128
	ds_read_b128 v[24:27], v220 offset:160
	ds_read_b128 v[28:31], v220 offset:192
	ds_read_b128 v[32:35], v220 offset:224
	global_load_dwordx2 v[100:101], v121, s[96:97]
	global_load_dwordx2 v[102:103], v121, s[6:7]
	global_load_dwordx2 v[116:117], v122, s[96:97]
	global_load_dwordx2 v[118:119], v122, s[6:7]
	s_waitcnt vmcnt(12) lgkmcnt(4)
	v_mfma_f32_32x32x16_bf16 v[0:15], v[48:51], v[16:19], v[0:15]
	v_or_b32_e32 v48, 0x2000, v95
	global_load_dwordx4 v[48:51], v48, s[82:83]
	s_nop 0
	global_load_dwordx4 v[80:83], v68, s[82:83]
	v_or_b32_e32 v68, 0x2800, v95
	global_load_dwordx4 v[84:87], v68, s[82:83]
	global_load_dwordx4 v[88:91], v69, s[82:83]
	s_waitcnt vmcnt(15) lgkmcnt(3)
	v_mfma_f32_32x32x16_bf16 v[0:15], v[52:55], v[20:23], v[0:15]
	v_or_b32_e32 v52, 0x3000, v95
	v_or_b32_e32 v53, 0x3400, v95
	global_load_dwordx4 v[104:107], v52, s[82:83]
	global_load_dwordx4 v[108:111], v53, s[82:83]
	v_or_b32_e32 v52, 0x3800, v95
	v_or_b32_e32 v53, 0x3c00, v95
	global_load_dwordx4 v[112:115], v52, s[82:83]
	s_nop 0
	global_load_dwordx4 v[52:55], v53, s[82:83]
	s_nop 0
	global_load_dwordx2 v[128:129], v206, s[96:97]
	global_load_dwordx2 v[204:205], v206, s[6:7]
	s_waitcnt vmcnt(20) lgkmcnt(2)
	v_mfma_f32_32x32x16_bf16 v[0:15], v[56:59], v[24:27], v[0:15]
	global_load_dwordx2 v[74:75], v207, s[96:97]
	global_load_dwordx2 v[78:79], v207, s[6:7]
	global_load_dwordx2 v[68:69], v208, s[96:97]
	global_load_dwordx2 v[70:71], v208, s[6:7]
	s_waitcnt vmcnt(21)
	v_lshlrev_b32_e32 v56, 16, v72
	s_waitcnt lgkmcnt(1)
	v_mfma_f32_32x32x16_bf16 v[0:15], v[60:63], v[28:31], v[0:15]
	global_load_dwordx2 v[60:61], v209, s[96:97]
	global_load_dwordx2 v[62:63], v209, s[6:7]
	s_waitcnt vmcnt(22)
	v_lshlrev_b32_e32 v57, 16, v76
	v_add_f32_e32 v56, v57, v56
	v_and_b32_e32 v57, 0xffff0000, v72
	s_waitcnt lgkmcnt(0)
	v_mfma_f32_32x32x16_bf16 v[0:15], v[64:67], v[32:35], v[0:15]
	s_nop 11
	v_add_f32_e32 v0, v56, v0
	v_and_b32_e32 v56, 0xffff0000, v76
	v_add_f32_e32 v56, v56, v57
	v_add_f32_e32 v1, v56, v1
	v_lshlrev_b32_e32 v56, 16, v73
	v_lshlrev_b32_e32 v57, 16, v77
	v_add_f32_e32 v56, v57, v56
	v_add_f32_e32 v2, v56, v2
	v_and_b32_e32 v56, 0xffff0000, v77
	v_and_b32_e32 v57, 0xffff0000, v73
	v_add_f32_e32 v56, v56, v57
	v_add_f32_e32 v3, v56, v3
	v_mul_f32_e32 v56, v1, v1
	v_fmac_f32_e32 v56, v0, v0
	v_cvt_pk_bf16_f32 v0, v0, v1
	v_cvt_pk_bf16_f32 v1, v2, v3
	v_mbcnt_lo_u32_b32 v243, -1, 0
	v_mbcnt_hi_u32_b32 v243, -1, v243
	v_readlane_b32 s100, v255, 12
	v_and_b32_e32 v244, 31, v243
	v_lshrrev_b32_e32 v245, 5, v243
	v_lshrrev_b32_e32 v246, 2, v243
	v_and_b32_e32 v247, 3, v243
	v_mov_b32_e32 v248, s100
	v_mul_u32_u24_e32 v248, 36, v248
	v_add_u32_e32 v248, 0x1a000, v248
	v_mul_u32_u24_e32 v241, 0x48, v244
	v_lshl_add_u32 v241, v245, 3, v241
	v_add_u32_e32 v241, v248, v241
	v_mul_u32_u24_e32 v242, 0x48, v246
	v_lshl_add_u32 v242, v247, 4, v242
	v_add_u32_e32 v242, v248, v242
	v_sub_u32_e32 v240, v246, v244
	v_lshlrev_b32_e32 v240, 12, v240
	v_lshl_add_u32 v240, v247, 4, v240
	v_lshlrev_b32_e32 v245, 3, v245
	v_sub_u32_e32 v240, v240, v245
	v_add_u32_e32 v252, v203, v240
	ds_write_b64 v241, v[0:1]
	s_waitcnt vmcnt(21)
	v_lshlrev_b32_e32 v0, 16, v96
	s_waitcnt vmcnt(20)
	v_lshlrev_b32_e32 v1, 16, v98
	v_fmac_f32_e32 v56, v2, v2
	v_add_f32_e32 v0, v1, v0
	v_and_b32_e32 v1, 0xffff0000, v98
	v_and_b32_e32 v2, 0xffff0000, v96
	v_fmac_f32_e32 v56, v3, v3
	v_add_f32_e32 v1, v1, v2
	v_lshlrev_b32_e32 v2, 16, v97
	v_lshlrev_b32_e32 v3, 16, v99
	v_add_f32_e32 v0, v0, v4
	v_add_f32_e32 v1, v1, v5
	v_add_f32_e32 v2, v3, v2
	v_and_b32_e32 v3, 0xffff0000, v99
	v_and_b32_e32 v4, 0xffff0000, v97
	v_add_f32_e32 v3, v3, v4
	v_mul_f32_e32 v4, v1, v1
	v_add_f32_e32 v2, v2, v6
	v_add_f32_e32 v3, v3, v7
	v_fmac_f32_e32 v4, v0, v0
	v_cvt_pk_bf16_f32 v0, v0, v1
	v_cvt_pk_bf16_f32 v1, v2, v3
	ds_write_b64 v241, v[0:1] offset:16
	s_waitcnt vmcnt(19)
	v_lshlrev_b32_e32 v0, 16, v100
	s_waitcnt vmcnt(18)
; DI unsigned cvt_pk_bf16(float lo, float hi) { unsigned r; asm volatile("v_cvt_pk_bf16_f32 %0, %1, %2" : "=v"(r) : "v"(lo), "v"(hi)); return r; }
; DI float bf_lo(unsigned w) { return __uint_as_float(w << 16); }
; DI float bf_hi(unsigned w) { return __uint_as_float(w & 0xffff0000u); }
; #define MFMA32(a, b, c) __builtin_amdgcn_mfma_f32_32x32x16_bf16((a), (b), (c), 0, 0, 0)
; template <bool DRY, bool H1>
; DI void intra_phase(LAS unsigned char* lds, const Params& p) {
;     ...
;       for (int t = 0; t < 8; ++t) {
;         if (t < 7) {
; #pragma unroll
;           for (int s = 0; s < 8; ++s) va[(t + 1) & 1][s] = ldg16(vT, vo + (unsigned)(t + 1) * 8192u + 1024u * s);
; #pragma unroll
;           for (int gq = 0; gq < 4; ++gq) { yold[(t + 1) & 1][gq] = *(const u32x2*)((const char*)y + (yo + 64u * (t + 1) + 16u * gq)); if constexpr (H1) yol2[(t + 1) & 1][gq] = *(const u32x2*)((const char*)yb + (yo + 64u * (t + 1) + 16u * gq)); }
;         }
;         f32x16 yt;
; #pragma unroll
;         for (int i = 0; i < 16; ++i) yt[i] = 0.f;
; #pragma unroll
;         for (int s = 0; s < 8; ++s) yt = MFMA32(va[t & 1][s], pf[s], yt);
; #pragma unroll
;         for (int gq = 0; gq < 4; ++gq) {
;           const u32x2 ov = yold[t & 1][gq], o2 = yol2[t & 1][gq];
;           const float v0 = bf_lo(ov.x) + bf_lo(o2.x) + yt[4 * gq], v1 = bf_hi(ov.x) + bf_hi(o2.x) + yt[4 * gq + 1], v2 = bf_lo(ov.y) + bf_lo(o2.y) + yt[4 * gq + 2], v3 = bf_hi(ov.y) + bf_hi(o2.y) + yt[4 * gq + 3];
;           sq2 += v0 * v0 + v1 * v1 + v2 * v2 + v3 * v3;
;           u32x2 a; a.x = cvt_pk_bf16(v0, v1); a.y = cvt_pk_bf16(v2, v3); if (!DRY || v0 == 12345.678f) *(u32x2*)((char*)y + (yo + 64u * t + 16u * gq)) = a;
;         }
	v_lshlrev_b32_e32 v1, 16, v102
	v_fmac_f32_e32 v4, v2, v2
	v_add_f32_e32 v0, v1, v0
	v_and_b32_e32 v1, 0xffff0000, v102
	v_and_b32_e32 v2, 0xffff0000, v100
	v_fmac_f32_e32 v4, v3, v3
	v_add_f32_e32 v1, v1, v2
	v_lshlrev_b32_e32 v2, 16, v101
	v_lshlrev_b32_e32 v3, 16, v103
	v_add_f32_e32 v1, v1, v9
	v_add_f32_e32 v2, v3, v2
	v_and_b32_e32 v3, 0xffff0000, v103
	v_and_b32_e32 v5, 0xffff0000, v101
	v_add_f32_e32 v0, v0, v8
	v_add_f32_e32 v3, v3, v5
	v_mul_f32_e32 v5, v1, v1
	v_add_f32_e32 v2, v2, v10
	v_add_f32_e32 v3, v3, v11
	v_fmac_f32_e32 v5, v0, v0
	v_cvt_pk_bf16_f32 v0, v0, v1
	v_cvt_pk_bf16_f32 v1, v2, v3
	ds_write_b64 v241, v[0:1] offset:32
	s_waitcnt vmcnt(17)
	v_lshlrev_b32_e32 v0, 16, v116
	s_waitcnt vmcnt(16)
	v_lshlrev_b32_e32 v1, 16, v118
	v_fmac_f32_e32 v5, v2, v2
	v_add_f32_e32 v0, v1, v0
	v_and_b32_e32 v1, 0xffff0000, v118
	v_and_b32_e32 v2, 0xffff0000, v116
	v_add_f32_e32 v4, v56, v4
	v_fmac_f32_e32 v5, v3, v3
	v_add_f32_e32 v1, v1, v2
	v_lshlrev_b32_e32 v2, 16, v117
	v_lshlrev_b32_e32 v3, 16, v119
	v_add_f32_e32 v4, v5, v4
	v_add_f32_e32 v1, v1, v13
	v_add_f32_e32 v2, v3, v2
	v_and_b32_e32 v3, 0xffff0000, v119
	v_and_b32_e32 v5, 0xffff0000, v117
	v_add_f32_e32 v0, v0, v12
	v_add_f32_e32 v3, v3, v5
	v_mul_f32_e32 v5, v1, v1
	v_add_f32_e32 v2, v2, v14
	v_fmac_f32_e32 v5, v0, v0
	v_add_f32_e32 v3, v3, v15
	v_fmac_f32_e32 v5, v2, v2
	v_fmac_f32_e32 v5, v3, v3
	v_add_f32_e32 v96, v5, v4
	v_cvt_pk_bf16_f32 v0, v0, v1
	v_cvt_pk_bf16_f32 v1, v2, v3
	ds_write_b64 v241, v[0:1] offset:48
	s_waitcnt lgkmcnt(0)
	ds_read_b128 v[244:247], v242
	ds_read_b128 v[248:251], v242 offset:1152
	v_add_u32_e32 v253, 0x10000, v252
	s_waitcnt lgkmcnt(0)
	global_store_dwordx4 v252, v[244:247], s[96:97]
	global_store_dwordx4 v253, v[248:251], s[96:97]
	s_nop 1
	s_waitcnt vmcnt(17)
	v_mfma_f32_32x32x16_bf16 v[0:15], v[48:51], v[40:43], 0
	v_or_b32_e32 v48, 0x4000, v95
	v_or_b32_e32 v49, 0x4400, v95
	v_or_b32_e32 v50, 0x4800, v95
	global_load_dwordx4 v[116:119], v48, s[82:83]
	global_load_dwordx4 v[120:123], v49, s[82:83]
	v_or_b32_e32 v48, 0x4c00, v95
	global_load_dwordx4 v[124:127], v50, s[82:83]
	global_load_dwordx4 v[222:225], v48, s[82:83]
	v_or_b32_e32 v48, 0x5000, v95
	s_waitcnt vmcnt(20)
	v_mfma_f32_32x32x16_bf16 v[0:15], v[80:83], v[36:39], v[0:15]
	v_or_b32_e32 v49, 0x5400, v95
	global_load_dwordx4 v[226:229], v48, s[82:83]
	global_load_dwordx4 v[64:67], v49, s[82:83]
	v_or_b32_e32 v48, 0x5800, v95
	v_or_b32_e32 v49, 0x5c00, v95
	v_or_b32_e32 v210, 0x80, v203
	v_or_b32_e32 v211, 0x90, v203
	v_or_b32_e32 v215, 0xa0, v203
	s_waitcnt vmcnt(21)
	v_mfma_f32_32x32x16_bf16 v[0:15], v[84:87], v[44:47], v[0:15]
	v_or_b32_e32 v216, 0xb0, v203
	global_load_dwordx4 v[56:59], v48, s[82:83]
	s_nop 0
	global_load_dwordx4 v[48:51], v49, s[82:83]
	s_nop 0
	global_load_dwordx2 v[98:99], v210, s[96:97]
	global_load_dwordx2 v[102:103], v210, s[6:7]
	s_waitcnt vmcnt(19)
	v_lshlrev_b32_e32 v82, 16, v128
	s_waitcnt vmcnt(18)
	v_lshlrev_b32_e32 v83, 16, v204
	v_add_f32_e32 v82, v83, v82
	v_and_b32_e32 v83, 0xffff0000, v204
	v_mfma_f32_32x32x16_bf16 v[0:15], v[88:91], v[16:19], v[0:15]
	global_load_dwordx2 v[88:89], v211, s[96:97]
	global_load_dwordx2 v[90:91], v211, s[6:7]
	global_load_dwordx2 v[80:81], v215, s[96:97]
	global_load_dwordx2 v[84:85], v215, s[6:7]
	global_load_dwordx2 v[72:73], v216, s[96:97]
	global_load_dwordx2 v[76:77], v216, s[6:7]
	v_and_b32_e32 v86, 0xffff0000, v128
	v_add_f32_e32 v83, v83, v86
	v_lshlrev_b32_e32 v86, 16, v129
	v_lshlrev_b32_e32 v87, 16, v205
	v_mfma_f32_32x32x16_bf16 v[0:15], v[104:107], v[20:23], v[0:15]
	v_add_f32_e32 v86, v87, v86
	v_and_b32_e32 v87, 0xffff0000, v205
	v_and_b32_e32 v97, 0xffff0000, v129
	s_waitcnt vmcnt(23)
	v_lshlrev_b32_e32 v100, 16, v74
	v_add_f32_e32 v87, v87, v97
	s_waitcnt vmcnt(22)
	v_lshlrev_b32_e32 v97, 16, v78
	v_and_b32_e32 v78, 0xffff0000, v78
	v_mfma_f32_32x32x16_bf16 v[0:15], v[108:111], v[24:27], v[0:15]
	v_and_b32_e32 v74, 0xffff0000, v74
	v_add_f32_e32 v74, v78, v74
	v_add_f32_e32 v97, v97, v100
	v_lshlrev_b32_e32 v100, 16, v75
	v_lshlrev_b32_e32 v101, 16, v79
	v_mfma_f32_32x32x16_bf16 v[0:15], v[112:115], v[28:31], v[0:15]
	v_mfma_f32_32x32x16_bf16 v[0:15], v[52:55], v[32:35], v[0:15]
	s_nop 11
	v_add_f32_e32 v52, v82, v0
	v_add_f32_e32 v0, v83, v1
	v_mul_f32_e32 v53, v0, v0
	v_add_f32_e32 v2, v86, v2
	v_fmac_f32_e32 v53, v52, v52
	v_add_f32_e32 v3, v87, v3
	v_fmac_f32_e32 v53, v2, v2
	v_add_f32_e32 v5, v74, v5
	v_cvt_pk_bf16_f32 v0, v52, v0
	v_cvt_pk_bf16_f32 v1, v2, v3
	v_fmac_f32_e32 v53, v3, v3
	v_and_b32_e32 v2, 0xffff0000, v79
	v_and_b32_e32 v3, 0xffff0000, v75
	v_add_f32_e32 v4, v97, v4
	v_add_u32_e32 v252, v206, v240
	ds_write_b64 v241, v[0:1]
	v_add_f32_e32 v1, v101, v100
	v_add_f32_e32 v2, v2, v3
	v_mul_f32_e32 v3, v5, v5
	v_add_f32_e32 v1, v1, v6
	v_fmac_f32_e32 v3, v4, v4
	v_add_f32_e32 v2, v2, v7
	v_fmac_f32_e32 v3, v1, v1
	v_add_f32_e32 v0, v96, v53
	v_fmac_f32_e32 v3, v2, v2
	v_add_f32_e32 v3, v3, v0
	v_cvt_pk_bf16_f32 v0, v4, v5
	v_cvt_pk_bf16_f32 v1, v1, v2
	ds_write_b64 v241, v[0:1] offset:16
	s_waitcnt vmcnt(21)
	v_lshlrev_b32_e32 v0, 16, v68
	s_waitcnt vmcnt(20)
	v_lshlrev_b32_e32 v1, 16, v70
	v_add_f32_e32 v0, v1, v0
	v_and_b32_e32 v1, 0xffff0000, v70
	v_and_b32_e32 v2, 0xffff0000, v68
	v_add_f32_e32 v1, v1, v2
	v_lshlrev_b32_e32 v2, 16, v69
	v_lshlrev_b32_e32 v4, 16, v71
	v_add_f32_e32 v1, v1, v9
	v_add_f32_e32 v2, v4, v2
	v_and_b32_e32 v4, 0xffff0000, v71
	v_and_b32_e32 v5, 0xffff0000, v69
	v_add_f32_e32 v0, v0, v8
	v_add_f32_e32 v4, v4, v5
	v_mul_f32_e32 v5, v1, v1
	v_add_f32_e32 v2, v2, v10
	v_add_f32_e32 v4, v4, v11
	v_fmac_f32_e32 v5, v0, v0
	v_cvt_pk_bf16_f32 v0, v0, v1
	v_cvt_pk_bf16_f32 v1, v2, v4
	ds_write_b64 v241, v[0:1] offset:32
	s_waitcnt vmcnt(19)
; DI unsigned cvt_pk_bf16(float lo, float hi) { unsigned r; asm volatile("v_cvt_pk_bf16_f32 %0, %1, %2" : "=v"(r) : "v"(lo), "v"(hi)); return r; }
; DI float bf_lo(unsigned w) { return __uint_as_float(w << 16); }
; DI float bf_hi(unsigned w) { return __uint_as_float(w & 0xffff0000u); }
; #define MFMA32(a, b, c) __builtin_amdgcn_mfma_f32_32x32x16_bf16((a), (b), (c), 0, 0, 0)
; template <bool DRY, bool H1>
; DI void intra_phase(LAS unsigned char* lds, const Params& p) {
;     ...
;       for (int t = 0; t < 8; ++t) {
;         if (t < 7) {
; #pragma unroll
;           for (int s = 0; s < 8; ++s) va[(t + 1) & 1][s] = ldg16(vT, vo + (unsigned)(t + 1) * 8192u + 1024u * s);
; #pragma unroll
;           for (int gq = 0; gq < 4; ++gq) { yold[(t + 1) & 1][gq] = *(const u32x2*)((const char*)y + (yo + 64u * (t + 1) + 16u * gq)); if constexpr (H1) yol2[(t + 1) & 1][gq] = *(const u32x2*)((const char*)yb + (yo + 64u * (t + 1) + 16u * gq)); }
;         }
;         f32x16 yt;
; #pragma unroll
;         for (int i = 0; i < 16; ++i) yt[i] = 0.f;
; #pragma unroll
;         for (int s = 0; s < 8; ++s) yt = MFMA32(va[t & 1][s], pf[s], yt);
; #pragma unroll
;         for (int gq = 0; gq < 4; ++gq) {
;           const u32x2 ov = yold[t & 1][gq], o2 = yol2[t & 1][gq];
;           const float v0 = bf_lo(ov.x) + bf_lo(o2.x) + yt[4 * gq], v1 = bf_hi(ov.x) + bf_hi(o2.x) + yt[4 * gq + 1], v2 = bf_lo(ov.y) + bf_lo(o2.y) + yt[4 * gq + 2], v3 = bf_hi(ov.y) + bf_hi(o2.y) + yt[4 * gq + 3];
;           sq2 += v0 * v0 + v1 * v1 + v2 * v2 + v3 * v3;
;           u32x2 a; a.x = cvt_pk_bf16(v0, v1); a.y = cvt_pk_bf16(v2, v3); if (!DRY || v0 == 12345.678f) *(u32x2*)((char*)y + (yo + 64u * t + 16u * gq)) = a;
;         }
	v_lshlrev_b32_e32 v0, 16, v60
	s_waitcnt vmcnt(18)
	v_lshlrev_b32_e32 v1, 16, v62
	v_fmac_f32_e32 v5, v2, v2
	v_add_f32_e32 v0, v1, v0
	v_and_b32_e32 v1, 0xffff0000, v62
	v_and_b32_e32 v2, 0xffff0000, v60
	v_fmac_f32_e32 v5, v4, v4
	v_add_f32_e32 v1, v1, v2
	v_lshlrev_b32_e32 v2, 16, v61
	v_lshlrev_b32_e32 v4, 16, v63
	v_add_f32_e32 v3, v5, v3
	v_add_f32_e32 v1, v1, v13
	v_add_f32_e32 v2, v4, v2
	v_and_b32_e32 v4, 0xffff0000, v63
	v_and_b32_e32 v5, 0xffff0000, v61
	v_add_f32_e32 v0, v0, v12
	v_add_f32_e32 v4, v4, v5
	v_mul_f32_e32 v5, v1, v1
	v_add_f32_e32 v2, v2, v14
	v_fmac_f32_e32 v5, v0, v0
	v_add_f32_e32 v4, v4, v15
	v_fmac_f32_e32 v5, v2, v2
	v_fmac_f32_e32 v5, v4, v4
	v_add_f32_e32 v106, v5, v3
	v_cvt_pk_bf16_f32 v0, v0, v1
	v_cvt_pk_bf16_f32 v1, v2, v4
	ds_write_b64 v241, v[0:1] offset:48
	s_waitcnt lgkmcnt(0)
	ds_read_b128 v[244:247], v242
	ds_read_b128 v[248:251], v242 offset:1152
	v_add_u32_e32 v253, 0x10000, v252
	s_waitcnt lgkmcnt(0)
	global_store_dwordx4 v252, v[244:247], s[96:97]
	global_store_dwordx4 v253, v[248:251], s[96:97]
	s_nop 1
	s_waitcnt vmcnt(17)
	v_mfma_f32_32x32x16_bf16 v[0:15], v[116:119], v[40:43], 0
	v_or_b32_e32 v52, 0x6000, v95
	v_or_b32_e32 v53, 0x6400, v95
	v_or_b32_e32 v54, 0x6800, v95
	global_load_dwordx4 v[110:113], v52, s[82:83]
	global_load_dwordx4 v[114:117], v53, s[82:83]
	v_or_b32_e32 v52, 0x6c00, v95
	v_or_b32_e32 v53, 0x7400, v95
	v_or_b32_e32 v204, 0xc0, v203
	s_waitcnt vmcnt(18)
	v_mfma_f32_32x32x16_bf16 v[0:15], v[120:123], v[36:39], v[0:15]
	global_load_dwordx4 v[118:121], v54, s[82:83]
	global_load_dwordx4 v[230:233], v52, s[82:83]
	v_or_b32_e32 v52, 0x7000, v95
	global_load_dwordx4 v[234:237], v52, s[82:83]
	global_load_dwordx4 v[68:71], v53, s[82:83]
	v_or_b32_e32 v52, 0x7800, v95
	v_or_b32_e32 v53, 0x7c00, v95
	v_or_b32_e32 v205, 0xd0, v203
	v_or_b32_e32 v206, 0xe0, v203
	v_or_b32_e32 v207, 0xf0, v203
	global_load_dwordx4 v[60:63], v52, s[82:83]
	s_nop 0
	global_load_dwordx4 v[52:55], v53, s[82:83]
	s_nop 0
	global_load_dwordx2 v[104:105], v204, s[96:97]
	global_load_dwordx2 v[108:109], v204, s[6:7]
	global_load_dwordx2 v[96:97], v205, s[96:97]
	global_load_dwordx2 v[100:101], v205, s[6:7]
	global_load_dwordx2 v[82:83], v206, s[96:97]
	global_load_dwordx2 v[86:87], v206, s[6:7]
	global_load_dwordx2 v[74:75], v207, s[96:97]
	global_load_dwordx2 v[78:79], v207, s[6:7]
	s_waitcnt vmcnt(31)
	v_mfma_f32_32x32x16_bf16 v[0:15], v[124:127], v[44:47], v[0:15]
	s_waitcnt vmcnt(25)
	v_lshlrev_b32_e32 v107, 16, v98
	s_waitcnt vmcnt(24)
	v_lshlrev_b32_e32 v122, 16, v102
	v_and_b32_e32 v102, 0xffff0000, v102
	v_and_b32_e32 v98, 0xffff0000, v98
	v_add_f32_e32 v107, v122, v107
	v_add_f32_e32 v98, v102, v98
	v_mfma_f32_32x32x16_bf16 v[0:15], v[222:225], v[16:19], v[0:15]
	v_mfma_f32_32x32x16_bf16 v[0:15], v[226:229], v[20:23], v[0:15]
	v_mfma_f32_32x32x16_bf16 v[0:15], v[64:67], v[24:27], v[0:15]
	v_lshlrev_b32_e32 v64, 16, v99
	v_lshlrev_b32_e32 v65, 16, v103
	v_add_f32_e32 v64, v65, v64
	v_and_b32_e32 v65, 0xffff0000, v103
	v_and_b32_e32 v66, 0xffff0000, v99
	v_add_f32_e32 v65, v65, v66
	s_waitcnt vmcnt(23)
	v_lshlrev_b32_e32 v67, 16, v88
	v_mfma_f32_32x32x16_bf16 v[0:15], v[56:59], v[28:31], v[0:15]
	s_waitcnt vmcnt(22)
	v_and_b32_e32 v57, 0xffff0000, v90
	v_and_b32_e32 v58, 0xffff0000, v88
	v_lshlrev_b32_e32 v56, 16, v90
	v_add_f32_e32 v57, v57, v58
	v_add_f32_e32 v56, v56, v67
	v_lshlrev_b32_e32 v59, 16, v89
	v_lshlrev_b32_e32 v66, 16, v91
	v_mfma_f32_32x32x16_bf16 v[0:15], v[48:51], v[32:35], v[0:15]
	s_nop 11
	v_add_f32_e32 v48, v107, v0
	v_add_f32_e32 v0, v98, v1
	v_mul_f32_e32 v49, v0, v0
	v_add_f32_e32 v2, v64, v2
	v_fmac_f32_e32 v49, v48, v48
	v_add_f32_e32 v3, v65, v3
	v_fmac_f32_e32 v49, v2, v2
	v_add_f32_e32 v5, v57, v5
	v_cvt_pk_bf16_f32 v0, v48, v0
	v_cvt_pk_bf16_f32 v1, v2, v3
	v_fmac_f32_e32 v49, v3, v3
	v_and_b32_e32 v2, 0xffff0000, v91
	v_and_b32_e32 v3, 0xffff0000, v89
	v_add_f32_e32 v4, v56, v4
	v_add_u32_e32 v252, v210, v240
	ds_write_b64 v241, v[0:1]
	v_add_f32_e32 v1, v66, v59
	v_add_f32_e32 v2, v2, v3
	v_mul_f32_e32 v3, v5, v5
	v_add_f32_e32 v1, v1, v6
	v_fmac_f32_e32 v3, v4, v4
	v_add_f32_e32 v2, v2, v7
	v_fmac_f32_e32 v3, v1, v1
	v_add_f32_e32 v0, v106, v49
	v_fmac_f32_e32 v3, v2, v2
	v_add_f32_e32 v3, v3, v0
	v_cvt_pk_bf16_f32 v0, v4, v5
	v_cvt_pk_bf16_f32 v1, v1, v2
	ds_write_b64 v241, v[0:1] offset:16
	s_waitcnt vmcnt(21)
	v_lshlrev_b32_e32 v0, 16, v80
	s_waitcnt vmcnt(20)
	v_lshlrev_b32_e32 v1, 16, v84
	v_add_f32_e32 v0, v1, v0
	v_and_b32_e32 v1, 0xffff0000, v84
	v_and_b32_e32 v2, 0xffff0000, v80
	v_add_f32_e32 v1, v1, v2
	v_lshlrev_b32_e32 v2, 16, v81
	v_lshlrev_b32_e32 v4, 16, v85
	v_add_f32_e32 v1, v1, v9
	v_add_f32_e32 v2, v4, v2
	v_and_b32_e32 v4, 0xffff0000, v85
	v_and_b32_e32 v5, 0xffff0000, v81
	v_add_f32_e32 v0, v0, v8
	v_add_f32_e32 v4, v4, v5
	v_mul_f32_e32 v5, v1, v1
	v_add_f32_e32 v2, v2, v10
	v_add_f32_e32 v4, v4, v11
	v_fmac_f32_e32 v5, v0, v0
	v_cvt_pk_bf16_f32 v0, v0, v1
	v_cvt_pk_bf16_f32 v1, v2, v4
	ds_write_b64 v241, v[0:1] offset:32
	s_waitcnt vmcnt(19)
	v_lshlrev_b32_e32 v0, 16, v72
	s_waitcnt vmcnt(18)
	v_lshlrev_b32_e32 v1, 16, v76
	v_fmac_f32_e32 v5, v2, v2
	v_add_f32_e32 v0, v1, v0
	v_and_b32_e32 v1, 0xffff0000, v76
	v_and_b32_e32 v2, 0xffff0000, v72
	v_fmac_f32_e32 v5, v4, v4
	v_add_f32_e32 v1, v1, v2
	v_lshlrev_b32_e32 v2, 16, v73
	v_lshlrev_b32_e32 v4, 16, v77
	v_add_f32_e32 v3, v5, v3
	v_add_f32_e32 v1, v1, v13
	v_add_f32_e32 v2, v4, v2
	v_and_b32_e32 v4, 0xffff0000, v77
	v_and_b32_e32 v5, 0xffff0000, v73
	v_add_f32_e32 v0, v0, v12
	v_add_f32_e32 v4, v4, v5
	v_mul_f32_e32 v5, v1, v1
	v_add_f32_e32 v2, v2, v14
	v_fmac_f32_e32 v5, v0, v0
	v_add_f32_e32 v4, v4, v15
	v_fmac_f32_e32 v5, v2, v2
	v_fmac_f32_e32 v5, v4, v4
	v_add_f32_e32 v80, v5, v3
	v_cvt_pk_bf16_f32 v0, v0, v1
	v_cvt_pk_bf16_f32 v1, v2, v4
	ds_write_b64 v241, v[0:1] offset:48
	s_waitcnt lgkmcnt(0)
; DI unsigned cvt_pk_bf16(float lo, float hi) { unsigned r; asm volatile("v_cvt_pk_bf16_f32 %0, %1, %2" : "=v"(r) : "v"(lo), "v"(hi)); return r; }
; DI float bf_lo(unsigned w) { return __uint_as_float(w << 16); }
; DI float bf_hi(unsigned w) { return __uint_as_float(w & 0xffff0000u); }
; #define MFMA32(a, b, c) __builtin_amdgcn_mfma_f32_32x32x16_bf16((a), (b), (c), 0, 0, 0)
; template <bool DRY, bool H1>
; DI void intra_phase(LAS unsigned char* lds, const Params& p) {
;     ...
;       for (int t = 0; t < 8; ++t) {
;         if (t < 7) {
; #pragma unroll
;           for (int s = 0; s < 8; ++s) va[(t + 1) & 1][s] = ldg16(vT, vo + (unsigned)(t + 1) * 8192u + 1024u * s);
; #pragma unroll
;           for (int gq = 0; gq < 4; ++gq) { yold[(t + 1) & 1][gq] = *(const u32x2*)((const char*)y + (yo + 64u * (t + 1) + 16u * gq)); if constexpr (H1) yol2[(t + 1) & 1][gq] = *(const u32x2*)((const char*)yb + (yo + 64u * (t + 1) + 16u * gq)); }
;         }
;         f32x16 yt;
; #pragma unroll
;         for (int i = 0; i < 16; ++i) yt[i] = 0.f;
; #pragma unroll
;         for (int s = 0; s < 8; ++s) yt = MFMA32(va[t & 1][s], pf[s], yt);
; #pragma unroll
;         for (int gq = 0; gq < 4; ++gq) {
;           const u32x2 ov = yold[t & 1][gq], o2 = yol2[t & 1][gq];
;           const float v0 = bf_lo(ov.x) + bf_lo(o2.x) + yt[4 * gq], v1 = bf_hi(ov.x) + bf_hi(o2.x) + yt[4 * gq + 1], v2 = bf_lo(ov.y) + bf_lo(o2.y) + yt[4 * gq + 2], v3 = bf_hi(ov.y) + bf_hi(o2.y) + yt[4 * gq + 3];
;           sq2 += v0 * v0 + v1 * v1 + v2 * v2 + v3 * v3;
;           u32x2 a; a.x = cvt_pk_bf16(v0, v1); a.y = cvt_pk_bf16(v2, v3); if (!DRY || v0 == 12345.678f) *(u32x2*)((char*)y + (yo + 64u * t + 16u * gq)) = a;
;         }
	ds_read_b128 v[244:247], v242
	ds_read_b128 v[248:251], v242 offset:1152
	v_add_u32_e32 v253, 0x10000, v252
	s_waitcnt lgkmcnt(0)
	global_store_dwordx4 v252, v[244:247], s[96:97]
	global_store_dwordx4 v253, v[248:251], s[96:97]
	s_nop 1
	s_waitcnt vmcnt(17)
	v_mfma_f32_32x32x16_bf16 v[0:15], v[110:113], v[40:43], 0
	v_or_b32_e32 v48, 0x8000, v95
	v_or_b32_e32 v49, 0x8400, v95
	v_or_b32_e32 v50, 0x8800, v95
	global_load_dwordx4 v[122:125], v48, s[82:83]
	global_load_dwordx4 v[126:129], v49, s[82:83]
	v_or_b32_e32 v48, 0x8c00, v95
	v_or_b32_e32 v49, 0x9400, v95
	v_or_b32_e32 v208, 0x100, v203
	s_waitcnt vmcnt(18)
	v_mfma_f32_32x32x16_bf16 v[0:15], v[114:117], v[36:39], v[0:15]
	global_load_dwordx4 v[112:115], v50, s[82:83]
	global_load_dwordx4 v[222:225], v48, s[82:83]
	v_or_b32_e32 v48, 0x9000, v95
	global_load_dwordx4 v[226:229], v48, s[82:83]
	global_load_dwordx4 v[64:67], v49, s[82:83]
	v_or_b32_e32 v48, 0x9800, v95
	v_or_b32_e32 v49, 0x9c00, v95
	v_or_b32_e32 v209, 0x110, v203
	v_or_b32_e32 v210, 0x120, v203
	v_or_b32_e32 v211, 0x130, v203
	global_load_dwordx4 v[56:59], v48, s[82:83]
	s_nop 0
	global_load_dwordx4 v[48:51], v49, s[82:83]
	s_nop 0
	global_load_dwordx2 v[106:107], v208, s[96:97]
	global_load_dwordx2 v[110:111], v208, s[6:7]
	global_load_dwordx2 v[98:99], v209, s[96:97]
	global_load_dwordx2 v[102:103], v209, s[6:7]
	global_load_dwordx2 v[84:85], v210, s[96:97]
	global_load_dwordx2 v[90:91], v210, s[6:7]
	global_load_dwordx2 v[72:73], v211, s[96:97]
	global_load_dwordx2 v[76:77], v211, s[6:7]
	s_waitcnt vmcnt(31)
	v_mfma_f32_32x32x16_bf16 v[0:15], v[118:121], v[44:47], v[0:15]
	s_waitcnt vmcnt(25)
	v_lshlrev_b32_e32 v81, 16, v104
	s_waitcnt vmcnt(24)
	v_lshlrev_b32_e32 v88, 16, v108
	v_add_f32_e32 v81, v88, v81
	v_and_b32_e32 v88, 0xffff0000, v108
	v_and_b32_e32 v89, 0xffff0000, v104
	v_add_f32_e32 v88, v88, v89
	v_mfma_f32_32x32x16_bf16 v[0:15], v[230:233], v[16:19], v[0:15]
	v_mfma_f32_32x32x16_bf16 v[0:15], v[234:237], v[20:23], v[0:15]
	v_mfma_f32_32x32x16_bf16 v[0:15], v[68:71], v[24:27], v[0:15]
	v_lshlrev_b32_e32 v68, 16, v105
	v_lshlrev_b32_e32 v69, 16, v109
	v_add_f32_e32 v68, v69, v68
	v_and_b32_e32 v69, 0xffff0000, v109
	v_and_b32_e32 v70, 0xffff0000, v105
	v_add_f32_e32 v69, v69, v70
	s_waitcnt vmcnt(23)
	v_lshlrev_b32_e32 v71, 16, v96
	v_mfma_f32_32x32x16_bf16 v[0:15], v[60:63], v[28:31], v[0:15]
	s_waitcnt vmcnt(22)
	v_and_b32_e32 v61, 0xffff0000, v100
	v_and_b32_e32 v62, 0xffff0000, v96
	v_lshlrev_b32_e32 v60, 16, v100
	v_add_f32_e32 v61, v61, v62
	v_add_f32_e32 v60, v60, v71
	v_lshlrev_b32_e32 v63, 16, v97
	v_lshlrev_b32_e32 v70, 16, v101
	v_mfma_f32_32x32x16_bf16 v[0:15], v[52:55], v[32:35], v[0:15]
	s_nop 11
	v_add_f32_e32 v52, v81, v0
	v_add_f32_e32 v0, v88, v1
	v_mul_f32_e32 v53, v0, v0
	v_add_f32_e32 v2, v68, v2
	v_fmac_f32_e32 v53, v52, v52
	v_add_f32_e32 v3, v69, v3
	v_fmac_f32_e32 v53, v2, v2
	v_add_f32_e32 v5, v61, v5
	v_cvt_pk_bf16_f32 v0, v52, v0
	v_cvt_pk_bf16_f32 v1, v2, v3
	v_fmac_f32_e32 v53, v3, v3
	v_and_b32_e32 v2, 0xffff0000, v101
	v_and_b32_e32 v3, 0xffff0000, v97
	v_add_f32_e32 v4, v60, v4
	v_add_u32_e32 v252, v204, v240
	ds_write_b64 v241, v[0:1]
	v_add_f32_e32 v1, v70, v63
	v_add_f32_e32 v2, v2, v3
	v_mul_f32_e32 v3, v5, v5
	v_add_f32_e32 v1, v1, v6
	v_fmac_f32_e32 v3, v4, v4
	v_add_f32_e32 v2, v2, v7
	v_fmac_f32_e32 v3, v1, v1
	v_add_f32_e32 v0, v80, v53
	v_fmac_f32_e32 v3, v2, v2
	v_add_f32_e32 v3, v3, v0
	v_cvt_pk_bf16_f32 v0, v4, v5
	v_cvt_pk_bf16_f32 v1, v1, v2
	ds_write_b64 v241, v[0:1] offset:16
	s_waitcnt vmcnt(21)
	v_lshlrev_b32_e32 v0, 16, v82
	s_waitcnt vmcnt(20)
	v_lshlrev_b32_e32 v1, 16, v86
	v_add_f32_e32 v0, v1, v0
	v_and_b32_e32 v1, 0xffff0000, v86
	v_and_b32_e32 v2, 0xffff0000, v82
	v_add_f32_e32 v1, v1, v2
	v_lshlrev_b32_e32 v2, 16, v83
	v_lshlrev_b32_e32 v4, 16, v87
	v_add_f32_e32 v1, v1, v9
	v_add_f32_e32 v2, v4, v2
	v_and_b32_e32 v4, 0xffff0000, v87
	v_and_b32_e32 v5, 0xffff0000, v83
	v_add_f32_e32 v0, v0, v8
	v_add_f32_e32 v4, v4, v5
	v_mul_f32_e32 v5, v1, v1
	v_add_f32_e32 v2, v2, v10
	v_add_f32_e32 v4, v4, v11
	v_fmac_f32_e32 v5, v0, v0
	v_cvt_pk_bf16_f32 v0, v0, v1
	v_cvt_pk_bf16_f32 v1, v2, v4
	ds_write_b64 v241, v[0:1] offset:32
	s_waitcnt vmcnt(19)
	v_lshlrev_b32_e32 v0, 16, v74
	s_waitcnt vmcnt(18)
	v_lshlrev_b32_e32 v1, 16, v78
	v_fmac_f32_e32 v5, v2, v2
	v_add_f32_e32 v0, v1, v0
	v_and_b32_e32 v1, 0xffff0000, v78
	v_and_b32_e32 v2, 0xffff0000, v74
	v_fmac_f32_e32 v5, v4, v4
	v_add_f32_e32 v1, v1, v2
	v_lshlrev_b32_e32 v2, 16, v75
	v_lshlrev_b32_e32 v4, 16, v79
	v_add_f32_e32 v3, v5, v3
	v_add_f32_e32 v1, v1, v13
	v_add_f32_e32 v2, v4, v2
	v_and_b32_e32 v4, 0xffff0000, v79
	v_and_b32_e32 v5, 0xffff0000, v75
	v_add_f32_e32 v0, v0, v12
	v_add_f32_e32 v4, v4, v5
	v_mul_f32_e32 v5, v1, v1
	v_add_f32_e32 v2, v2, v14
	v_fmac_f32_e32 v5, v0, v0
	v_add_f32_e32 v4, v4, v15
	v_fmac_f32_e32 v5, v2, v2
	v_fmac_f32_e32 v5, v4, v4
	v_add_f32_e32 v74, v5, v3
	v_cvt_pk_bf16_f32 v0, v0, v1
	v_cvt_pk_bf16_f32 v1, v2, v4
	ds_write_b64 v241, v[0:1] offset:48
	s_waitcnt lgkmcnt(0)
	ds_read_b128 v[244:247], v242
	ds_read_b128 v[248:251], v242 offset:1152
	v_add_u32_e32 v253, 0x10000, v252
	s_waitcnt lgkmcnt(0)
	global_store_dwordx4 v252, v[244:247], s[96:97]
	global_store_dwordx4 v253, v[248:251], s[96:97]
	s_nop 1
	s_waitcnt vmcnt(17)
	v_mfma_f32_32x32x16_bf16 v[0:15], v[122:125], v[40:43], 0
	v_or_b32_e32 v52, 0xa000, v95
	v_or_b32_e32 v53, 0xa400, v95
	v_or_b32_e32 v54, 0xa800, v95
	global_load_dwordx4 v[116:119], v52, s[82:83]
	global_load_dwordx4 v[120:123], v53, s[82:83]
	v_or_b32_e32 v52, 0xac00, v95
	v_or_b32_e32 v53, 0xb400, v95
	v_or_b32_e32 v204, 0x140, v203
	s_waitcnt vmcnt(18)
; DI unsigned cvt_pk_bf16(float lo, float hi) { unsigned r; asm volatile("v_cvt_pk_bf16_f32 %0, %1, %2" : "=v"(r) : "v"(lo), "v"(hi)); return r; }
; DI float bf_lo(unsigned w) { return __uint_as_float(w << 16); }
; DI float bf_hi(unsigned w) { return __uint_as_float(w & 0xffff0000u); }
; #define MFMA32(a, b, c) __builtin_amdgcn_mfma_f32_32x32x16_bf16((a), (b), (c), 0, 0, 0)
; template <bool DRY, bool H1>
; DI void intra_phase(LAS unsigned char* lds, const Params& p) {
;     ...
;       for (int t = 0; t < 8; ++t) {
;         if (t < 7) {
; #pragma unroll
;           for (int s = 0; s < 8; ++s) va[(t + 1) & 1][s] = ldg16(vT, vo + (unsigned)(t + 1) * 8192u + 1024u * s);
; #pragma unroll
;           for (int gq = 0; gq < 4; ++gq) { yold[(t + 1) & 1][gq] = *(const u32x2*)((const char*)y + (yo + 64u * (t + 1) + 16u * gq)); if constexpr (H1) yol2[(t + 1) & 1][gq] = *(const u32x2*)((const char*)yb + (yo + 64u * (t + 1) + 16u * gq)); }
;         }
;         f32x16 yt;
; #pragma unroll
;         for (int i = 0; i < 16; ++i) yt[i] = 0.f;
; #pragma unroll
;         for (int s = 0; s < 8; ++s) yt = MFMA32(va[t & 1][s], pf[s], yt);
; #pragma unroll
;         for (int gq = 0; gq < 4; ++gq) {
;           const u32x2 ov = yold[t & 1][gq], o2 = yol2[t & 1][gq];
;           const float v0 = bf_lo(ov.x) + bf_lo(o2.x) + yt[4 * gq], v1 = bf_hi(ov.x) + bf_hi(o2.x) + yt[4 * gq + 1], v2 = bf_lo(ov.y) + bf_lo(o2.y) + yt[4 * gq + 2], v3 = bf_hi(ov.y) + bf_hi(o2.y) + yt[4 * gq + 3];
;           sq2 += v0 * v0 + v1 * v1 + v2 * v2 + v3 * v3;
;           u32x2 a; a.x = cvt_pk_bf16(v0, v1); a.y = cvt_pk_bf16(v2, v3); if (!DRY || v0 == 12345.678f) *(u32x2*)((char*)y + (yo + 64u * t + 16u * gq)) = a;
;         }
	v_mfma_f32_32x32x16_bf16 v[0:15], v[126:129], v[36:39], v[0:15]
	global_load_dwordx4 v[126:129], v54, s[82:83]
	global_load_dwordx4 v[230:233], v52, s[82:83]
	v_or_b32_e32 v52, 0xb000, v95
	global_load_dwordx4 v[234:237], v52, s[82:83]
	global_load_dwordx4 v[68:71], v53, s[82:83]
	v_or_b32_e32 v52, 0xb800, v95
	v_or_b32_e32 v53, 0xbc00, v95
	v_or_b32_e32 v205, 0x150, v203
	v_or_b32_e32 v206, 0x160, v203
	v_or_b32_e32 v207, 0x170, v203
	global_load_dwordx4 v[60:63], v52, s[82:83]
	s_nop 0
	global_load_dwordx4 v[52:55], v53, s[82:83]
	s_nop 0
	global_load_dwordx2 v[108:109], v204, s[96:97]
	global_load_dwordx2 v[124:125], v204, s[6:7]
	global_load_dwordx2 v[100:101], v205, s[96:97]
	global_load_dwordx2 v[104:105], v205, s[6:7]
	global_load_dwordx2 v[88:89], v206, s[96:97]
	global_load_dwordx2 v[96:97], v206, s[6:7]
	global_load_dwordx2 v[80:81], v207, s[96:97]
	global_load_dwordx2 v[82:83], v207, s[6:7]
	s_waitcnt vmcnt(31)
	v_mfma_f32_32x32x16_bf16 v[0:15], v[112:115], v[44:47], v[0:15]
	s_waitcnt vmcnt(25)
	v_lshlrev_b32_e32 v75, 16, v106
	s_waitcnt vmcnt(24)
	v_lshlrev_b32_e32 v78, 16, v110
	v_add_f32_e32 v75, v78, v75
	v_and_b32_e32 v78, 0xffff0000, v110
	v_and_b32_e32 v79, 0xffff0000, v106
	v_add_f32_e32 v78, v78, v79
	v_mfma_f32_32x32x16_bf16 v[0:15], v[222:225], v[16:19], v[0:15]
	v_mfma_f32_32x32x16_bf16 v[0:15], v[226:229], v[20:23], v[0:15]
	v_mfma_f32_32x32x16_bf16 v[0:15], v[64:67], v[24:27], v[0:15]
	v_lshlrev_b32_e32 v64, 16, v107
	v_lshlrev_b32_e32 v65, 16, v111
	v_add_f32_e32 v64, v65, v64
	v_and_b32_e32 v65, 0xffff0000, v111
	v_and_b32_e32 v66, 0xffff0000, v107
	v_add_f32_e32 v65, v65, v66
	s_waitcnt vmcnt(23)
	v_lshlrev_b32_e32 v67, 16, v98
	v_mfma_f32_32x32x16_bf16 v[0:15], v[56:59], v[28:31], v[0:15]
	s_waitcnt vmcnt(22)
	v_and_b32_e32 v57, 0xffff0000, v102
	v_and_b32_e32 v58, 0xffff0000, v98
	v_lshlrev_b32_e32 v56, 16, v102
	v_add_f32_e32 v57, v57, v58
	v_add_f32_e32 v56, v56, v67
	v_lshlrev_b32_e32 v59, 16, v99
	v_lshlrev_b32_e32 v66, 16, v103
	v_mfma_f32_32x32x16_bf16 v[0:15], v[48:51], v[32:35], v[0:15]
	s_nop 11
	v_add_f32_e32 v48, v75, v0
	v_add_f32_e32 v0, v78, v1
	v_mul_f32_e32 v49, v0, v0
	v_add_f32_e32 v2, v64, v2
	v_fmac_f32_e32 v49, v48, v48
	v_add_f32_e32 v3, v65, v3
	v_fmac_f32_e32 v49, v2, v2
	v_add_f32_e32 v5, v57, v5
	v_cvt_pk_bf16_f32 v0, v48, v0
	v_cvt_pk_bf16_f32 v1, v2, v3
	v_fmac_f32_e32 v49, v3, v3
	v_and_b32_e32 v2, 0xffff0000, v103
	v_and_b32_e32 v3, 0xffff0000, v99
	v_add_f32_e32 v4, v56, v4
	v_add_u32_e32 v252, v208, v240
	ds_write_b64 v241, v[0:1]
	v_add_f32_e32 v1, v66, v59
	v_add_f32_e32 v2, v2, v3
	v_mul_f32_e32 v3, v5, v5
	v_add_f32_e32 v1, v1, v6
	v_fmac_f32_e32 v3, v4, v4
	v_add_f32_e32 v2, v2, v7
	v_fmac_f32_e32 v3, v1, v1
	v_add_f32_e32 v0, v74, v49
	v_fmac_f32_e32 v3, v2, v2
	v_add_f32_e32 v3, v3, v0
	v_cvt_pk_bf16_f32 v0, v4, v5
	v_cvt_pk_bf16_f32 v1, v1, v2
	ds_write_b64 v241, v[0:1] offset:16
	s_waitcnt vmcnt(21)
	v_lshlrev_b32_e32 v0, 16, v84
	s_waitcnt vmcnt(20)
	v_lshlrev_b32_e32 v1, 16, v90
	v_add_f32_e32 v0, v1, v0
	v_and_b32_e32 v1, 0xffff0000, v90
	v_and_b32_e32 v2, 0xffff0000, v84
	v_add_f32_e32 v1, v1, v2
	v_lshlrev_b32_e32 v2, 16, v85
	v_lshlrev_b32_e32 v4, 16, v91
	v_add_f32_e32 v1, v1, v9
	v_add_f32_e32 v2, v4, v2
	v_and_b32_e32 v4, 0xffff0000, v91
	v_and_b32_e32 v5, 0xffff0000, v85
	v_add_f32_e32 v0, v0, v8
	v_add_f32_e32 v4, v4, v5
	v_mul_f32_e32 v5, v1, v1
	v_add_f32_e32 v2, v2, v10
	v_add_f32_e32 v4, v4, v11
	v_fmac_f32_e32 v5, v0, v0
	v_cvt_pk_bf16_f32 v0, v0, v1
	v_cvt_pk_bf16_f32 v1, v2, v4
	ds_write_b64 v241, v[0:1] offset:32
	s_waitcnt vmcnt(19)
	v_lshlrev_b32_e32 v0, 16, v72
	s_waitcnt vmcnt(18)
	v_lshlrev_b32_e32 v1, 16, v76
	v_fmac_f32_e32 v5, v2, v2
	v_add_f32_e32 v0, v1, v0
	v_and_b32_e32 v1, 0xffff0000, v76
	v_and_b32_e32 v2, 0xffff0000, v72
	v_fmac_f32_e32 v5, v4, v4
	v_add_f32_e32 v1, v1, v2
	v_lshlrev_b32_e32 v2, 16, v73
	v_lshlrev_b32_e32 v4, 16, v77
	v_add_f32_e32 v3, v5, v3
	v_add_f32_e32 v1, v1, v13
	v_add_f32_e32 v2, v4, v2
	v_and_b32_e32 v4, 0xffff0000, v77
	v_and_b32_e32 v5, 0xffff0000, v73
	v_add_f32_e32 v0, v0, v12
	v_add_f32_e32 v4, v4, v5
	v_mul_f32_e32 v5, v1, v1
	v_add_f32_e32 v2, v2, v14
	v_fmac_f32_e32 v5, v0, v0
	v_add_f32_e32 v4, v4, v15
	v_fmac_f32_e32 v5, v2, v2
	v_fmac_f32_e32 v5, v4, v4
	v_add_f32_e32 v90, v5, v3
	v_cvt_pk_bf16_f32 v0, v0, v1
	v_cvt_pk_bf16_f32 v1, v2, v4
	ds_write_b64 v241, v[0:1] offset:48
	s_waitcnt lgkmcnt(0)
	ds_read_b128 v[244:247], v242
	ds_read_b128 v[248:251], v242 offset:1152
	v_add_u32_e32 v253, 0x10000, v252
	s_waitcnt lgkmcnt(0)
	global_store_dwordx4 v252, v[244:247], s[96:97]
	global_store_dwordx4 v253, v[248:251], s[96:97]
	s_nop 1
	s_waitcnt vmcnt(17)
	v_mfma_f32_32x32x16_bf16 v[0:15], v[116:119], v[40:43], 0
	v_or_b32_e32 v48, 0xc000, v95
	v_or_b32_e32 v56, 0xc400, v95
	v_or_b32_e32 v64, 0xc800, v95
	v_or_b32_e32 v72, 0xcc00, v95
	global_load_dwordx4 v[48:51], v48, s[82:83]
	s_nop 0
	global_load_dwordx4 v[56:59], v56, s[82:83]
	s_nop 0
	global_load_dwordx4 v[64:67], v64, s[82:83]
	s_nop 0
	global_load_dwordx4 v[222:225], v72, s[82:83]
	v_or_b32_e32 v72, 0xd000, v95
	s_waitcnt vmcnt(20)
	v_mfma_f32_32x32x16_bf16 v[0:15], v[120:123], v[36:39], v[0:15]
	v_or_b32_e32 v73, 0xd400, v95
	global_load_dwordx4 v[226:229], v72, s[82:83]
	global_load_dwordx4 v[84:87], v73, s[82:83]
	v_or_b32_e32 v72, 0xd800, v95
	v_or_b32_e32 v73, 0xdc00, v95
	v_or_b32_e32 v208, 0x180, v203
	v_or_b32_e32 v209, 0x190, v203
	v_or_b32_e32 v210, 0x1a0, v203
	v_or_b32_e32 v211, 0x1b0, v203
	s_waitcnt vmcnt(21)
; DI unsigned cvt_pk_bf16(float lo, float hi) { unsigned r; asm volatile("v_cvt_pk_bf16_f32 %0, %1, %2" : "=v"(r) : "v"(lo), "v"(hi)); return r; }
; DI float bf_lo(unsigned w) { return __uint_as_float(w << 16); }
; DI float bf_hi(unsigned w) { return __uint_as_float(w & 0xffff0000u); }
; #define MFMA32(a, b, c) __builtin_amdgcn_mfma_f32_32x32x16_bf16((a), (b), (c), 0, 0, 0)
; template <bool DRY, bool H1>
; DI void intra_phase(LAS unsigned char* lds, const Params& p) {
;     ...
;       for (int t = 0; t < 8; ++t) {
;         if (t < 7) {
; #pragma unroll
;           for (int s = 0; s < 8; ++s) va[(t + 1) & 1][s] = ldg16(vT, vo + (unsigned)(t + 1) * 8192u + 1024u * s);
; #pragma unroll
;           for (int gq = 0; gq < 4; ++gq) { yold[(t + 1) & 1][gq] = *(const u32x2*)((const char*)y + (yo + 64u * (t + 1) + 16u * gq)); if constexpr (H1) yol2[(t + 1) & 1][gq] = *(const u32x2*)((const char*)yb + (yo + 64u * (t + 1) + 16u * gq)); }
;         }
;         f32x16 yt;
; #pragma unroll
;         for (int i = 0; i < 16; ++i) yt[i] = 0.f;
; #pragma unroll
;         for (int s = 0; s < 8; ++s) yt = MFMA32(va[t & 1][s], pf[s], yt);
; #pragma unroll
;         for (int gq = 0; gq < 4; ++gq) {
;           const u32x2 ov = yold[t & 1][gq], o2 = yol2[t & 1][gq];
;           const float v0 = bf_lo(ov.x) + bf_lo(o2.x) + yt[4 * gq], v1 = bf_hi(ov.x) + bf_hi(o2.x) + yt[4 * gq + 1], v2 = bf_lo(ov.y) + bf_lo(o2.y) + yt[4 * gq + 2], v3 = bf_hi(ov.y) + bf_hi(o2.y) + yt[4 * gq + 3];
;           sq2 += v0 * v0 + v1 * v1 + v2 * v2 + v3 * v3;
;           u32x2 a; a.x = cvt_pk_bf16(v0, v1); a.y = cvt_pk_bf16(v2, v3); if (!DRY || v0 == 12345.678f) *(u32x2*)((char*)y + (yo + 64u * t + 16u * gq)) = a;
;         }
	v_mfma_f32_32x32x16_bf16 v[0:15], v[126:129], v[44:47], v[0:15]
	global_load_dwordx4 v[76:79], v72, s[82:83]
	s_nop 0
	global_load_dwordx4 v[72:75], v73, s[82:83]
	s_nop 0
	global_load_dwordx2 v[126:127], v208, s[96:97]
	global_load_dwordx2 v[128:129], v208, s[6:7]
	global_load_dwordx2 v[120:121], v209, s[96:97]
	global_load_dwordx2 v[122:123], v209, s[6:7]
	global_load_dwordx2 v[116:117], v210, s[96:97]
	global_load_dwordx2 v[118:119], v210, s[6:7]
	global_load_dwordx2 v[112:113], v211, s[96:97]
	global_load_dwordx2 v[114:115], v211, s[6:7]
	s_waitcnt vmcnt(25)
	v_lshlrev_b32_e32 v91, 16, v108
	s_waitcnt vmcnt(24)
	v_lshlrev_b32_e32 v98, 16, v124
	v_mfma_f32_32x32x16_bf16 v[0:15], v[230:233], v[16:19], v[0:15]
	v_add_f32_e32 v91, v98, v91
	v_and_b32_e32 v98, 0xffff0000, v124
	v_and_b32_e32 v99, 0xffff0000, v108
	v_add_f32_e32 v98, v98, v99
	v_mfma_f32_32x32x16_bf16 v[0:15], v[234:237], v[20:23], v[0:15]
	v_mfma_f32_32x32x16_bf16 v[0:15], v[68:71], v[24:27], v[0:15]
	v_lshlrev_b32_e32 v68, 16, v109
	v_lshlrev_b32_e32 v69, 16, v125
	v_add_f32_e32 v68, v69, v68
	v_and_b32_e32 v69, 0xffff0000, v125
	v_and_b32_e32 v70, 0xffff0000, v109
	v_add_f32_e32 v69, v69, v70
	s_waitcnt vmcnt(23)
	v_lshlrev_b32_e32 v71, 16, v100
	v_mfma_f32_32x32x16_bf16 v[0:15], v[60:63], v[28:31], v[0:15]
	s_waitcnt vmcnt(22)
	v_and_b32_e32 v61, 0xffff0000, v104
	v_and_b32_e32 v62, 0xffff0000, v100
	v_lshlrev_b32_e32 v60, 16, v104
	v_add_f32_e32 v61, v61, v62
	v_add_f32_e32 v60, v60, v71
	v_lshlrev_b32_e32 v63, 16, v101
	v_lshlrev_b32_e32 v70, 16, v105
	v_mfma_f32_32x32x16_bf16 v[0:15], v[52:55], v[32:35], v[0:15]
	s_nop 11
	v_add_f32_e32 v52, v91, v0
	v_add_f32_e32 v0, v98, v1
	v_mul_f32_e32 v53, v0, v0
	v_add_f32_e32 v2, v68, v2
	v_fmac_f32_e32 v53, v52, v52
	v_add_f32_e32 v3, v69, v3
	v_fmac_f32_e32 v53, v2, v2
	v_add_f32_e32 v5, v61, v5
	v_cvt_pk_bf16_f32 v0, v52, v0
	v_cvt_pk_bf16_f32 v1, v2, v3
	v_fmac_f32_e32 v53, v3, v3
	v_and_b32_e32 v2, 0xffff0000, v105
	v_and_b32_e32 v3, 0xffff0000, v101
	v_add_f32_e32 v4, v60, v4
	v_add_u32_e32 v252, v204, v240
	ds_write_b64 v241, v[0:1]
	v_add_f32_e32 v1, v70, v63
	v_add_f32_e32 v2, v2, v3
	v_mul_f32_e32 v3, v5, v5
	v_add_f32_e32 v1, v1, v6
	v_fmac_f32_e32 v3, v4, v4
	v_add_f32_e32 v2, v2, v7
	v_fmac_f32_e32 v3, v1, v1
	v_add_f32_e32 v0, v90, v53
	v_fmac_f32_e32 v3, v2, v2
	v_add_f32_e32 v3, v3, v0
	v_cvt_pk_bf16_f32 v0, v4, v5
	v_cvt_pk_bf16_f32 v1, v1, v2
	ds_write_b64 v241, v[0:1] offset:16
	s_waitcnt vmcnt(21)
	v_lshlrev_b32_e32 v0, 16, v88
	s_waitcnt vmcnt(20)
	v_lshlrev_b32_e32 v1, 16, v96
	v_add_f32_e32 v0, v1, v0
	v_and_b32_e32 v1, 0xffff0000, v96
	v_and_b32_e32 v2, 0xffff0000, v88
	v_add_f32_e32 v1, v1, v2
	v_lshlrev_b32_e32 v2, 16, v89
	v_lshlrev_b32_e32 v4, 16, v97
	v_add_f32_e32 v1, v1, v9
	v_add_f32_e32 v2, v4, v2
	v_and_b32_e32 v4, 0xffff0000, v97
	v_and_b32_e32 v5, 0xffff0000, v89
	v_add_f32_e32 v0, v0, v8
	v_add_f32_e32 v4, v4, v5
	v_mul_f32_e32 v5, v1, v1
	v_add_f32_e32 v2, v2, v10
	v_add_f32_e32 v4, v4, v11
	v_fmac_f32_e32 v5, v0, v0
	v_cvt_pk_bf16_f32 v0, v0, v1
	v_cvt_pk_bf16_f32 v1, v2, v4
	ds_write_b64 v241, v[0:1] offset:32
	s_waitcnt vmcnt(19)
	v_lshlrev_b32_e32 v0, 16, v80
	s_waitcnt vmcnt(18)
	v_lshlrev_b32_e32 v1, 16, v82
	v_fmac_f32_e32 v5, v2, v2
	v_add_f32_e32 v0, v1, v0
	v_and_b32_e32 v1, 0xffff0000, v82
	v_and_b32_e32 v2, 0xffff0000, v80
	v_fmac_f32_e32 v5, v4, v4
	v_add_f32_e32 v1, v1, v2
	v_lshlrev_b32_e32 v2, 16, v81
	v_lshlrev_b32_e32 v4, 16, v83
	v_add_f32_e32 v3, v5, v3
	v_add_f32_e32 v1, v1, v13
	v_add_f32_e32 v2, v4, v2
	v_and_b32_e32 v4, 0xffff0000, v83
	v_and_b32_e32 v5, 0xffff0000, v81
	v_add_f32_e32 v0, v0, v12
	v_add_f32_e32 v4, v4, v5
	v_mul_f32_e32 v5, v1, v1
	v_add_f32_e32 v2, v2, v14
	v_fmac_f32_e32 v5, v0, v0
	v_add_f32_e32 v4, v4, v15
	v_fmac_f32_e32 v5, v2, v2
	v_fmac_f32_e32 v5, v4, v4
	v_add_f32_e32 v204, v5, v3
	v_cvt_pk_bf16_f32 v0, v0, v1
	v_cvt_pk_bf16_f32 v1, v2, v4
	ds_write_b64 v241, v[0:1] offset:48
	s_waitcnt lgkmcnt(0)
	ds_read_b128 v[244:247], v242
	ds_read_b128 v[248:251], v242 offset:1152
	v_add_u32_e32 v253, 0x10000, v252
	s_waitcnt lgkmcnt(0)
	global_store_dwordx4 v252, v[244:247], s[96:97]
	global_store_dwordx4 v253, v[248:251], s[96:97]
	s_nop 1
	s_waitcnt vmcnt(17)
	v_mfma_f32_32x32x16_bf16 v[0:15], v[48:51], v[40:43], 0
	v_or_b32_e32 v48, 0xe000, v95
	v_or_b32_e32 v49, 0xe400, v95
	v_or_b32_e32 v50, 0xe800, v95
	v_or_b32_e32 v51, 0xec00, v95
	v_or_b32_e32 v52, 0xf000, v95
	v_or_b32_e32 v60, 0xf800, v95
	v_or_b32_e32 v205, 0x1c0, v203
	s_waitcnt vmcnt(16)
	v_mfma_f32_32x32x16_bf16 v[0:15], v[56:59], v[36:39], v[0:15]
	v_or_b32_e32 v56, 0xf400, v95
	v_or_b32_e32 v125, 0x1d0, v203
	v_or_b32_e32 v124, 0x1e0, v203
	global_load_dwordx4 v[88:91], v48, s[82:83]
	global_load_dwordx4 v[80:83], v49, s[82:83]
	global_load_dwordx4 v[68:71], v50, s[82:83]
	s_nop 0
	global_load_dwordx4 v[48:51], v51, s[82:83]
	s_nop 0
	global_load_dwordx4 v[52:55], v52, s[82:83]
	s_nop 0
	global_load_dwordx4 v[56:59], v56, s[82:83]
	s_waitcnt vmcnt(14)
	v_lshlrev_b32_e32 v206, 16, v128
	v_mfma_f32_32x32x16_bf16 v[0:15], v[64:67], v[44:47], v[0:15]
	v_or_b32_e32 v64, 0xfc00, v95
	v_or_b32_e32 v95, 0x1f0, v203
	global_load_dwordx4 v[60:63], v60, s[82:83]
	s_nop 0
	global_load_dwordx4 v[64:67], v64, s[82:83]
	s_nop 0
	global_load_dwordx2 v[108:109], v205, s[96:97]
	global_load_dwordx2 v[110:111], v205, s[6:7]
	global_load_dwordx2 v[104:105], v125, s[96:97]
	global_load_dwordx2 v[106:107], v125, s[6:7]
	global_load_dwordx2 v[100:101], v124, s[96:97]
	global_load_dwordx2 v[102:103], v124, s[6:7]
	global_load_dwordx2 v[96:97], v95, s[96:97]
	global_load_dwordx2 v[98:99], v95, s[6:7]
	v_mfma_f32_32x32x16_bf16 v[0:15], v[222:225], v[16:19], v[0:15]
	v_lshlrev_b32_e32 v203, 16, v126
	v_add_f32_e32 v203, v206, v203
	v_and_b32_e32 v128, 0xffff0000, v128
	v_and_b32_e32 v126, 0xffff0000, v126
	v_lshlrev_b32_e32 v206, 16, v127
	v_add_f32_e32 v126, v128, v126
	v_mfma_f32_32x32x16_bf16 v[0:15], v[226:229], v[20:23], v[0:15]
	v_mfma_f32_32x32x16_bf16 v[0:15], v[84:87], v[24:27], v[0:15]
	v_lshlrev_b32_e32 v84, 16, v129
	v_and_b32_e32 v85, 0xffff0000, v129
	v_and_b32_e32 v86, 0xffff0000, v127
	v_add_f32_e32 v84, v84, v206
	v_add_f32_e32 v85, v85, v86
	s_waitcnt vmcnt(23)
; DI unsigned cvt_pk_bf16(float lo, float hi) { unsigned r; asm volatile("v_cvt_pk_bf16_f32 %0, %1, %2" : "=v"(r) : "v"(lo), "v"(hi)); return r; }
; DI float bf_lo(unsigned w) { return __uint_as_float(w << 16); }
; DI float bf_hi(unsigned w) { return __uint_as_float(w & 0xffff0000u); }
; #define MFMA32(a, b, c) __builtin_amdgcn_mfma_f32_32x32x16_bf16((a), (b), (c), 0, 0, 0)
; template <bool DRY, bool H1>
; DI void intra_phase(LAS unsigned char* lds, const Params& p) {
;     ...
;       for (int t = 0; t < 8; ++t) {
;         if (t < 7) {
; #pragma unroll
;           for (int s = 0; s < 8; ++s) va[(t + 1) & 1][s] = ldg16(vT, vo + (unsigned)(t + 1) * 8192u + 1024u * s);
; #pragma unroll
;           for (int gq = 0; gq < 4; ++gq) { yold[(t + 1) & 1][gq] = *(const u32x2*)((const char*)y + (yo + 64u * (t + 1) + 16u * gq)); if constexpr (H1) yol2[(t + 1) & 1][gq] = *(const u32x2*)((const char*)yb + (yo + 64u * (t + 1) + 16u * gq)); }
;         }
;         f32x16 yt;
; #pragma unroll
;         for (int i = 0; i < 16; ++i) yt[i] = 0.f;
; #pragma unroll
;         for (int s = 0; s < 8; ++s) yt = MFMA32(va[t & 1][s], pf[s], yt);
; #pragma unroll
;         for (int gq = 0; gq < 4; ++gq) {
;           const u32x2 ov = yold[t & 1][gq], o2 = yol2[t & 1][gq];
;           const float v0 = bf_lo(ov.x) + bf_lo(o2.x) + yt[4 * gq], v1 = bf_hi(ov.x) + bf_hi(o2.x) + yt[4 * gq + 1], v2 = bf_lo(ov.y) + bf_lo(o2.y) + yt[4 * gq + 2], v3 = bf_hi(ov.y) + bf_hi(o2.y) + yt[4 * gq + 3];
;           sq2 += v0 * v0 + v1 * v1 + v2 * v2 + v3 * v3;
;           u32x2 a; a.x = cvt_pk_bf16(v0, v1); a.y = cvt_pk_bf16(v2, v3); if (!DRY || v0 == 12345.678f) *(u32x2*)((char*)y + (yo + 64u * t + 16u * gq)) = a;
;         }
	v_lshlrev_b32_e32 v87, 16, v120
	s_waitcnt vmcnt(22)
	v_lshlrev_b32_e32 v127, 16, v122
	v_mfma_f32_32x32x16_bf16 v[0:15], v[76:79], v[28:31], v[0:15]
	v_and_b32_e32 v77, 0xffff0000, v122
	v_and_b32_e32 v78, 0xffff0000, v120
	v_add_f32_e32 v77, v77, v78
	v_lshlrev_b32_e32 v78, 16, v121
	v_lshlrev_b32_e32 v79, 16, v123
	v_add_f32_e32 v76, v127, v87
	v_add_f32_e32 v78, v79, v78
	v_mfma_f32_32x32x16_bf16 v[0:15], v[72:75], v[32:35], v[0:15]
	s_nop 11
	v_add_f32_e32 v72, v203, v0
	v_add_f32_e32 v73, v126, v1
	v_add_f32_e32 v2, v84, v2
	v_add_f32_e32 v3, v85, v3
	v_cvt_pk_bf16_f32 v0, v72, v73
	v_cvt_pk_bf16_f32 v1, v2, v3
	v_add_u32_e32 v252, v208, v240
	ds_write_b64 v241, v[0:1]
	v_and_b32_e32 v0, 0xffff0000, v123
	v_and_b32_e32 v1, 0xffff0000, v121
	v_add_f32_e32 v0, v0, v1
	v_add_f32_e32 v4, v76, v4
	v_add_f32_e32 v5, v77, v5
	v_add_f32_e32 v6, v78, v6
	v_add_f32_e32 v7, v0, v7
	v_cvt_pk_bf16_f32 v0, v4, v5
	v_cvt_pk_bf16_f32 v1, v6, v7
	ds_write_b64 v241, v[0:1] offset:16
	s_waitcnt vmcnt(21)
	v_lshlrev_b32_e32 v0, 16, v116
	s_waitcnt vmcnt(20)
	v_lshlrev_b32_e32 v1, 16, v118
	v_add_f32_e32 v0, v1, v0
	v_add_f32_e32 v8, v0, v8
	v_and_b32_e32 v0, 0xffff0000, v118
	v_and_b32_e32 v1, 0xffff0000, v116
	v_add_f32_e32 v0, v0, v1
	v_add_f32_e32 v9, v0, v9
	v_lshlrev_b32_e32 v0, 16, v117
	v_lshlrev_b32_e32 v1, 16, v119
	v_add_f32_e32 v0, v1, v0
	v_add_f32_e32 v10, v0, v10
	v_and_b32_e32 v0, 0xffff0000, v119
	v_and_b32_e32 v1, 0xffff0000, v117
	v_add_f32_e32 v0, v0, v1
	v_add_f32_e32 v11, v0, v11
	v_cvt_pk_bf16_f32 v0, v8, v9
	v_cvt_pk_bf16_f32 v1, v10, v11
	ds_write_b64 v241, v[0:1] offset:32
	s_waitcnt vmcnt(19)
	v_lshlrev_b32_e32 v0, 16, v112
	s_waitcnt vmcnt(18)
	v_lshlrev_b32_e32 v1, 16, v114
	v_add_f32_e32 v0, v1, v0
	v_add_f32_e32 v12, v0, v12
	v_and_b32_e32 v0, 0xffff0000, v114
	v_and_b32_e32 v1, 0xffff0000, v112
	v_add_f32_e32 v0, v0, v1
	v_add_f32_e32 v13, v0, v13
	v_lshlrev_b32_e32 v0, 16, v113
	v_lshlrev_b32_e32 v1, 16, v115
	v_add_f32_e32 v0, v1, v0
	v_add_f32_e32 v14, v0, v14
	v_and_b32_e32 v0, 0xffff0000, v115
	v_and_b32_e32 v1, 0xffff0000, v113
	v_add_f32_e32 v0, v0, v1
	v_add_f32_e32 v15, v0, v15
	v_cvt_pk_bf16_f32 v0, v12, v13
	v_cvt_pk_bf16_f32 v1, v14, v15
	ds_write_b64 v241, v[0:1] offset:48
	s_waitcnt lgkmcnt(0)
	ds_read_b128 v[244:247], v242
	ds_read_b128 v[248:251], v242 offset:1152
	v_add_u32_e32 v253, 0x10000, v252
	s_waitcnt lgkmcnt(0)
	global_store_dwordx4 v252, v[244:247], s[96:97]
	global_store_dwordx4 v253, v[248:251], s[96:97]
	s_nop 1
	v_mul_f32_e32 v0, v73, v73
	v_fmac_f32_e32 v0, v72, v72
	v_mul_f32_e32 v1, v5, v5
	v_fmac_f32_e32 v0, v2, v2
	v_fmac_f32_e32 v1, v4, v4
	v_fmac_f32_e32 v0, v3, v3
	v_fmac_f32_e32 v1, v6, v6
	v_add_f32_e32 v0, v204, v0
	v_fmac_f32_e32 v1, v7, v7
	v_add_f32_e32 v0, v1, v0
	v_mul_f32_e32 v1, v9, v9
	v_fmac_f32_e32 v1, v8, v8
	v_fmac_f32_e32 v1, v10, v10
	v_fmac_f32_e32 v1, v11, v11
	v_add_f32_e32 v0, v1, v0
	v_mul_f32_e32 v1, v13, v13
	v_fmac_f32_e32 v1, v12, v12
	v_fmac_f32_e32 v1, v14, v14
	v_fmac_f32_e32 v1, v15, v15
	v_add_f32_e32 v72, v1, v0
	s_waitcnt vmcnt(17)
	v_mfma_f32_32x32x16_bf16 v[0:15], v[88:91], v[40:43], 0
	s_waitcnt vmcnt(16)
	v_mfma_f32_32x32x16_bf16 v[0:15], v[80:83], v[36:39], v[0:15]
	s_waitcnt vmcnt(15)
	v_mfma_f32_32x32x16_bf16 v[0:15], v[68:71], v[44:47], v[0:15]
	s_waitcnt vmcnt(14)
	v_mfma_f32_32x32x16_bf16 v[0:15], v[48:51], v[16:19], v[0:15]
	s_waitcnt vmcnt(9)
	v_lshlrev_b32_e32 v16, 16, v108
	s_waitcnt vmcnt(8)
; DI unsigned cvt_pk_bf16(float lo, float hi) { unsigned r; asm volatile("v_cvt_pk_bf16_f32 %0, %1, %2" : "=v"(r) : "v"(lo), "v"(hi)); return r; }
; DI float bf_lo(unsigned w) { return __uint_as_float(w << 16); }
; DI float bf_hi(unsigned w) { return __uint_as_float(w & 0xffff0000u); }
; DI float shx(float v, int lane, int mask) { return __int_as_float(__builtin_amdgcn_ds_bpermute((lane ^ mask) << 2, __float_as_int(v))); }
; template <bool DRY, bool H1>
; DI void intra_phase(LAS unsigned char* lds, const Params& p) {
;     ...
; #pragma unroll
;         for (int gq = 0; gq < 4; ++gq) {
;           const u32x2 ov = yold[t & 1][gq], o2 = yol2[t & 1][gq];
;           const float v0 = bf_lo(ov.x) + bf_lo(o2.x) + yt[4 * gq], v1 = bf_hi(ov.x) + bf_hi(o2.x) + yt[4 * gq + 1], v2 = bf_lo(ov.y) + bf_lo(o2.y) + yt[4 * gq + 2], v3 = bf_hi(ov.y) + bf_hi(o2.y) + yt[4 * gq + 3];
;           sq2 += v0 * v0 + v1 * v1 + v2 * v2 + v3 * v3;
;           u32x2 a; a.x = cvt_pk_bf16(v0, v1); a.y = cvt_pk_bf16(v2, v3); if (!DRY || v0 == 12345.678f) *(u32x2*)((char*)y + (yo + 64u * t + 16u * gq)) = a;
;         }
;         __builtin_amdgcn_sched_barrier(0);
;       }
;       sq2 += shx(sq2, lane, 32);
;       if (h == 0 && (!DRY || sq2 == 12345.678f)) ss[((size_t)(tb + icol) * 4 + hd) * 16 + wh] = sq2;
	v_lshlrev_b32_e32 v17, 16, v110
	v_add_f32_e32 v16, v17, v16
	v_and_b32_e32 v17, 0xffff0000, v108
	v_mfma_f32_32x32x16_bf16 v[0:15], v[52:55], v[20:23], v[0:15]
	v_mfma_f32_32x32x16_bf16 v[0:15], v[56:59], v[24:27], v[0:15]
	v_mfma_f32_32x32x16_bf16 v[0:15], v[60:63], v[28:31], v[0:15]
	v_mfma_f32_32x32x16_bf16 v[0:15], v[64:67], v[32:35], v[0:15]
	s_nop 11
	v_add_f32_e32 v0, v16, v0
	v_and_b32_e32 v16, 0xffff0000, v110
	v_add_f32_e32 v16, v16, v17
	v_add_f32_e32 v1, v16, v1
	v_lshlrev_b32_e32 v16, 16, v109
	v_lshlrev_b32_e32 v17, 16, v111
	v_add_f32_e32 v16, v17, v16
	v_add_f32_e32 v2, v16, v2
	v_and_b32_e32 v16, 0xffff0000, v111
	v_and_b32_e32 v17, 0xffff0000, v109
	v_add_f32_e32 v16, v16, v17
	v_add_f32_e32 v3, v16, v3
	v_mul_f32_e32 v16, v1, v1
	v_fmac_f32_e32 v16, v0, v0
	v_cvt_pk_bf16_f32 v0, v0, v1
	v_cvt_pk_bf16_f32 v1, v2, v3
	v_add_u32_e32 v252, v205, v240
	ds_write_b64 v241, v[0:1]
	s_waitcnt vmcnt(7)
	v_lshlrev_b32_e32 v0, 16, v104
	s_waitcnt vmcnt(6)
	v_lshlrev_b32_e32 v1, 16, v106
	v_fmac_f32_e32 v16, v2, v2
	v_add_f32_e32 v0, v1, v0
	v_and_b32_e32 v1, 0xffff0000, v106
	v_and_b32_e32 v2, 0xffff0000, v104
	v_fmac_f32_e32 v16, v3, v3
	v_add_f32_e32 v1, v1, v2
	v_lshlrev_b32_e32 v2, 16, v105
	v_lshlrev_b32_e32 v3, 16, v107
	v_add_f32_e32 v0, v0, v4
	v_add_f32_e32 v1, v1, v5
	v_add_f32_e32 v2, v3, v2
	v_and_b32_e32 v3, 0xffff0000, v107
	v_and_b32_e32 v4, 0xffff0000, v105
	v_add_f32_e32 v3, v3, v4
	v_mul_f32_e32 v4, v1, v1
	v_add_f32_e32 v2, v2, v6
	v_add_f32_e32 v3, v3, v7
	v_fmac_f32_e32 v4, v0, v0
	v_cvt_pk_bf16_f32 v0, v0, v1
	v_cvt_pk_bf16_f32 v1, v2, v3
	ds_write_b64 v241, v[0:1] offset:16
	s_waitcnt vmcnt(5)
	v_lshlrev_b32_e32 v0, 16, v100
	s_waitcnt vmcnt(4)
	v_lshlrev_b32_e32 v1, 16, v102
	v_fmac_f32_e32 v4, v2, v2
	v_add_f32_e32 v0, v1, v0
	v_and_b32_e32 v1, 0xffff0000, v102
	v_and_b32_e32 v2, 0xffff0000, v100
	v_fmac_f32_e32 v4, v3, v3
	v_add_f32_e32 v1, v1, v2
	v_lshlrev_b32_e32 v2, 16, v101
	v_lshlrev_b32_e32 v3, 16, v103
	v_add_f32_e32 v1, v1, v9
	v_add_f32_e32 v2, v3, v2
	v_and_b32_e32 v3, 0xffff0000, v103
	v_and_b32_e32 v5, 0xffff0000, v101
	v_add_f32_e32 v0, v0, v8
	v_add_f32_e32 v3, v3, v5
	v_mul_f32_e32 v5, v1, v1
	v_add_f32_e32 v2, v2, v10
	v_add_f32_e32 v3, v3, v11
	v_fmac_f32_e32 v5, v0, v0
	v_cvt_pk_bf16_f32 v0, v0, v1
	v_cvt_pk_bf16_f32 v1, v2, v3
	ds_write_b64 v241, v[0:1] offset:32
	s_waitcnt vmcnt(3)
	v_lshlrev_b32_e32 v0, 16, v96
	s_waitcnt vmcnt(2)
	v_lshlrev_b32_e32 v1, 16, v98
	v_add_f32_e32 v0, v1, v0
	v_fmac_f32_e32 v5, v2, v2
	v_add_f32_e32 v1, v0, v12
	v_and_b32_e32 v0, 0xffff0000, v98
	v_and_b32_e32 v2, 0xffff0000, v96
	v_add_f32_e32 v0, v0, v2
	v_add_f32_e32 v16, v72, v16
	v_fmac_f32_e32 v5, v3, v3
	v_add_f32_e32 v2, v0, v13
	v_lshlrev_b32_e32 v0, 16, v97
	v_lshlrev_b32_e32 v3, 16, v99
	v_add_f32_e32 v4, v4, v16
	v_add_f32_e32 v0, v3, v0
	v_add_f32_e32 v4, v5, v4
	v_add_f32_e32 v3, v0, v14
	v_and_b32_e32 v0, 0xffff0000, v99
	v_and_b32_e32 v5, 0xffff0000, v97
	v_add_f32_e32 v0, v0, v5
	v_add_f32_e32 v5, v0, v15
	v_mul_f32_e32 v0, v2, v2
	v_fmac_f32_e32 v0, v1, v1
	v_fmac_f32_e32 v0, v3, v3
	v_fmac_f32_e32 v0, v5, v5
	v_add_f32_e32 v0, v0, v4
	v_cvt_pk_bf16_f32 v2, v1, v2
	v_cvt_pk_bf16_f32 v3, v3, v5
	ds_write_b64 v241, v[2:3] offset:48
	s_waitcnt lgkmcnt(0)
	ds_read_b128 v[244:247], v242
	ds_read_b128 v[248:251], v242 offset:1152
	v_add_u32_e32 v253, 0x10000, v252
	s_waitcnt lgkmcnt(0)
	global_store_dwordx4 v252, v[244:247], s[96:97]
	global_store_dwordx4 v253, v[248:251], s[96:97]
	s_nop 1
	ds_bpermute_b32 v1, v134, v0
	v_readlane_b32 s8, v255, 47
	v_readlane_b32 s9, v255, 48
	s_and_saveexec_b64 s[0:1], s[8:9]
	s_cbranch_execz .LBB0_17
	v_ashrrev_i32_e32 v95, 31, v94
	v_readlane_b32 s8, v255, 53
	s_waitcnt lgkmcnt(0)
	v_add_f32_e32 v2, v0, v1
	v_lshlrev_b64 v[0:1], 8, v[94:95]
	v_readlane_b32 s9, v255, 54
	s_lshl_b32 s94, s94, 6
	s_nop 0
	v_lshl_add_u64 v[0:1], s[8:9], 0, v[0:1]
	v_lshl_add_u64 v[0:1], v[0:1], 0, s[94:95]
	v_lshl_add_u64 v[0:1], v[92:93], 2, v[0:1]
	global_store_dword v[0:1], v2, off
	s_branch .LBB0_17

; #define MFMA32(a, b, c) __builtin_amdgcn_mfma_f32_32x32x16_bf16((a), (b), (c), 0, 0, 0)
; DI float log2_gamma(float x) { return -__builtin_amdgcn_logf(1.0f + __builtin_amdgcn_exp2f(-1.4426950408889634f * x)); }
; template <bool DRY, bool H1>
; DI void intra_phase(LAS unsigned char* lds, const Params& p) {
;     ...
;   for (int item = blockIdx.x; item < 512; item += gridDim.x) {
;     const int hd = item & 3, tb = (item >> 2) * 128;
;     const float lgf = log2_gamma(p.dec_f[hd]), lgb = log2_gamma(p.dec_b[hd]);
;     const int icol = 32 * ib + r;
;     {
;       bf16x8 qf[16];
;       const unsigned qo = (unsigned)(item) * 65536u + (unsigned)ib * 16384u + (unsigned)lane * 16u;
; #pragma unroll
;       for (int s = 0; s < 16; ++s) qf[s] = ldg16(qr, qo + 1024u * s);
; #pragma unroll
;       for (int jj = 0; jj < 2; ++jj) {
;         const int jt = 2 * wh + jj;
;         f32x16 pt;
; #pragma unroll
;         for (int i = 0; i < 16; ++i) pt[i] = 0.f;
;         const unsigned ko = (unsigned)(item) * 65536u + (unsigned)jt * 16384u + (unsigned)lane * 16u;
; #pragma unroll
;         for (int s = 0; s < 16; ++s) pt = MFMA32(ldg16(kr, ko + 1024u * s), qf[s], pt);
.LBB0_58:
	s_lshl_b32 s78, s2, 16
	v_or_b32_e32 v8, s78, v93
	v_add_u32_e32 v90, v8, v97
	global_load_dwordx4 v[0:3], v90, s[0:1]
	v_or_b32_e32 v91, s78, v94
	global_load_dwordx4 v[4:7], v91, s[92:93]
	v_or_b32_e32 v12, 0x400, v90
	global_load_dwordx4 v[32:35], v12, s[0:1]
	v_add_u32_e32 v167, v8, v130
	global_load_dwordx4 v[8:11], v167, s[0:1]
	v_or_b32_e32 v168, 0x1400, v167
	v_or_b32_e32 v172, 0x1800, v90
	v_or_b32_e32 v176, 0x1800, v167
	s_and_b32 s94, s2, 3
	s_lshl_b32 s78, s94, 2
	s_mov_b64 s[66:67], s[18:19]
	s_mov_b64 s[64:65], s[16:17]
	v_or_b32_e32 v178, 0x2000, v167
	v_or_b32_e32 v182, 0x2c00, v91
	v_or_b32_e32 v186, 0x3400, v91
	v_or_b32_e32 v195, 0x3400, v167
	s_mov_b64 s[60:61], s[12:13]
	v_readlane_b32 s60, v255, 49
	v_readlane_b32 s61, v255, 50
	s_mov_b64 s[62:63], s[14:15]
	s_waitcnt vmcnt(2)
	v_mfma_f32_32x32x16_bf16 v[16:31], v[0:3], v[4:7], 0
	v_or_b32_e32 v0, 0x1400, v91
	global_load_dwordx4 v[86:89], v0, s[92:93]
	v_or_b32_e32 v12, 0x400, v91
	global_load_dwordx4 v[36:39], v12, s[92:93]
	v_or_b32_e32 v12, 0x400, v167
	global_load_dwordx4 v[40:43], v12, s[0:1]
	v_or_b32_e32 v12, 0x800, v90
	global_load_dwordx4 v[44:47], v12, s[0:1]
	s_waitcnt vmcnt(2)
	v_mfma_f32_32x32x16_bf16 v[16:31], v[32:35], v[36:39], v[16:31]
	global_load_dwordx4 v[168:171], v168, s[0:1]
	v_or_b32_e32 v12, 0x800, v91
	global_load_dwordx4 v[48:51], v12, s[92:93]
	v_or_b32_e32 v12, 0x800, v167
	global_load_dwordx4 v[52:55], v12, s[0:1]
	global_load_dwordx4 v[32:35], v172, s[0:1]
	v_or_b32_e32 v172, 0x1800, v91
	s_waitcnt vmcnt(2)
	v_mfma_f32_32x32x16_bf16 v[16:31], v[44:47], v[48:51], v[16:31]
	v_or_b32_e32 v44, 0x1c00, v91
	global_load_dwordx4 v[44:47], v44, s[92:93]
	v_or_b32_e32 v12, 0xc00, v90
	global_load_dwordx4 v[56:59], v12, s[0:1]
	v_or_b32_e32 v12, 0xc00, v91
	global_load_dwordx4 v[60:63], v12, s[92:93]
	v_or_b32_e32 v12, 0xc00, v167
	global_load_dwordx4 v[64:67], v12, s[0:1]
	s_waitcnt vmcnt(1)
	v_mfma_f32_32x32x16_bf16 v[16:31], v[56:59], v[60:63], v[16:31]
	v_or_b32_e32 v56, 0x2000, v91
	global_load_dwordx4 v[56:59], v56, s[92:93]
	v_or_b32_e32 v12, 0x1000, v90
	global_load_dwordx4 v[68:71], v12, s[0:1]
	s_nop 0
	global_load_dwordx4 v[172:175], v172, s[92:93]
	v_or_b32_e32 v12, 0x1000, v91
	global_load_dwordx4 v[72:75], v12, s[92:93]
	v_or_b32_e32 v12, 0x1000, v167
	global_load_dwordx4 v[78:81], v12, s[0:1]
	v_or_b32_e32 v12, 0x1400, v90
	global_load_dwordx4 v[82:85], v12, s[0:1]
	v_mfma_f32_32x32x16_bf16 v[0:15], v[8:11], v[4:7], 0
	v_mfma_f32_32x32x16_bf16 v[0:15], v[40:43], v[36:39], v[0:15]
	global_load_dwordx4 v[36:39], v176, s[0:1]
	v_or_b32_e32 v40, 0x1c00, v90
	global_load_dwordx4 v[40:43], v40, s[0:1]
	v_or_b32_e32 v176, 0x1c00, v167
	v_mfma_f32_32x32x16_bf16 v[0:15], v[52:55], v[48:51], v[0:15]
	global_load_dwordx4 v[48:51], v176, s[0:1]
	v_or_b32_e32 v52, 0x2000, v90
	global_load_dwordx4 v[52:55], v52, s[0:1]
	v_mov_b32_e32 v176, s78
	global_load_dword v194, v176, s[64:65]
	s_nop 0
	global_load_dword v176, v176, s[66:67]
	s_lshl_b32 s78, s2, 5
	s_and_b32 s78, s78, 0xffffff80
	s_waitcnt vmcnt(12)
	v_mfma_f32_32x32x16_bf16 v[0:15], v[64:67], v[60:63], v[0:15]
	global_load_dwordx4 v[60:63], v178, s[0:1]
	v_or_b32_e32 v64, 0x2400, v90
	global_load_dwordx4 v[64:67], v64, s[0:1]
	s_waitcnt vmcnt(10)
	v_mfma_f32_32x32x16_bf16 v[16:31], v[68:71], v[72:75], v[16:31]
	v_or_b32_e32 v68, 0x2400, v91
	global_load_dwordx4 v[68:71], v68, s[92:93]
	s_waitcnt vmcnt(10)
	v_mfma_f32_32x32x16_bf16 v[0:15], v[78:81], v[72:75], v[0:15]
	v_or_b32_e32 v78, 0x2800, v90
	global_load_dwordx4 v[78:81], v78, s[0:1]
	s_waitcnt vmcnt(10)
	v_mfma_f32_32x32x16_bf16 v[16:31], v[82:85], v[86:89], v[16:31]
	v_mfma_f32_32x32x16_bf16 v[0:15], v[168:171], v[86:89], v[0:15]
	global_load_dwordx4 v[86:89], v182, s[92:93]
	v_or_b32_e32 v182, 0x3000, v91
	v_or_b32_e32 v168, 0x3000, v90
	global_load_dwordx4 v[168:171], v168, s[0:1]
	v_mfma_f32_32x32x16_bf16 v[16:31], v[32:35], v[172:175], v[16:31]
	global_load_dwordx4 v[32:35], v182, s[92:93]
	v_or_b32_e32 v182, 0x3400, v90
	global_load_dwordx4 v[182:185], v182, s[0:1]
	v_or_b32_e32 v178, 0x2400, v167
	global_load_dwordx4 v[72:75], v178, s[0:1]
	s_waitcnt vmcnt(14)
	v_mfma_f32_32x32x16_bf16 v[0:15], v[36:39], v[172:175], v[0:15]
	global_load_dwordx4 v[36:39], v186, s[92:93]
	v_or_b32_e32 v178, 0x2800, v91
	global_load_dwordx4 v[82:85], v178, s[92:93]
	v_or_b32_e32 v186, 0x3800, v91
	v_or_b32_e32 v172, 0x3800, v90
	global_load_dwordx4 v[172:175], v172, s[0:1]
	s_waitcnt vmcnt(16)
	v_mfma_f32_32x32x16_bf16 v[16:31], v[40:43], v[44:47], v[16:31]
	global_load_dwordx4 v[40:43], v186, s[92:93]
	v_or_b32_e32 v178, 0x2c00, v90
	global_load_dwordx4 v[178:181], v178, s[0:1]
	v_or_b32_e32 v90, 0x3c00, v90
	global_load_dwordx4 v[186:189], v90, s[0:1]
	v_or_b32_e32 v90, 0x3c00, v91
	global_load_dwordx4 v[190:193], v90, s[92:93]
	v_or_b32_e32 v90, 0x2800, v167
	s_waitcnt vmcnt(19)
	v_mfma_f32_32x32x16_bf16 v[0:15], v[48:51], v[44:47], v[0:15]
	global_load_dwordx4 v[44:47], v90, s[0:1]
	v_or_b32_e32 v48, 0x2c00, v167
	global_load_dwordx4 v[48:51], v48, s[0:1]
	v_or_b32_e32 v91, 0x3000, v167
	v_or_b32_e32 v90, 0x3800, v167
	v_or_b32_e32 v167, 0x3c00, v167
	s_waitcnt vmcnt(20)
	v_mfma_f32_32x32x16_bf16 v[16:31], v[52:55], v[56:59], v[16:31]
	s_waitcnt vmcnt(19)
	v_mul_f32_e32 v52, 0xbfb8aa3b, v194
	s_waitcnt vmcnt(18)
	v_mul_f32_e32 v53, 0xbfb8aa3b, v176
	v_exp_f32_e32 v176, v52
	v_exp_f32_e32 v198, v53
	global_load_dwordx4 v[52:55], v91, s[0:1]
	s_nop 0
	global_load_dwordx4 v[194:197], v195, s[0:1]
	v_add_f32_e32 v91, 1.0, v176
	s_waitcnt vmcnt(19)
; #define LAS __attribute__((address_space(3)))
; #define MFMA32(a, b, c) __builtin_amdgcn_mfma_f32_32x32x16_bf16((a), (b), (c), 0, 0, 0)
; #define EX2(x) __builtin_amdgcn_exp2f(x)
; template <bool DRY, bool H1>
; DI void intra_phase(LAS unsigned char* lds, const Params& p) {
;     ...
;       for (int jj = 0; jj < 2; ++jj) {
;         const int jt = 2 * wh + jj;
;         f32x16 pt;
; #pragma unroll
;         for (int i = 0; i < 16; ++i) pt[i] = 0.f;
;         const unsigned ko = (unsigned)(item) * 65536u + (unsigned)jt * 16384u + (unsigned)lane * 16u;
; #pragma unroll
;         for (int s = 0; s < 16; ++s) pt = MFMA32(ldg16(kr, ko + 1024u * s), qf[s], pt);
; #pragma unroll
;         for (int gq = 0; gq < 4; ++gq) {
;           float f[4];
; #pragma unroll
;           for (int e = 0; e < 4; ++e) {
;             const int df = icol - (32 * jt + 8 * gq + 4 * h + e);
;             f[e] = pt[4 * gq + e] * EX2(df >= 0 ? lgf * (float)df : lgb * (float)(-df));
;           }
;           u32x2 a; a.x = rne_pk(f[0], f[1]); a.y = rne_pk(f[2], f[3]);
;           *(LAS u32x2*)(Pimg + icol * 272 + (32 * jt + 8 * gq + 4 * h) * 2) = a;
;         }
;       }
	v_mfma_f32_32x32x16_bf16 v[0:15], v[60:63], v[56:59], v[0:15]
	v_add_f32_e32 v56, 1.0, v198
	v_log_f32_e32 v176, v56
	global_load_dwordx4 v[56:59], v90, s[0:1]
	global_load_dwordx4 v[60:63], v167, s[0:1]
	v_log_f32_e32 v91, v91
	v_mul_f32_e64 v167, v98, -v176
	v_mul_f32_e64 v199, v104, -v176
	s_waitcnt vmcnt(19)
	v_mfma_f32_32x32x16_bf16 v[16:31], v[64:67], v[68:71], v[16:31]
	v_mul_f32_e64 v90, v99, -v91
	v_cndmask_b32_e64 v90, v90, v167, s[60:61]
	v_readlane_b32 s60, v255, 51
	v_mul_f32_e64 v64, v101, -v91
	v_mul_f32_e64 v65, v100, -v176
	v_readlane_b32 s61, v255, 52
	v_mul_f32_e64 v66, v103, -v91
	s_waitcnt vmcnt(11)
	v_mfma_f32_32x32x16_bf16 v[16:31], v[78:81], v[82:85], v[16:31]
	v_cndmask_b32_e64 v65, v64, v65, s[60:61]
	v_readlane_b32 s60, v255, 53
	v_mul_f32_e64 v67, v102, -v176
	v_readlane_b32 s61, v255, 54
	v_mul_f32_e64 v198, v105, -v91
	v_mul_f32_e64 v200, v107, -v91
	v_cndmask_b32_e64 v66, v66, v67, s[60:61]
	s_waitcnt vmcnt(8)
	v_mfma_f32_32x32x16_bf16 v[16:31], v[178:181], v[86:89], v[16:31]
	v_readlane_b32 s60, v255, 55
	v_readlane_b32 s61, v255, 56
	v_cndmask_b32_e64 v67, v198, v199, s[74:75]
	v_exp_f32_e32 v64, v90
	v_exp_f32_e32 v65, v65
	v_exp_f32_e32 v66, v66
	v_exp_f32_e32 v67, v67
	v_mfma_f32_32x32x16_bf16 v[0:15], v[72:75], v[68:71], v[0:15]
	v_mul_f32_e64 v69, v109, -v91
	v_mul_f32_e64 v70, v108, -v176
	v_cndmask_b32_e64 v69, v69, v70, s[60:61]
	v_readlane_b32 s60, v255, 57
	v_mul_f32_e64 v68, v106, -v176
	v_mul_f32_e64 v71, v111, -v91
	v_mul_f32_e64 v72, v110, -v176
	v_mfma_f32_32x32x16_bf16 v[16:31], v[168:171], v[32:35], v[16:31]
	v_mul_f32_e64 v73, v113, -v91
	v_mul_f32_e64 v74, v112, -v176
	v_readlane_b32 s61, v255, 58
	v_cndmask_b32_e64 v68, v200, v68, s[10:11]
	v_exp_f32_e32 v68, v68
	v_cndmask_b32_e64 v70, v71, v72, s[60:61]
	v_cndmask_b32_e64 v71, v73, v74, s[20:21]
	s_waitcnt vmcnt(5)
	v_mfma_f32_32x32x16_bf16 v[0:15], v[44:47], v[82:85], v[0:15]
	v_exp_f32_e32 v69, v69
	v_exp_f32_e32 v70, v70
	v_exp_f32_e32 v71, v71
	v_mul_f32_e64 v75, v115, -v91
	v_mul_f32_e64 v78, v114, -v176
	v_mul_f32_e64 v79, v117, -v91
	v_mul_f32_e64 v80, v116, -v176
	v_mfma_f32_32x32x16_bf16 v[16:31], v[182:185], v[36:39], v[16:31]
	v_mul_f32_e64 v81, v119, -v91
	v_mul_f32_e64 v201, v118, -v176
	v_mul_f32_e64 v203, v121, -v91
	v_mul_f32_e64 v178, v120, -v176
	v_mul_f32_e64 v179, v123, -v91
	v_mul_f32_e64 v180, v122, -v176
	v_mul_f32_e64 v181, v125, -v91
	s_waitcnt vmcnt(4)
	v_mfma_f32_32x32x16_bf16 v[0:15], v[48:51], v[86:89], v[0:15]
	v_mul_f32_e64 v204, v124, -v176
	v_mul_f32_e64 v205, v127, -v91
	v_mul_f32_e64 v206, v126, -v176
	v_cndmask_b32_e64 v72, v75, v78, s[22:23]
	v_cndmask_b32_e64 v73, v79, v80, s[24:25]
	v_cndmask_b32_e64 v74, v81, v201, s[26:27]
	v_cndmask_b32_e64 v75, v203, v178, s[28:29]
	v_mfma_f32_32x32x16_bf16 v[16:31], v[172:175], v[40:43], v[16:31]
	v_cndmask_b32_e64 v78, v179, v180, s[30:31]
	v_cndmask_b32_e64 v79, v181, v204, s[34:35]
	v_exp_f32_e32 v72, v72
	v_exp_f32_e32 v73, v73
	v_exp_f32_e32 v74, v74
	v_exp_f32_e32 v75, v75
	v_exp_f32_e32 v78, v78
	s_waitcnt vmcnt(3)
	v_mfma_f32_32x32x16_bf16 v[0:15], v[52:55], v[32:35], v[0:15]
	v_exp_f32_e32 v79, v79
	v_mfma_f32_32x32x16_bf16 v[16:31], v[186:189], v[190:193], v[16:31]
	s_waitcnt vmcnt(2)
	v_mfma_f32_32x32x16_bf16 v[0:15], v[194:197], v[36:39], v[0:15]
	s_nop 9
	v_mul_f32_e64 v16, v64, v16
	v_mul_f32_e64 v17, v65, v17
	v_mul_f32_e64 v18, v66, v18
	v_mul_f32_e64 v19, v67, v19
	v_mul_f32_e64 v20, v68, v20
	v_mul_f32_e64 v21, v69, v21
	v_pk_mul_f32 v[22:23], v[70:71], v[22:23]
	v_cvt_pk_bf16_f32 v16, v16, v17
	v_cvt_pk_bf16_f32 v17, v18, v19
	v_cvt_pk_bf16_f32 v18, v20, v21
	v_cvt_pk_bf16_f32 v19, v22, v23
	s_waitcnt vmcnt(1)
	v_mfma_f32_32x32x16_bf16 v[0:15], v[56:59], v[40:43], v[0:15]
	ds_write2_b64 v164, v[16:17], v[18:19] offset1:2
	v_mul_f32_e64 v17, v129, -v91
	v_mul_f32_e64 v18, v128, -v176
	v_cndmask_b32_e64 v16, v205, v206, s[36:37]
	v_cndmask_b32_e64 v17, v17, v18, s[38:39]
	v_exp_f32_e32 v16, v16
	v_exp_f32_e32 v17, v17
	v_pk_mul_f32 v[24:25], v[72:73], v[24:25]
	v_pk_mul_f32 v[26:27], v[74:75], v[26:27]
	v_pk_mul_f32 v[18:19], v[78:79], v[28:29]
	v_pk_mul_f32 v[16:17], v[16:17], v[30:31]
	v_cvt_pk_bf16_f32 v20, v24, v25
	v_cvt_pk_bf16_f32 v21, v26, v27
	v_cvt_pk_bf16_f32 v18, v18, v19
	v_cvt_pk_bf16_f32 v19, v16, v17
	v_mul_f32_e64 v16, v132, -v91
	v_mul_f32_e64 v17, v131, -v176
	s_waitcnt vmcnt(0)
; #define LAS __attribute__((address_space(3)))
; #define EX2(x) __builtin_amdgcn_exp2f(x)
; template <bool DRY, bool H1>
; DI void intra_phase(LAS unsigned char* lds, const Params& p) {
;     ...
;         for (int gq = 0; gq < 4; ++gq) {
;           float f[4];
; #pragma unroll
;           for (int e = 0; e < 4; ++e) {
;             const int df = icol - (32 * jt + 8 * gq + 4 * h + e);
;             f[e] = pt[4 * gq + e] * EX2(df >= 0 ? lgf * (float)df : lgb * (float)(-df));
;           }
;           u32x2 a; a.x = rne_pk(f[0], f[1]); a.y = rne_pk(f[2], f[3]);
;           *(LAS u32x2*)(Pimg + icol * 272 + (32 * jt + 8 * gq + 4 * h) * 2) = a;
;         }
;       }
;     }
;     __syncthreads();
;     {
;       bf16x8 pf[8];
; #pragma unroll
;       for (int s = 0; s < 8; ++s) pf[s] = *(const LAS bf16x8*)(Pimg + icol * 272 + (16 * s + 8 * h) * 2);
;       float sq2 = 0.f;
;       const unsigned vo = (unsigned)(item) * 131072u + (unsigned)(8 * wh) * 8192u + (unsigned)lane * 16u;
;       const unsigned yo = (unsigned)((tb + icol) * 2048 + hd * 512 + 256 * wh + 4 * h) * 2u;
;       bf16x8 va[2][8]; u32x2 yold[2][4], yol2[2][4];
; #pragma unroll
;       for (int gq = 0; gq < 4; ++gq) { yol2[0][gq] = (u32x2){0u, 0u}; yol2[1][gq] = (u32x2){0u, 0u}; }
; #pragma unroll
;       for (int s = 0; s < 8; ++s) va[0][s] = ldg16(vT, vo + 1024u * s);
; #pragma unroll
;       for (int gq = 0; gq < 4; ++gq) { yold[0][gq] = *(const u32x2*)((const char*)y + (yo + 16u * gq)); if constexpr (H1) yol2[0][gq] = *(const u32x2*)((const char*)yb + (yo + 16u * gq)); }
; #pragma unroll
;       for (int t = 0; t < 8; ++t) {
;         if (t < 7) {
; #pragma unroll
;           for (int s = 0; s < 8; ++s) va[(t + 1) & 1][s] = ldg16(vT, vo + (unsigned)(t + 1) * 8192u + 1024u * s);
; #pragma unroll
;           for (int gq = 0; gq < 4; ++gq) { yold[(t + 1) & 1][gq] = *(const u32x2*)((const char*)y + (yo + 64u * (t + 1) + 16u * gq)); if constexpr (H1) yol2[(t + 1) & 1][gq] = *(const u32x2*)((const char*)yb + (yo + 64u * (t + 1) + 16u * gq)); }
	v_mfma_f32_32x32x16_bf16 v[0:15], v[60:63], v[190:193], v[0:15]
	ds_write2_b64 v164, v[20:21], v[18:19] offset0:4 offset1:6
	v_cndmask_b32_e64 v16, v16, v17, s[40:41]
	v_mul_f32_e64 v17, v134, -v91
	v_mul_f32_e64 v18, v133, -v176
	v_cndmask_b32_e64 v17, v17, v18, s[42:43]
	v_mul_f32_e64 v18, v136, -v91
	v_mul_f32_e64 v19, v135, -v176
	v_cndmask_b32_e64 v18, v18, v19, s[44:45]
	v_mul_f32_e64 v19, v138, -v91
	v_mul_f32_e64 v20, v137, -v176
	v_exp_f32_e32 v16, v16
	v_exp_f32_e32 v17, v17
	v_cndmask_b32_e64 v19, v19, v20, s[46:47]
	v_exp_f32_e32 v18, v18
	v_exp_f32_e32 v19, v19
	v_pk_mul_f32 v[0:1], v[16:17], v[0:1]
	v_mul_f32_e64 v16, v140, -v91
	v_mul_f32_e64 v17, v139, -v176
	v_pk_mul_f32 v[2:3], v[18:19], v[2:3]
	v_cndmask_b32_e64 v16, v16, v17, s[48:49]
	v_mul_f32_e64 v17, v142, -v91
	v_mul_f32_e64 v18, v141, -v176
	v_cndmask_b32_e64 v17, v17, v18, s[50:51]
	v_mul_f32_e64 v18, v144, -v91
	v_mul_f32_e64 v19, v143, -v176
	v_cndmask_b32_e64 v18, v18, v19, s[52:53]
	v_mul_f32_e64 v19, v146, -v91
	v_mul_f32_e64 v20, v145, -v176
	v_exp_f32_e32 v16, v16
	v_exp_f32_e32 v17, v17
	v_cndmask_b32_e64 v19, v19, v20, s[54:55]
	v_exp_f32_e32 v18, v18
	v_exp_f32_e32 v19, v19
	v_cvt_pk_bf16_f32 v0, v0, v1
	v_cvt_pk_bf16_f32 v1, v2, v3
	v_pk_mul_f32 v[2:3], v[16:17], v[4:5]
	v_pk_mul_f32 v[4:5], v[18:19], v[6:7]
	v_cvt_pk_bf16_f32 v2, v2, v3
	v_mul_f32_e64 v3, v148, -v91
	v_mul_f32_e64 v6, v147, -v176
	v_cndmask_b32_e64 v3, v3, v6, s[56:57]
	v_exp_f32_e32 v6, v3
	v_mul_f32_e64 v3, v150, -v91
	v_mul_f32_e64 v7, v149, -v176
	v_cndmask_b32_e64 v3, v3, v7, s[58:59]
	v_exp_f32_e32 v7, v3
	v_mul_f32_e64 v3, v152, -v91
	v_mul_f32_e64 v16, v151, -v176
	v_cndmask_b32_e32 v3, v3, v16, vcc
	v_exp_f32_e32 v16, v3
	v_mul_f32_e64 v3, v154, -v91
	v_mul_f32_e64 v17, v153, -v176
	v_cndmask_b32_e64 v3, v3, v17, s[76:77]
	v_exp_f32_e32 v17, v3
	v_cvt_pk_bf16_f32 v3, v4, v5
	v_mul_f32_e64 v4, v156, -v91
	v_mul_f32_e64 v5, v155, -v176
	ds_write2_b64 v165, v[0:1], v[2:3] offset1:2
	v_pk_mul_f32 v[0:1], v[6:7], v[8:9]
	v_cndmask_b32_e64 v4, v4, v5, s[6:7]
	v_mul_f32_e64 v5, v158, -v91
	v_mul_f32_e64 v6, v157, -v176
	v_cndmask_b32_e64 v5, v5, v6, s[8:9]
	v_mul_f32_e64 v6, v160, -v91
	v_mul_f32_e64 v7, v159, -v176
	v_cndmask_b32_e64 v6, v6, v7, s[68:69]
	v_mul_f32_e64 v7, v162, -v91
	v_mul_f32_e64 v8, v161, -v176
	v_cndmask_b32_e64 v7, v7, v8, s[70:71]
	v_exp_f32_e32 v4, v4
	v_exp_f32_e32 v5, v5
	v_exp_f32_e32 v6, v6
	v_exp_f32_e32 v7, v7
	v_pk_mul_f32 v[2:3], v[16:17], v[10:11]
	v_cvt_pk_bf16_f32 v0, v0, v1
	v_cvt_pk_bf16_f32 v1, v2, v3
	v_pk_mul_f32 v[2:3], v[4:5], v[12:13]
	v_pk_mul_f32 v[4:5], v[6:7], v[14:15]
	v_cvt_pk_bf16_f32 v2, v2, v3
	v_cvt_pk_bf16_f32 v3, v4, v5
	v_lshl_add_u32 v56, s2, 17, v95
	ds_write2_b64 v165, v[0:1], v[2:3] offset0:4 offset1:6
	s_waitcnt lgkmcnt(0)
	s_barrier
	global_load_dwordx4 v[0:3], v56, s[4:5]
	v_or_b32_e32 v4, 0x400, v56
	global_load_dwordx4 v[16:19], v4, s[4:5]
	v_or_b32_e32 v4, 0x800, v56
	global_load_dwordx4 v[20:23], v4, s[4:5]
	v_or_b32_e32 v4, 0xc00, v56
	global_load_dwordx4 v[24:27], v4, s[4:5]
	v_or_b32_e32 v4, 0x1000, v56
	global_load_dwordx4 v[48:51], v4, s[4:5]
	v_or_b32_e32 v4, 0x1400, v56
	global_load_dwordx4 v[52:55], v4, s[4:5]
	v_or_b32_e32 v4, 0x1800, v56
	global_load_dwordx4 v[58:61], v4, s[4:5]
	ds_read_b128 v[36:39], v166
	ds_read_b128 v[32:35], v166 offset:32
	s_waitcnt vmcnt(6) lgkmcnt(1)
	v_mfma_f32_32x32x16_bf16 v[0:15], v[0:3], v[36:39], 0
	v_or_b32_e32 v28, 0x1c00, v56
	global_load_dwordx4 v[62:65], v28, s[4:5]
	v_or_b32_e32 v78, s78, v92
	v_lshlrev_b32_e32 v28, 12, v78
	s_lshl_b32 s78, s94, 10
	v_add3_u32 v57, v163, s78, v28
	global_load_dwordx2 v[74:75], v57, s[82:83]
	s_waitcnt vmcnt(7) lgkmcnt(0)
	v_mfma_f32_32x32x16_bf16 v[0:15], v[16:19], v[32:35], v[0:15]
	ds_read_b128 v[44:47], v166 offset:64
	ds_read_b128 v[40:43], v166 offset:96
	v_or_b32_e32 v79, 16, v57
	global_load_dwordx2 v[178:179], v79, s[82:83]
	v_or_b32_e32 v167, 32, v57
	global_load_dwordx2 v[180:181], v167, s[82:83]
	v_or_b32_e32 v176, 48, v57
	v_or_b32_e32 v66, 0x2000, v56
	s_waitcnt vmcnt(8) lgkmcnt(1)
	v_mfma_f32_32x32x16_bf16 v[0:15], v[20:23], v[44:47], v[0:15]
	v_or_b32_e32 v70, 0x2400, v56
	v_or_b32_e32 v194, 64, v57
	v_or_b32_e32 v195, 0x50, v57
	v_or_b32_e32 v196, 0x60, v57
	v_or_b32_e32 v197, 0x70, v57
	s_waitcnt vmcnt(7) lgkmcnt(0)
	v_mfma_f32_32x32x16_bf16 v[0:15], v[24:27], v[40:43], v[0:15]
	ds_read_b128 v[16:19], v166 offset:128
	ds_read_b128 v[20:23], v166 offset:160
	ds_read_b128 v[24:27], v166 offset:192
	ds_read_b128 v[28:31], v166 offset:224
	global_load_dwordx2 v[182:183], v176, s[82:83]
	s_nop 0
	global_load_dwordx4 v[66:69], v66, s[4:5]
	s_nop 0
	global_load_dwordx4 v[70:73], v70, s[4:5]
	s_waitcnt vmcnt(9) lgkmcnt(3)
	v_mfma_f32_32x32x16_bf16 v[0:15], v[48:51], v[16:19], v[0:15]
	v_or_b32_e32 v48, 0x2800, v56
	v_or_b32_e32 v49, 0x2c00, v56
	global_load_dwordx4 v[80:83], v48, s[4:5]
	global_load_dwordx4 v[84:87], v49, s[4:5]
	v_or_b32_e32 v48, 0x3000, v56
	v_or_b32_e32 v49, 0x3400, v56
	s_waitcnt vmcnt(10) lgkmcnt(2)
	v_mfma_f32_32x32x16_bf16 v[0:15], v[52:55], v[20:23], v[0:15]
	global_load_dwordx4 v[52:55], v48, s[4:5]
	global_load_dwordx4 v[88:91], v49, s[4:5]
	v_or_b32_e32 v48, 0x3800, v56
	v_or_b32_e32 v49, 0x3c00, v56
	global_load_dwordx4 v[168:171], v48, s[4:5]
	global_load_dwordx4 v[172:175], v49, s[4:5]
	global_load_dwordx2 v[186:187], v194, s[82:83]
	global_load_dwordx2 v[188:189], v195, s[82:83]
	global_load_dwordx2 v[190:191], v196, s[82:83]
	global_load_dwordx2 v[50:51], v197, s[82:83]
	s_waitcnt vmcnt(15)
	v_lshlrev_b32_e32 v48, 16, v74
	s_waitcnt lgkmcnt(1)
; DI unsigned cvt_pk_bf16(float lo, float hi) { unsigned r; asm volatile("v_cvt_pk_bf16_f32 %0, %1, %2" : "=v"(r) : "v"(lo), "v"(hi)); return r; }
; DI float bf_lo(unsigned w) { return __uint_as_float(w << 16); }
; DI float bf_hi(unsigned w) { return __uint_as_float(w & 0xffff0000u); }
; #define MFMA32(a, b, c) __builtin_amdgcn_mfma_f32_32x32x16_bf16((a), (b), (c), 0, 0, 0)
; template <bool DRY, bool H1>
; DI void intra_phase(LAS unsigned char* lds, const Params& p) {
;     ...
;       for (int t = 0; t < 8; ++t) {
;         if (t < 7) {
; #pragma unroll
;           for (int s = 0; s < 8; ++s) va[(t + 1) & 1][s] = ldg16(vT, vo + (unsigned)(t + 1) * 8192u + 1024u * s);
; #pragma unroll
;           for (int gq = 0; gq < 4; ++gq) { yold[(t + 1) & 1][gq] = *(const u32x2*)((const char*)y + (yo + 64u * (t + 1) + 16u * gq)); if constexpr (H1) yol2[(t + 1) & 1][gq] = *(const u32x2*)((const char*)yb + (yo + 64u * (t + 1) + 16u * gq)); }
;         }
;         f32x16 yt;
; #pragma unroll
;         for (int i = 0; i < 16; ++i) yt[i] = 0.f;
; #pragma unroll
;         for (int s = 0; s < 8; ++s) yt = MFMA32(va[t & 1][s], pf[s], yt);
; #pragma unroll
;         for (int gq = 0; gq < 4; ++gq) {
;           const u32x2 ov = yold[t & 1][gq], o2 = yol2[t & 1][gq];
;           const float v0 = bf_lo(ov.x) + bf_lo(o2.x) + yt[4 * gq], v1 = bf_hi(ov.x) + bf_hi(o2.x) + yt[4 * gq + 1], v2 = bf_lo(ov.y) + bf_lo(o2.y) + yt[4 * gq + 2], v3 = bf_hi(ov.y) + bf_hi(o2.y) + yt[4 * gq + 3];
;           sq2 += v0 * v0 + v1 * v1 + v2 * v2 + v3 * v3;
;           u32x2 a; a.x = cvt_pk_bf16(v0, v1); a.y = cvt_pk_bf16(v2, v3); if (!DRY || v0 == 12345.678f) *(u32x2*)((char*)y + (yo + 64u * t + 16u * gq)) = a;
;         }
	v_mfma_f32_32x32x16_bf16 v[0:15], v[58:61], v[24:27], v[0:15]
	v_add_f32_e32 v48, 0, v48
	s_waitcnt lgkmcnt(0)
	v_mfma_f32_32x32x16_bf16 v[0:15], v[62:65], v[28:31], v[0:15]
	s_nop 11
	v_add_f32_e32 v0, v48, v0
	v_and_b32_e32 v48, 0xffff0000, v74
	v_add_f32_e32 v48, 0, v48
	v_add_f32_e32 v1, v48, v1
	v_lshlrev_b32_e32 v48, 16, v75
	v_add_f32_e32 v48, 0, v48
	v_add_f32_e32 v2, v48, v2
	v_and_b32_e32 v48, 0xffff0000, v75
	v_add_f32_e32 v48, 0, v48
	v_add_f32_e32 v3, v48, v3
	v_mul_f32_e32 v48, v1, v1
	v_fmac_f32_e32 v48, v0, v0
	v_cvt_pk_bf16_f32 v0, v0, v1
	v_cvt_pk_bf16_f32 v1, v2, v3
	v_mbcnt_lo_u32_b32 v243, -1, 0
	v_mbcnt_hi_u32_b32 v243, -1, v243
	v_readlane_b32 s100, v255, 12
	v_and_b32_e32 v244, 31, v243
	v_lshrrev_b32_e32 v245, 5, v243
	v_lshrrev_b32_e32 v246, 2, v243
	v_and_b32_e32 v247, 3, v243
	v_mov_b32_e32 v248, s100
	v_mul_u32_u24_e32 v248, 36, v248
	v_add_u32_e32 v248, 0x1a000, v248
	v_mul_u32_u24_e32 v241, 0x48, v244
	v_lshl_add_u32 v241, v245, 3, v241
	v_add_u32_e32 v241, v248, v241
	v_mul_u32_u24_e32 v242, 0x48, v246
	v_lshl_add_u32 v242, v247, 4, v242
	v_add_u32_e32 v242, v248, v242
	v_sub_u32_e32 v240, v246, v244
	v_lshlrev_b32_e32 v240, 12, v240
	v_lshl_add_u32 v240, v247, 4, v240
	v_lshlrev_b32_e32 v245, 3, v245
	v_sub_u32_e32 v240, v240, v245
	v_add_u32_e32 v252, v57, v240
	ds_write_b64 v241, v[0:1]
	s_waitcnt vmcnt(14)
	v_and_b32_e32 v1, 0xffff0000, v178
	v_fmac_f32_e32 v48, v2, v2
	v_lshlrev_b32_e32 v0, 16, v178
	v_add_f32_e32 v1, 0, v1
	v_fmac_f32_e32 v48, v3, v3
	v_add_f32_e32 v0, 0, v0
	v_add_f32_e32 v1, v1, v5
	v_lshlrev_b32_e32 v2, 16, v179
	v_and_b32_e32 v3, 0xffff0000, v179
	v_add_f32_e32 v0, v0, v4
	v_add_f32_e32 v2, 0, v2
	v_add_f32_e32 v3, 0, v3
	v_mul_f32_e32 v4, v1, v1
	v_add_f32_e32 v2, v2, v6
	v_add_f32_e32 v3, v3, v7
	v_fmac_f32_e32 v4, v0, v0
	v_cvt_pk_bf16_f32 v0, v0, v1
	v_cvt_pk_bf16_f32 v1, v2, v3
	ds_write_b64 v241, v[0:1] offset:16
	s_waitcnt vmcnt(13)
	v_and_b32_e32 v1, 0xffff0000, v180
	v_fmac_f32_e32 v4, v2, v2
	v_lshlrev_b32_e32 v0, 16, v180
	v_add_f32_e32 v1, 0, v1
	v_fmac_f32_e32 v4, v3, v3
	v_add_f32_e32 v0, 0, v0
	v_add_f32_e32 v1, v1, v9
	v_lshlrev_b32_e32 v2, 16, v181
	v_and_b32_e32 v3, 0xffff0000, v181
	v_add_f32_e32 v0, v0, v8
	v_add_f32_e32 v2, 0, v2
	v_add_f32_e32 v3, 0, v3
	v_mul_f32_e32 v5, v1, v1
	v_add_f32_e32 v2, v2, v10
	v_add_f32_e32 v3, v3, v11
	v_fmac_f32_e32 v5, v0, v0
	v_cvt_pk_bf16_f32 v0, v0, v1
	v_cvt_pk_bf16_f32 v1, v2, v3
	ds_write_b64 v241, v[0:1] offset:32
	s_waitcnt vmcnt(12)
	v_and_b32_e32 v1, 0xffff0000, v182
	v_fmac_f32_e32 v5, v2, v2
	v_lshlrev_b32_e32 v0, 16, v182
	v_add_f32_e32 v1, 0, v1
	v_add_f32_e32 v4, v48, v4
	v_fmac_f32_e32 v5, v3, v3
	v_add_f32_e32 v0, 0, v0
	v_add_f32_e32 v1, v1, v13
	v_lshlrev_b32_e32 v2, 16, v183
	v_add_f32_e32 v4, v5, v4
	v_add_f32_e32 v0, v0, v12
	v_add_f32_e32 v2, 0, v2
	v_and_b32_e32 v3, 0xffff0000, v183
	v_mul_f32_e32 v5, v1, v1
	v_add_f32_e32 v2, v2, v14
	v_add_f32_e32 v3, 0, v3
	v_fmac_f32_e32 v5, v0, v0
	v_add_f32_e32 v3, v3, v15
	v_fmac_f32_e32 v5, v2, v2
	v_fmac_f32_e32 v5, v3, v3
	v_add_f32_e32 v79, v5, v4
	v_cvt_pk_bf16_f32 v0, v0, v1
	v_cvt_pk_bf16_f32 v1, v2, v3
	ds_write_b64 v241, v[0:1] offset:48
	s_waitcnt lgkmcnt(0)
	ds_read_b128 v[244:247], v242
	ds_read_b128 v[248:251], v242 offset:1152
	v_add_u32_e32 v253, 0x10000, v252
	s_waitcnt lgkmcnt(0)
	global_store_dwordx4 v252, v[244:247], s[82:83]
	global_store_dwordx4 v253, v[248:251], s[82:83]
	s_nop 1
	s_waitcnt vmcnt(13)
	v_mfma_f32_32x32x16_bf16 v[0:15], v[66:69], v[36:39], 0
	v_or_b32_e32 v48, 0x4000, v56
	v_or_b32_e32 v49, 0x4400, v56
	v_or_b32_e32 v66, 0x4800, v56
	global_load_dwordx4 v[58:61], v48, s[4:5]
	global_load_dwordx4 v[62:65], v49, s[4:5]
	v_or_b32_e32 v48, 0x4c00, v56
	v_or_b32_e32 v49, 0x5400, v56
	v_or_b32_e32 v167, 0x80, v57
	s_waitcnt vmcnt(14)
	v_mfma_f32_32x32x16_bf16 v[0:15], v[70:73], v[32:35], v[0:15]
	global_load_dwordx4 v[66:69], v66, s[4:5]
	s_nop 0
	global_load_dwordx4 v[70:73], v48, s[4:5]
	v_or_b32_e32 v48, 0x5000, v56
	v_or_b32_e32 v176, 0x90, v57
	v_or_b32_e32 v198, 0xa0, v57
	v_or_b32_e32 v199, 0xb0, v57
	s_waitcnt vmcnt(15)
	v_mfma_f32_32x32x16_bf16 v[0:15], v[80:83], v[44:47], v[0:15]
	global_load_dwordx4 v[80:83], v48, s[4:5]
	global_load_dwordx4 v[178:181], v49, s[4:5]
	v_or_b32_e32 v48, 0x5800, v56
	v_or_b32_e32 v49, 0x5c00, v56
	s_waitcnt vmcnt(16)
	v_mfma_f32_32x32x16_bf16 v[0:15], v[84:87], v[40:43], v[0:15]
	global_load_dwordx4 v[84:87], v48, s[4:5]
	global_load_dwordx4 v[182:185], v49, s[4:5]
	s_waitcnt vmcnt(17)
	v_mfma_f32_32x32x16_bf16 v[0:15], v[52:55], v[16:19], v[0:15]
	global_load_dwordx2 v[74:75], v167, s[82:83]
	global_load_dwordx2 v[192:193], v176, s[82:83]
	global_load_dwordx2 v[52:53], v198, s[82:83]
	global_load_dwordx2 v[48:49], v199, s[82:83]
	s_waitcnt vmcnt(17)
	v_lshlrev_b32_e32 v54, 16, v186
	v_and_b32_e32 v55, 0xffff0000, v186
	v_add_f32_e32 v54, 0, v54
	v_add_f32_e32 v55, 0, v55
	v_mfma_f32_32x32x16_bf16 v[0:15], v[88:91], v[20:23], v[0:15]
	v_lshlrev_b32_e32 v88, 16, v187
	v_and_b32_e32 v89, 0xffff0000, v187
	v_add_f32_e32 v88, 0, v88
	s_waitcnt vmcnt(16)
	v_lshlrev_b32_e32 v90, 16, v188
	v_add_f32_e32 v89, 0, v89
	v_and_b32_e32 v91, 0xffff0000, v188
	v_add_f32_e32 v90, 0, v90
	v_mfma_f32_32x32x16_bf16 v[0:15], v[168:171], v[24:27], v[0:15]
	v_lshlrev_b32_e32 v168, 16, v189
	v_and_b32_e32 v169, 0xffff0000, v189
	v_add_f32_e32 v91, 0, v91
	v_add_f32_e32 v168, 0, v168
	v_add_f32_e32 v169, 0, v169
	v_mfma_f32_32x32x16_bf16 v[0:15], v[172:175], v[28:31], v[0:15]
	s_nop 11
	v_add_f32_e32 v54, v54, v0
	v_add_f32_e32 v0, v55, v1
	v_add_f32_e32 v2, v88, v2
	v_add_f32_e32 v3, v89, v3
	v_mul_f32_e32 v55, v0, v0
	v_cvt_pk_bf16_f32 v0, v54, v0
	v_cvt_pk_bf16_f32 v1, v2, v3
	v_add_f32_e32 v4, v90, v4
	v_add_f32_e32 v5, v91, v5
	v_add_f32_e32 v6, v168, v6
	v_add_f32_e32 v7, v169, v7
	v_add_u32_e32 v252, v194, v240
	ds_write_b64 v241, v[0:1]
	v_cvt_pk_bf16_f32 v0, v4, v5
	v_cvt_pk_bf16_f32 v1, v6, v7
	v_fmac_f32_e32 v55, v54, v54
	ds_write_b64 v241, v[0:1] offset:16
	s_waitcnt vmcnt(15)
; DI unsigned cvt_pk_bf16(float lo, float hi) { unsigned r; asm volatile("v_cvt_pk_bf16_f32 %0, %1, %2" : "=v"(r) : "v"(lo), "v"(hi)); return r; }
; DI float bf_lo(unsigned w) { return __uint_as_float(w << 16); }
; DI float bf_hi(unsigned w) { return __uint_as_float(w & 0xffff0000u); }
; #define MFMA32(a, b, c) __builtin_amdgcn_mfma_f32_32x32x16_bf16((a), (b), (c), 0, 0, 0)
; template <bool DRY, bool H1>
; DI void intra_phase(LAS unsigned char* lds, const Params& p) {
;     ...
;       for (int t = 0; t < 8; ++t) {
;         if (t < 7) {
; #pragma unroll
;           for (int s = 0; s < 8; ++s) va[(t + 1) & 1][s] = ldg16(vT, vo + (unsigned)(t + 1) * 8192u + 1024u * s);
; #pragma unroll
;           for (int gq = 0; gq < 4; ++gq) { yold[(t + 1) & 1][gq] = *(const u32x2*)((const char*)y + (yo + 64u * (t + 1) + 16u * gq)); if constexpr (H1) yol2[(t + 1) & 1][gq] = *(const u32x2*)((const char*)yb + (yo + 64u * (t + 1) + 16u * gq)); }
;         }
;         f32x16 yt;
; #pragma unroll
;         for (int i = 0; i < 16; ++i) yt[i] = 0.f;
; #pragma unroll
;         for (int s = 0; s < 8; ++s) yt = MFMA32(va[t & 1][s], pf[s], yt);
; #pragma unroll
;         for (int gq = 0; gq < 4; ++gq) {
;           const u32x2 ov = yold[t & 1][gq], o2 = yol2[t & 1][gq];
;           const float v0 = bf_lo(ov.x) + bf_lo(o2.x) + yt[4 * gq], v1 = bf_hi(ov.x) + bf_hi(o2.x) + yt[4 * gq + 1], v2 = bf_lo(ov.y) + bf_lo(o2.y) + yt[4 * gq + 2], v3 = bf_hi(ov.y) + bf_hi(o2.y) + yt[4 * gq + 3];
;           sq2 += v0 * v0 + v1 * v1 + v2 * v2 + v3 * v3;
;           u32x2 a; a.x = cvt_pk_bf16(v0, v1); a.y = cvt_pk_bf16(v2, v3); if (!DRY || v0 == 12345.678f) *(u32x2*)((char*)y + (yo + 64u * t + 16u * gq)) = a;
;         }
	v_and_b32_e32 v1, 0xffff0000, v190
	v_mul_f32_e32 v88, v5, v5
	v_fmac_f32_e32 v55, v2, v2
	v_lshlrev_b32_e32 v0, 16, v190
	v_add_f32_e32 v1, 0, v1
	v_fmac_f32_e32 v88, v4, v4
	v_fmac_f32_e32 v55, v3, v3
	v_add_f32_e32 v0, 0, v0
	v_add_f32_e32 v1, v1, v9
	v_lshlrev_b32_e32 v3, 16, v191
	v_and_b32_e32 v4, 0xffff0000, v191
	v_add_f32_e32 v0, v0, v8
	v_add_f32_e32 v3, 0, v3
	v_add_f32_e32 v4, 0, v4
	v_mul_f32_e32 v5, v1, v1
	v_add_f32_e32 v3, v3, v10
	v_add_f32_e32 v4, v4, v11
	v_fmac_f32_e32 v5, v0, v0
	v_cvt_pk_bf16_f32 v0, v0, v1
	v_cvt_pk_bf16_f32 v1, v3, v4
	v_fmac_f32_e32 v88, v6, v6
	ds_write_b64 v241, v[0:1] offset:32
	s_waitcnt vmcnt(14)
	v_and_b32_e32 v1, 0xffff0000, v50
	v_fmac_f32_e32 v88, v7, v7
	v_add_f32_e32 v2, v79, v55
	v_fmac_f32_e32 v5, v3, v3
	v_lshlrev_b32_e32 v0, 16, v50
	v_add_f32_e32 v1, 0, v1
	v_add_f32_e32 v2, v88, v2
	v_fmac_f32_e32 v5, v4, v4
	v_add_f32_e32 v0, 0, v0
	v_add_f32_e32 v1, v1, v13
	v_lshlrev_b32_e32 v3, 16, v51
	v_add_f32_e32 v2, v5, v2
	v_add_f32_e32 v0, v0, v12
	v_add_f32_e32 v3, 0, v3
	v_and_b32_e32 v4, 0xffff0000, v51
	v_mul_f32_e32 v5, v1, v1
	v_add_f32_e32 v3, v3, v14
	v_add_f32_e32 v4, 0, v4
	v_fmac_f32_e32 v5, v0, v0
	v_add_f32_e32 v4, v4, v15
	v_fmac_f32_e32 v5, v3, v3
	v_fmac_f32_e32 v5, v4, v4
	v_add_f32_e32 v79, v5, v2
	v_cvt_pk_bf16_f32 v0, v0, v1
	v_cvt_pk_bf16_f32 v1, v3, v4
	ds_write_b64 v241, v[0:1] offset:48
	s_waitcnt lgkmcnt(0)
	ds_read_b128 v[244:247], v242
	ds_read_b128 v[248:251], v242 offset:1152
	v_add_u32_e32 v253, 0x10000, v252
	s_waitcnt lgkmcnt(0)
	global_store_dwordx4 v252, v[244:247], s[82:83]
	global_store_dwordx4 v253, v[248:251], s[82:83]
	s_nop 1
	s_waitcnt vmcnt(13)
	v_mfma_f32_32x32x16_bf16 v[0:15], v[58:61], v[36:39], 0
	v_or_b32_e32 v50, 0x6000, v56
	v_or_b32_e32 v51, 0x6400, v56
	v_or_b32_e32 v54, 0x6800, v56
	v_or_b32_e32 v196, 0xc0, v57
	v_or_b32_e32 v197, 0xd0, v57
	v_or_b32_e32 v200, 0xe0, v57
	v_or_b32_e32 v201, 0xf0, v57
	s_waitcnt vmcnt(12)
	v_mfma_f32_32x32x16_bf16 v[0:15], v[62:65], v[32:35], v[0:15]
	global_load_dwordx4 v[58:61], v50, s[4:5]
	global_load_dwordx4 v[62:65], v51, s[4:5]
	v_or_b32_e32 v50, 0x6c00, v56
	v_or_b32_e32 v51, 0x7400, v56
	s_waitcnt vmcnt(13)
	v_mfma_f32_32x32x16_bf16 v[0:15], v[66:69], v[44:47], v[0:15]
	global_load_dwordx4 v[66:69], v54, s[4:5]
	global_load_dwordx4 v[88:91], v50, s[4:5]
	v_or_b32_e32 v50, 0x7000, v56
	global_load_dwordx4 v[168:171], v50, s[4:5]
	global_load_dwordx4 v[172:175], v51, s[4:5]
	v_or_b32_e32 v50, 0x7800, v56
	v_or_b32_e32 v51, 0x7c00, v56
	s_waitcnt vmcnt(16)
	v_mfma_f32_32x32x16_bf16 v[0:15], v[70:73], v[40:43], v[0:15]
	global_load_dwordx4 v[70:73], v50, s[4:5]
	global_load_dwordx4 v[186:189], v51, s[4:5]
	global_load_dwordx2 v[190:191], v196, s[82:83]
	global_load_dwordx2 v[194:195], v197, s[82:83]
	global_load_dwordx2 v[54:55], v200, s[82:83]
	s_nop 0
	global_load_dwordx2 v[50:51], v201, s[82:83]
	s_waitcnt vmcnt(21)
	v_mfma_f32_32x32x16_bf16 v[0:15], v[80:83], v[16:19], v[0:15]
	s_waitcnt vmcnt(17)
	v_lshlrev_b32_e32 v80, 16, v74
	v_and_b32_e32 v74, 0xffff0000, v74
	v_add_f32_e32 v80, 0, v80
	v_add_f32_e32 v74, 0, v74
	v_lshlrev_b32_e32 v81, 16, v75
	v_and_b32_e32 v75, 0xffff0000, v75
	v_add_f32_e32 v81, 0, v81
	v_mfma_f32_32x32x16_bf16 v[0:15], v[178:181], v[20:23], v[0:15]
	s_waitcnt vmcnt(16)
	v_lshlrev_b32_e32 v82, 16, v192
	v_add_f32_e32 v75, 0, v75
	v_and_b32_e32 v83, 0xffff0000, v192
	v_add_f32_e32 v82, 0, v82
	v_add_f32_e32 v83, 0, v83
	v_mfma_f32_32x32x16_bf16 v[0:15], v[84:87], v[24:27], v[0:15]
	v_lshlrev_b32_e32 v84, 16, v193
	v_and_b32_e32 v85, 0xffff0000, v193
	v_add_f32_e32 v84, 0, v84
	v_add_f32_e32 v85, 0, v85
	v_mfma_f32_32x32x16_bf16 v[0:15], v[182:185], v[28:31], v[0:15]
	s_nop 11
	v_add_f32_e32 v80, v80, v0
	v_add_f32_e32 v0, v74, v1
	v_add_f32_e32 v2, v81, v2
	v_add_f32_e32 v3, v75, v3
	v_mul_f32_e32 v74, v0, v0
	v_cvt_pk_bf16_f32 v0, v80, v0
	v_cvt_pk_bf16_f32 v1, v2, v3
	v_add_f32_e32 v4, v82, v4
	v_add_f32_e32 v5, v83, v5
	v_add_f32_e32 v6, v84, v6
	v_add_f32_e32 v7, v85, v7
	v_add_u32_e32 v252, v167, v240
	ds_write_b64 v241, v[0:1]
	v_cvt_pk_bf16_f32 v0, v4, v5
	v_cvt_pk_bf16_f32 v1, v6, v7
	v_fmac_f32_e32 v74, v80, v80
	ds_write_b64 v241, v[0:1] offset:16
	s_waitcnt vmcnt(15)
	v_and_b32_e32 v1, 0xffff0000, v52
	v_mul_f32_e32 v75, v5, v5
	v_fmac_f32_e32 v74, v2, v2
	v_lshlrev_b32_e32 v0, 16, v52
	v_add_f32_e32 v1, 0, v1
	v_fmac_f32_e32 v75, v4, v4
	v_fmac_f32_e32 v74, v3, v3
	v_add_f32_e32 v0, 0, v0
	v_add_f32_e32 v1, v1, v9
	v_lshlrev_b32_e32 v3, 16, v53
	v_and_b32_e32 v4, 0xffff0000, v53
	v_add_f32_e32 v0, v0, v8
	v_add_f32_e32 v3, 0, v3
	v_add_f32_e32 v4, 0, v4
	v_mul_f32_e32 v5, v1, v1
	v_add_f32_e32 v3, v3, v10
	v_add_f32_e32 v4, v4, v11
	v_fmac_f32_e32 v5, v0, v0
	v_cvt_pk_bf16_f32 v0, v0, v1
	v_cvt_pk_bf16_f32 v1, v3, v4
	v_fmac_f32_e32 v75, v6, v6
	ds_write_b64 v241, v[0:1] offset:32
	s_waitcnt vmcnt(14)
	v_and_b32_e32 v1, 0xffff0000, v48
	v_fmac_f32_e32 v75, v7, v7
	v_add_f32_e32 v2, v79, v74
	v_fmac_f32_e32 v5, v3, v3
	v_lshlrev_b32_e32 v0, 16, v48
	v_add_f32_e32 v1, 0, v1
	v_add_f32_e32 v2, v75, v2
	v_fmac_f32_e32 v5, v4, v4
	v_add_f32_e32 v0, 0, v0
	v_add_f32_e32 v1, v1, v13
	v_lshlrev_b32_e32 v3, 16, v49
	v_add_f32_e32 v2, v5, v2
	v_add_f32_e32 v0, v0, v12
	v_add_f32_e32 v3, 0, v3
	v_and_b32_e32 v4, 0xffff0000, v49
	v_mul_f32_e32 v5, v1, v1
	v_add_f32_e32 v3, v3, v14
	v_add_f32_e32 v4, 0, v4
	v_fmac_f32_e32 v5, v0, v0
	v_add_f32_e32 v4, v4, v15
	v_fmac_f32_e32 v5, v3, v3
	v_fmac_f32_e32 v5, v4, v4
	v_add_f32_e32 v79, v5, v2
	v_cvt_pk_bf16_f32 v0, v0, v1
	v_cvt_pk_bf16_f32 v1, v3, v4
	ds_write_b64 v241, v[0:1] offset:48
	s_waitcnt lgkmcnt(0)
; DI unsigned cvt_pk_bf16(float lo, float hi) { unsigned r; asm volatile("v_cvt_pk_bf16_f32 %0, %1, %2" : "=v"(r) : "v"(lo), "v"(hi)); return r; }
; DI float bf_lo(unsigned w) { return __uint_as_float(w << 16); }
; DI float bf_hi(unsigned w) { return __uint_as_float(w & 0xffff0000u); }
; #define MFMA32(a, b, c) __builtin_amdgcn_mfma_f32_32x32x16_bf16((a), (b), (c), 0, 0, 0)
; template <bool DRY, bool H1>
; DI void intra_phase(LAS unsigned char* lds, const Params& p) {
;     ...
;       for (int t = 0; t < 8; ++t) {
;         if (t < 7) {
; #pragma unroll
;           for (int s = 0; s < 8; ++s) va[(t + 1) & 1][s] = ldg16(vT, vo + (unsigned)(t + 1) * 8192u + 1024u * s);
; #pragma unroll
;           for (int gq = 0; gq < 4; ++gq) { yold[(t + 1) & 1][gq] = *(const u32x2*)((const char*)y + (yo + 64u * (t + 1) + 16u * gq)); if constexpr (H1) yol2[(t + 1) & 1][gq] = *(const u32x2*)((const char*)yb + (yo + 64u * (t + 1) + 16u * gq)); }
;         }
;         f32x16 yt;
; #pragma unroll
;         for (int i = 0; i < 16; ++i) yt[i] = 0.f;
; #pragma unroll
;         for (int s = 0; s < 8; ++s) yt = MFMA32(va[t & 1][s], pf[s], yt);
; #pragma unroll
;         for (int gq = 0; gq < 4; ++gq) {
;           const u32x2 ov = yold[t & 1][gq], o2 = yol2[t & 1][gq];
;           const float v0 = bf_lo(ov.x) + bf_lo(o2.x) + yt[4 * gq], v1 = bf_hi(ov.x) + bf_hi(o2.x) + yt[4 * gq + 1], v2 = bf_lo(ov.y) + bf_lo(o2.y) + yt[4 * gq + 2], v3 = bf_hi(ov.y) + bf_hi(o2.y) + yt[4 * gq + 3];
;           sq2 += v0 * v0 + v1 * v1 + v2 * v2 + v3 * v3;
;           u32x2 a; a.x = cvt_pk_bf16(v0, v1); a.y = cvt_pk_bf16(v2, v3); if (!DRY || v0 == 12345.678f) *(u32x2*)((char*)y + (yo + 64u * t + 16u * gq)) = a;
;         }
	ds_read_b128 v[244:247], v242
	ds_read_b128 v[248:251], v242 offset:1152
	v_add_u32_e32 v253, 0x10000, v252
	s_waitcnt lgkmcnt(0)
	global_store_dwordx4 v252, v[244:247], s[82:83]
	global_store_dwordx4 v253, v[248:251], s[82:83]
	s_nop 1
	s_waitcnt vmcnt(13)
	v_mfma_f32_32x32x16_bf16 v[0:15], v[58:61], v[36:39], 0
	v_or_b32_e32 v48, 0x8000, v56
	v_or_b32_e32 v49, 0x8400, v56
	v_or_b32_e32 v52, 0x8800, v56
	v_or_b32_e32 v167, 0x100, v57
	v_or_b32_e32 v176, 0x110, v57
	v_or_b32_e32 v203, 0x120, v57
	v_or_b32_e32 v204, 0x130, v57
	s_waitcnt vmcnt(12)
	v_mfma_f32_32x32x16_bf16 v[0:15], v[62:65], v[32:35], v[0:15]
	global_load_dwordx4 v[58:61], v48, s[4:5]
	global_load_dwordx4 v[62:65], v49, s[4:5]
	v_or_b32_e32 v48, 0x8c00, v56
	v_or_b32_e32 v49, 0x9400, v56
	s_waitcnt vmcnt(13)
	v_mfma_f32_32x32x16_bf16 v[0:15], v[66:69], v[44:47], v[0:15]
	global_load_dwordx4 v[66:69], v52, s[4:5]
	global_load_dwordx4 v[80:83], v48, s[4:5]
	v_or_b32_e32 v48, 0x9000, v56
	global_load_dwordx4 v[84:87], v48, s[4:5]
	global_load_dwordx4 v[178:181], v49, s[4:5]
	v_or_b32_e32 v48, 0x9800, v56
	v_or_b32_e32 v49, 0x9c00, v56
	s_waitcnt vmcnt(16)
	v_mfma_f32_32x32x16_bf16 v[0:15], v[88:91], v[40:43], v[0:15]
	global_load_dwordx4 v[88:91], v48, s[4:5]
	global_load_dwordx4 v[182:185], v49, s[4:5]
	global_load_dwordx2 v[74:75], v167, s[82:83]
	global_load_dwordx2 v[192:193], v176, s[82:83]
	global_load_dwordx2 v[52:53], v203, s[82:83]
	s_nop 0
	global_load_dwordx2 v[48:49], v204, s[82:83]
	s_waitcnt vmcnt(21)
	v_mfma_f32_32x32x16_bf16 v[0:15], v[168:171], v[16:19], v[0:15]
	s_waitcnt vmcnt(17)
	v_lshlrev_b32_e32 v168, 16, v190
	v_and_b32_e32 v169, 0xffff0000, v190
	v_add_f32_e32 v168, 0, v168
	v_add_f32_e32 v169, 0, v169
	v_lshlrev_b32_e32 v170, 16, v191
	v_and_b32_e32 v171, 0xffff0000, v191
	v_add_f32_e32 v170, 0, v170
	v_mfma_f32_32x32x16_bf16 v[0:15], v[172:175], v[20:23], v[0:15]
	s_waitcnt vmcnt(16)
	v_lshlrev_b32_e32 v172, 16, v194
	v_add_f32_e32 v171, 0, v171
	v_mfma_f32_32x32x16_bf16 v[0:15], v[70:73], v[24:27], v[0:15]
	v_add_f32_e32 v70, 0, v172
	v_and_b32_e32 v71, 0xffff0000, v194
	v_lshlrev_b32_e32 v72, 16, v195
	v_and_b32_e32 v73, 0xffff0000, v195
	v_add_f32_e32 v71, 0, v71
	v_add_f32_e32 v72, 0, v72
	v_add_f32_e32 v73, 0, v73
	v_mfma_f32_32x32x16_bf16 v[0:15], v[186:189], v[28:31], v[0:15]
	s_nop 11
	v_add_f32_e32 v168, v168, v0
	v_add_f32_e32 v0, v169, v1
	v_add_f32_e32 v2, v170, v2
	v_add_f32_e32 v3, v171, v3
	v_add_f32_e32 v4, v70, v4
	v_mul_f32_e32 v70, v0, v0
	v_cvt_pk_bf16_f32 v0, v168, v0
	v_cvt_pk_bf16_f32 v1, v2, v3
	v_add_f32_e32 v5, v71, v5
	v_add_f32_e32 v6, v72, v6
	v_add_f32_e32 v7, v73, v7
	v_add_u32_e32 v252, v196, v240
	ds_write_b64 v241, v[0:1]
	v_cvt_pk_bf16_f32 v0, v4, v5
	v_cvt_pk_bf16_f32 v1, v6, v7
	v_fmac_f32_e32 v70, v168, v168
	ds_write_b64 v241, v[0:1] offset:16
	s_waitcnt vmcnt(15)
	v_and_b32_e32 v1, 0xffff0000, v54
	v_mul_f32_e32 v71, v5, v5
	v_fmac_f32_e32 v70, v2, v2
	v_lshlrev_b32_e32 v0, 16, v54
	v_add_f32_e32 v1, 0, v1
	v_fmac_f32_e32 v71, v4, v4
	v_fmac_f32_e32 v70, v3, v3
	v_add_f32_e32 v0, 0, v0
	v_add_f32_e32 v1, v1, v9
	v_lshlrev_b32_e32 v3, 16, v55
	v_and_b32_e32 v4, 0xffff0000, v55
	v_add_f32_e32 v0, v0, v8
	v_add_f32_e32 v3, 0, v3
	v_add_f32_e32 v4, 0, v4
	v_mul_f32_e32 v5, v1, v1
	v_add_f32_e32 v3, v3, v10
	v_add_f32_e32 v4, v4, v11
	v_fmac_f32_e32 v5, v0, v0
	v_cvt_pk_bf16_f32 v0, v0, v1
	v_cvt_pk_bf16_f32 v1, v3, v4
	v_fmac_f32_e32 v71, v6, v6
	ds_write_b64 v241, v[0:1] offset:32
	s_waitcnt vmcnt(14)
	v_and_b32_e32 v1, 0xffff0000, v50
	v_fmac_f32_e32 v71, v7, v7
	v_add_f32_e32 v2, v79, v70
	v_fmac_f32_e32 v5, v3, v3
	v_lshlrev_b32_e32 v0, 16, v50
	v_add_f32_e32 v1, 0, v1
	v_add_f32_e32 v2, v71, v2
	v_fmac_f32_e32 v5, v4, v4
	v_add_f32_e32 v0, 0, v0
	v_add_f32_e32 v1, v1, v13
	v_lshlrev_b32_e32 v3, 16, v51
	v_add_f32_e32 v2, v5, v2
	v_add_f32_e32 v0, v0, v12
	v_add_f32_e32 v3, 0, v3
	v_and_b32_e32 v4, 0xffff0000, v51
	v_mul_f32_e32 v5, v1, v1
	v_add_f32_e32 v3, v3, v14
	v_add_f32_e32 v4, 0, v4
	v_fmac_f32_e32 v5, v0, v0
	v_add_f32_e32 v4, v4, v15
	v_fmac_f32_e32 v5, v3, v3
	v_fmac_f32_e32 v5, v4, v4
	v_add_f32_e32 v79, v5, v2
	v_cvt_pk_bf16_f32 v0, v0, v1
	v_cvt_pk_bf16_f32 v1, v3, v4
	ds_write_b64 v241, v[0:1] offset:48
	s_waitcnt lgkmcnt(0)
	ds_read_b128 v[244:247], v242
	ds_read_b128 v[248:251], v242 offset:1152
	v_add_u32_e32 v253, 0x10000, v252
	s_waitcnt lgkmcnt(0)
	global_store_dwordx4 v252, v[244:247], s[82:83]
	global_store_dwordx4 v253, v[248:251], s[82:83]
	s_nop 1
	s_waitcnt vmcnt(13)
	v_mfma_f32_32x32x16_bf16 v[0:15], v[58:61], v[36:39], 0
	v_or_b32_e32 v50, 0xa000, v56
	v_or_b32_e32 v51, 0xa400, v56
	v_or_b32_e32 v54, 0xa800, v56
	v_or_b32_e32 v206, 0x140, v57
	v_or_b32_e32 v207, 0x150, v57
	v_or_b32_e32 v210, 0x160, v57
	v_or_b32_e32 v211, 0x170, v57
	s_waitcnt vmcnt(12)
	v_mfma_f32_32x32x16_bf16 v[0:15], v[62:65], v[32:35], v[0:15]
	global_load_dwordx4 v[58:61], v50, s[4:5]
	global_load_dwordx4 v[62:65], v51, s[4:5]
	v_or_b32_e32 v50, 0xac00, v56
	v_or_b32_e32 v51, 0xb400, v56
	s_waitcnt vmcnt(13)
	v_mfma_f32_32x32x16_bf16 v[0:15], v[66:69], v[44:47], v[0:15]
	global_load_dwordx4 v[66:69], v54, s[4:5]
	global_load_dwordx4 v[70:73], v50, s[4:5]
	v_or_b32_e32 v50, 0xb000, v56
	global_load_dwordx4 v[168:171], v50, s[4:5]
	global_load_dwordx4 v[172:175], v51, s[4:5]
	v_or_b32_e32 v50, 0xb800, v56
	v_or_b32_e32 v51, 0xbc00, v56
	s_waitcnt vmcnt(16)
	v_mfma_f32_32x32x16_bf16 v[0:15], v[80:83], v[40:43], v[0:15]
	global_load_dwordx4 v[80:83], v50, s[4:5]
	global_load_dwordx4 v[186:189], v51, s[4:5]
	global_load_dwordx2 v[198:199], v206, s[82:83]
	global_load_dwordx2 v[200:201], v207, s[82:83]
	global_load_dwordx2 v[54:55], v210, s[82:83]
	s_nop 0
	global_load_dwordx2 v[50:51], v211, s[82:83]
	s_waitcnt vmcnt(21)
; DI unsigned cvt_pk_bf16(float lo, float hi) { unsigned r; asm volatile("v_cvt_pk_bf16_f32 %0, %1, %2" : "=v"(r) : "v"(lo), "v"(hi)); return r; }
; DI float bf_lo(unsigned w) { return __uint_as_float(w << 16); }
; DI float bf_hi(unsigned w) { return __uint_as_float(w & 0xffff0000u); }
; #define MFMA32(a, b, c) __builtin_amdgcn_mfma_f32_32x32x16_bf16((a), (b), (c), 0, 0, 0)
; template <bool DRY, bool H1>
; DI void intra_phase(LAS unsigned char* lds, const Params& p) {
;     ...
;       for (int t = 0; t < 8; ++t) {
;         if (t < 7) {
; #pragma unroll
;           for (int s = 0; s < 8; ++s) va[(t + 1) & 1][s] = ldg16(vT, vo + (unsigned)(t + 1) * 8192u + 1024u * s);
; #pragma unroll
;           for (int gq = 0; gq < 4; ++gq) { yold[(t + 1) & 1][gq] = *(const u32x2*)((const char*)y + (yo + 64u * (t + 1) + 16u * gq)); if constexpr (H1) yol2[(t + 1) & 1][gq] = *(const u32x2*)((const char*)yb + (yo + 64u * (t + 1) + 16u * gq)); }
;         }
;         f32x16 yt;
; #pragma unroll
;         for (int i = 0; i < 16; ++i) yt[i] = 0.f;
; #pragma unroll
;         for (int s = 0; s < 8; ++s) yt = MFMA32(va[t & 1][s], pf[s], yt);
; #pragma unroll
;         for (int gq = 0; gq < 4; ++gq) {
;           const u32x2 ov = yold[t & 1][gq], o2 = yol2[t & 1][gq];
;           const float v0 = bf_lo(ov.x) + bf_lo(o2.x) + yt[4 * gq], v1 = bf_hi(ov.x) + bf_hi(o2.x) + yt[4 * gq + 1], v2 = bf_lo(ov.y) + bf_lo(o2.y) + yt[4 * gq + 2], v3 = bf_hi(ov.y) + bf_hi(o2.y) + yt[4 * gq + 3];
;           sq2 += v0 * v0 + v1 * v1 + v2 * v2 + v3 * v3;
;           u32x2 a; a.x = cvt_pk_bf16(v0, v1); a.y = cvt_pk_bf16(v2, v3); if (!DRY || v0 == 12345.678f) *(u32x2*)((char*)y + (yo + 64u * t + 16u * gq)) = a;
;         }
	v_mfma_f32_32x32x16_bf16 v[0:15], v[84:87], v[16:19], v[0:15]
	s_waitcnt vmcnt(17)
	v_lshlrev_b32_e32 v84, 16, v74
	v_and_b32_e32 v74, 0xffff0000, v74
	v_add_f32_e32 v84, 0, v84
	v_add_f32_e32 v74, 0, v74
	v_lshlrev_b32_e32 v85, 16, v75
	v_and_b32_e32 v75, 0xffff0000, v75
	v_add_f32_e32 v85, 0, v85
	v_mfma_f32_32x32x16_bf16 v[0:15], v[178:181], v[20:23], v[0:15]
	s_waitcnt vmcnt(16)
	v_lshlrev_b32_e32 v86, 16, v192
	v_add_f32_e32 v75, 0, v75
	v_and_b32_e32 v87, 0xffff0000, v192
	v_add_f32_e32 v86, 0, v86
	v_add_f32_e32 v87, 0, v87
	v_mfma_f32_32x32x16_bf16 v[0:15], v[88:91], v[24:27], v[0:15]
	v_lshlrev_b32_e32 v88, 16, v193
	v_and_b32_e32 v89, 0xffff0000, v193
	v_add_f32_e32 v88, 0, v88
	v_add_f32_e32 v89, 0, v89
	v_mfma_f32_32x32x16_bf16 v[0:15], v[182:185], v[28:31], v[0:15]
	s_nop 11
	v_add_f32_e32 v84, v84, v0
	v_add_f32_e32 v0, v74, v1
	v_add_f32_e32 v2, v85, v2
	v_add_f32_e32 v3, v75, v3
	v_mul_f32_e32 v74, v0, v0
	v_cvt_pk_bf16_f32 v0, v84, v0
	v_cvt_pk_bf16_f32 v1, v2, v3
	v_add_f32_e32 v4, v86, v4
	v_add_f32_e32 v5, v87, v5
	v_add_f32_e32 v6, v88, v6
	v_add_f32_e32 v7, v89, v7
	v_add_u32_e32 v252, v167, v240
	ds_write_b64 v241, v[0:1]
	v_cvt_pk_bf16_f32 v0, v4, v5
	v_cvt_pk_bf16_f32 v1, v6, v7
	v_fmac_f32_e32 v74, v84, v84
	ds_write_b64 v241, v[0:1] offset:16
	s_waitcnt vmcnt(15)
	v_and_b32_e32 v1, 0xffff0000, v52
	v_mul_f32_e32 v75, v5, v5
	v_fmac_f32_e32 v74, v2, v2
	v_lshlrev_b32_e32 v0, 16, v52
	v_add_f32_e32 v1, 0, v1
	v_fmac_f32_e32 v75, v4, v4
	v_fmac_f32_e32 v74, v3, v3
	v_add_f32_e32 v0, 0, v0
	v_add_f32_e32 v1, v1, v9
	v_lshlrev_b32_e32 v3, 16, v53
	v_and_b32_e32 v4, 0xffff0000, v53
	v_add_f32_e32 v0, v0, v8
	v_add_f32_e32 v3, 0, v3
	v_add_f32_e32 v4, 0, v4
	v_mul_f32_e32 v5, v1, v1
	v_add_f32_e32 v3, v3, v10
	v_add_f32_e32 v4, v4, v11
	v_fmac_f32_e32 v5, v0, v0
	v_cvt_pk_bf16_f32 v0, v0, v1
	v_cvt_pk_bf16_f32 v1, v3, v4
	v_fmac_f32_e32 v75, v6, v6
	ds_write_b64 v241, v[0:1] offset:32
	s_waitcnt vmcnt(14)
	v_and_b32_e32 v1, 0xffff0000, v48
	v_fmac_f32_e32 v75, v7, v7
	v_add_f32_e32 v2, v79, v74
	v_fmac_f32_e32 v5, v3, v3
	v_lshlrev_b32_e32 v0, 16, v48
	v_add_f32_e32 v1, 0, v1
	v_add_f32_e32 v2, v75, v2
	v_fmac_f32_e32 v5, v4, v4
	v_add_f32_e32 v0, 0, v0
	v_add_f32_e32 v1, v1, v13
	v_lshlrev_b32_e32 v3, 16, v49
	v_add_f32_e32 v2, v5, v2
	v_add_f32_e32 v0, v0, v12
	v_add_f32_e32 v3, 0, v3
	v_and_b32_e32 v4, 0xffff0000, v49
	v_mul_f32_e32 v5, v1, v1
	v_add_f32_e32 v3, v3, v14
	v_add_f32_e32 v4, 0, v4
	v_fmac_f32_e32 v5, v0, v0
	v_add_f32_e32 v4, v4, v15
	v_fmac_f32_e32 v5, v3, v3
	v_fmac_f32_e32 v5, v4, v4
	v_add_f32_e32 v48, v5, v2
	v_cvt_pk_bf16_f32 v0, v0, v1
	v_cvt_pk_bf16_f32 v1, v3, v4
	ds_write_b64 v241, v[0:1] offset:48
	s_waitcnt lgkmcnt(0)
	ds_read_b128 v[244:247], v242
	ds_read_b128 v[248:251], v242 offset:1152
	v_add_u32_e32 v253, 0x10000, v252
	s_waitcnt lgkmcnt(0)
	global_store_dwordx4 v252, v[244:247], s[82:83]
	global_store_dwordx4 v253, v[248:251], s[82:83]
	s_nop 1
	s_waitcnt vmcnt(13)
	v_mfma_f32_32x32x16_bf16 v[0:15], v[58:61], v[36:39], 0
	v_or_b32_e32 v49, 0xc000, v56
	v_or_b32_e32 v52, 0xc400, v56
	v_or_b32_e32 v53, 0xc800, v56
	v_or_b32_e32 v176, 0x180, v57
	v_or_b32_e32 v203, 0x190, v57
	v_or_b32_e32 v215, 0x1a0, v57
	v_or_b32_e32 v216, 0x1b0, v57
	s_waitcnt vmcnt(12)
	v_mfma_f32_32x32x16_bf16 v[0:15], v[62:65], v[32:35], v[0:15]
	global_load_dwordx4 v[58:61], v49, s[4:5]
	global_load_dwordx4 v[62:65], v52, s[4:5]
	v_or_b32_e32 v49, 0xcc00, v56
	global_load_dwordx4 v[84:87], v53, s[4:5]
	global_load_dwordx4 v[178:181], v49, s[4:5]
	v_or_b32_e32 v49, 0xd000, v56
	v_or_b32_e32 v52, 0xd400, v56
	global_load_dwordx4 v[182:185], v49, s[4:5]
	global_load_dwordx4 v[190:193], v52, s[4:5]
	v_or_b32_e32 v49, 0xd800, v56
	s_waitcnt vmcnt(17)
	v_mfma_f32_32x32x16_bf16 v[0:15], v[66:69], v[44:47], v[0:15]
	v_or_b32_e32 v52, 0xdc00, v56
	s_waitcnt vmcnt(11)
	v_lshlrev_b32_e32 v53, 16, v199
	v_and_b32_e32 v66, 0xffff0000, v199
	v_add_f32_e32 v53, 0, v53
	s_waitcnt vmcnt(10)
	v_lshlrev_b32_e32 v67, 16, v200
	v_add_f32_e32 v66, 0, v66
	v_and_b32_e32 v74, 0xffff0000, v201
	v_mfma_f32_32x32x16_bf16 v[0:15], v[70:73], v[40:43], v[0:15]
	global_load_dwordx4 v[194:197], v49, s[4:5]
	global_load_dwordx4 v[68:71], v52, s[4:5]
	global_load_dwordx2 v[204:205], v176, s[82:83]
	global_load_dwordx2 v[208:209], v203, s[82:83]
	global_load_dwordx2 v[90:91], v215, s[82:83]
	global_load_dwordx2 v[88:89], v216, s[82:83]
	v_lshlrev_b32_e32 v49, 16, v198
	v_and_b32_e32 v52, 0xffff0000, v198
	v_add_f32_e32 v49, 0, v49
	v_add_f32_e32 v52, 0, v52
	v_and_b32_e32 v72, 0xffff0000, v200
	v_mfma_f32_32x32x16_bf16 v[0:15], v[168:171], v[16:19], v[0:15]
	v_lshlrev_b32_e32 v73, 16, v201
	v_add_f32_e32 v67, 0, v67
	v_add_f32_e32 v72, 0, v72
	v_add_f32_e32 v73, 0, v73
	v_add_f32_e32 v74, 0, v74
	v_mfma_f32_32x32x16_bf16 v[0:15], v[172:175], v[20:23], v[0:15]
	v_mfma_f32_32x32x16_bf16 v[0:15], v[80:83], v[24:27], v[0:15]
	v_mfma_f32_32x32x16_bf16 v[0:15], v[186:189], v[28:31], v[0:15]
	s_nop 11
	v_add_f32_e32 v49, v49, v0
	v_add_f32_e32 v0, v52, v1
	v_add_f32_e32 v2, v53, v2
	v_add_f32_e32 v3, v66, v3
	v_mul_f32_e32 v52, v0, v0
	v_cvt_pk_bf16_f32 v0, v49, v0
	v_cvt_pk_bf16_f32 v1, v2, v3
	v_add_f32_e32 v4, v67, v4
	v_add_f32_e32 v5, v72, v5
	v_add_f32_e32 v6, v73, v6
	v_add_f32_e32 v7, v74, v7
	v_add_u32_e32 v252, v206, v240
	ds_write_b64 v241, v[0:1]
	v_cvt_pk_bf16_f32 v0, v4, v5
	v_cvt_pk_bf16_f32 v1, v6, v7
	v_fmac_f32_e32 v52, v49, v49
	ds_write_b64 v241, v[0:1] offset:16
	s_waitcnt vmcnt(15)
; DI unsigned cvt_pk_bf16(float lo, float hi) { unsigned r; asm volatile("v_cvt_pk_bf16_f32 %0, %1, %2" : "=v"(r) : "v"(lo), "v"(hi)); return r; }
; DI float bf_lo(unsigned w) { return __uint_as_float(w << 16); }
; DI float bf_hi(unsigned w) { return __uint_as_float(w & 0xffff0000u); }
; #define MFMA32(a, b, c) __builtin_amdgcn_mfma_f32_32x32x16_bf16((a), (b), (c), 0, 0, 0)
; template <bool DRY, bool H1>
; DI void intra_phase(LAS unsigned char* lds, const Params& p) {
;     ...
;       for (int t = 0; t < 8; ++t) {
;         if (t < 7) {
; #pragma unroll
;           for (int s = 0; s < 8; ++s) va[(t + 1) & 1][s] = ldg16(vT, vo + (unsigned)(t + 1) * 8192u + 1024u * s);
; #pragma unroll
;           for (int gq = 0; gq < 4; ++gq) { yold[(t + 1) & 1][gq] = *(const u32x2*)((const char*)y + (yo + 64u * (t + 1) + 16u * gq)); if constexpr (H1) yol2[(t + 1) & 1][gq] = *(const u32x2*)((const char*)yb + (yo + 64u * (t + 1) + 16u * gq)); }
;         }
;         f32x16 yt;
; #pragma unroll
;         for (int i = 0; i < 16; ++i) yt[i] = 0.f;
; #pragma unroll
;         for (int s = 0; s < 8; ++s) yt = MFMA32(va[t & 1][s], pf[s], yt);
; #pragma unroll
;         for (int gq = 0; gq < 4; ++gq) {
;           const u32x2 ov = yold[t & 1][gq], o2 = yol2[t & 1][gq];
;           const float v0 = bf_lo(ov.x) + bf_lo(o2.x) + yt[4 * gq], v1 = bf_hi(ov.x) + bf_hi(o2.x) + yt[4 * gq + 1], v2 = bf_lo(ov.y) + bf_lo(o2.y) + yt[4 * gq + 2], v3 = bf_hi(ov.y) + bf_hi(o2.y) + yt[4 * gq + 3];
;           sq2 += v0 * v0 + v1 * v1 + v2 * v2 + v3 * v3;
;           u32x2 a; a.x = cvt_pk_bf16(v0, v1); a.y = cvt_pk_bf16(v2, v3); if (!DRY || v0 == 12345.678f) *(u32x2*)((char*)y + (yo + 64u * t + 16u * gq)) = a;
;         }
	v_and_b32_e32 v1, 0xffff0000, v54
	v_mul_f32_e32 v53, v5, v5
	v_fmac_f32_e32 v52, v2, v2
	v_lshlrev_b32_e32 v0, 16, v54
	v_add_f32_e32 v1, 0, v1
	v_fmac_f32_e32 v53, v4, v4
	v_fmac_f32_e32 v52, v3, v3
	v_add_f32_e32 v0, 0, v0
	v_add_f32_e32 v1, v1, v9
	v_lshlrev_b32_e32 v3, 16, v55
	v_and_b32_e32 v4, 0xffff0000, v55
	v_add_f32_e32 v0, v0, v8
	v_add_f32_e32 v3, 0, v3
	v_add_f32_e32 v4, 0, v4
	v_mul_f32_e32 v5, v1, v1
	v_add_f32_e32 v3, v3, v10
	v_add_f32_e32 v4, v4, v11
	v_fmac_f32_e32 v5, v0, v0
	v_cvt_pk_bf16_f32 v0, v0, v1
	v_cvt_pk_bf16_f32 v1, v3, v4
	v_fmac_f32_e32 v53, v6, v6
	ds_write_b64 v241, v[0:1] offset:32
	s_waitcnt vmcnt(14)
	v_and_b32_e32 v1, 0xffff0000, v50
	v_fmac_f32_e32 v53, v7, v7
	v_add_f32_e32 v2, v48, v52
	v_fmac_f32_e32 v5, v3, v3
	v_lshlrev_b32_e32 v0, 16, v50
	v_add_f32_e32 v1, 0, v1
	v_add_f32_e32 v2, v53, v2
	v_fmac_f32_e32 v5, v4, v4
	v_add_f32_e32 v0, 0, v0
	v_add_f32_e32 v1, v1, v13
	v_lshlrev_b32_e32 v3, 16, v51
	v_add_f32_e32 v2, v5, v2
	v_add_f32_e32 v0, v0, v12
	v_add_f32_e32 v3, 0, v3
	v_and_b32_e32 v4, 0xffff0000, v51
	v_mul_f32_e32 v5, v1, v1
	v_add_f32_e32 v3, v3, v14
	v_add_f32_e32 v4, 0, v4
	v_fmac_f32_e32 v5, v0, v0
	v_add_f32_e32 v4, v4, v15
	v_fmac_f32_e32 v5, v3, v3
	v_fmac_f32_e32 v5, v4, v4
	v_add_f32_e32 v186, v5, v2
	v_cvt_pk_bf16_f32 v0, v0, v1
	v_cvt_pk_bf16_f32 v1, v3, v4
	ds_write_b64 v241, v[0:1] offset:48
	s_waitcnt lgkmcnt(0)
	ds_read_b128 v[244:247], v242
	ds_read_b128 v[248:251], v242 offset:1152
	v_add_u32_e32 v253, 0x10000, v252
	s_waitcnt lgkmcnt(0)
	global_store_dwordx4 v252, v[244:247], s[82:83]
	global_store_dwordx4 v253, v[248:251], s[82:83]
	s_nop 1
	s_waitcnt vmcnt(13)
	v_mfma_f32_32x32x16_bf16 v[0:15], v[58:61], v[36:39], 0
	v_or_b32_e32 v48, 0xe000, v56
	v_or_b32_e32 v49, 0xe400, v56
	v_or_b32_e32 v50, 0xe800, v56
	v_or_b32_e32 v51, 0xec00, v56
	global_load_dwordx4 v[168:171], v48, s[4:5]
	global_load_dwordx4 v[172:175], v49, s[4:5]
	v_or_b32_e32 v48, 0xf000, v56
	v_or_b32_e32 v52, 0xf400, v56
	s_waitcnt vmcnt(14)
	v_mfma_f32_32x32x16_bf16 v[0:15], v[62:65], v[32:35], v[0:15]
	v_or_b32_e32 v58, 0xf800, v56
	v_or_b32_e32 v60, 0xfc00, v56
	global_load_dwordx4 v[72:75], v50, s[4:5]
	global_load_dwordx4 v[64:67], v51, s[4:5]
	s_nop 0
	global_load_dwordx4 v[48:51], v48, s[4:5]
	s_nop 0
	global_load_dwordx4 v[52:55], v52, s[4:5]
	v_or_b32_e32 v167, 0x1e0, v57
	v_or_b32_e32 v79, 0x1f0, v57
	s_waitcnt vmcnt(10)
	v_lshlrev_b32_e32 v187, 16, v209
	v_mfma_f32_32x32x16_bf16 v[0:15], v[84:87], v[44:47], v[0:15]
	v_and_b32_e32 v188, 0xffff0000, v209
	v_add_f32_e32 v187, 0, v187
	v_add_f32_e32 v188, 0, v188
	s_waitcnt vmcnt(9)
	v_lshlrev_b32_e32 v189, 16, v90
	v_and_b32_e32 v90, 0xffff0000, v90
	v_add_f32_e32 v189, 0, v189
	v_add_f32_e32 v90, 0, v90
	v_mfma_f32_32x32x16_bf16 v[0:15], v[178:181], v[40:43], v[0:15]
	v_or_b32_e32 v178, 0x1c0, v57
	v_or_b32_e32 v179, 0x1d0, v57
	global_load_dwordx4 v[56:59], v58, s[4:5]
	s_nop 0
	global_load_dwordx4 v[60:63], v60, s[4:5]
	s_nop 0
	global_load_dwordx2 v[86:87], v178, s[82:83]
	global_load_dwordx2 v[84:85], v179, s[82:83]
	global_load_dwordx2 v[82:83], v167, s[82:83]
	global_load_dwordx2 v[80:81], v79, s[82:83]
	v_lshlrev_b32_e32 v180, 16, v204
	v_and_b32_e32 v181, 0xffff0000, v204
	v_add_f32_e32 v180, 0, v180
	v_mfma_f32_32x32x16_bf16 v[0:15], v[182:185], v[16:19], v[0:15]
	v_add_f32_e32 v181, 0, v181
	v_lshlrev_b32_e32 v182, 16, v205
	v_and_b32_e32 v183, 0xffff0000, v205
	v_lshlrev_b32_e32 v184, 16, v208
	v_and_b32_e32 v185, 0xffff0000, v208
	v_add_f32_e32 v182, 0, v182
	v_add_f32_e32 v183, 0, v183
	v_mfma_f32_32x32x16_bf16 v[0:15], v[190:193], v[20:23], v[0:15]
	v_add_f32_e32 v184, 0, v184
	v_add_f32_e32 v185, 0, v185
	v_mfma_f32_32x32x16_bf16 v[0:15], v[194:197], v[24:27], v[0:15]
	v_mfma_f32_32x32x16_bf16 v[0:15], v[68:71], v[28:31], v[0:15]
	s_nop 11
	v_add_f32_e32 v68, v180, v0
	v_add_f32_e32 v69, v181, v1
	v_cvt_pk_bf16_f32 v0, v68, v69
	v_add_f32_e32 v2, v182, v2
	v_add_f32_e32 v3, v183, v3
	v_add_f32_e32 v4, v184, v4
	v_add_f32_e32 v5, v185, v5
	v_cvt_pk_bf16_f32 v1, v2, v3
	v_add_u32_e32 v252, v176, v240
	ds_write_b64 v241, v[0:1]
	v_cvt_pk_bf16_f32 v0, v4, v5
	v_add_f32_e32 v6, v187, v6
	v_add_f32_e32 v7, v188, v7
	v_cvt_pk_bf16_f32 v1, v6, v7
	ds_write_b64 v241, v[0:1] offset:16
	v_lshlrev_b32_e32 v0, 16, v91
	v_add_f32_e32 v0, 0, v0
	v_add_f32_e32 v10, v0, v10
	v_and_b32_e32 v0, 0xffff0000, v91
	v_add_f32_e32 v0, 0, v0
	v_add_f32_e32 v8, v189, v8
	v_add_f32_e32 v9, v90, v9
	v_add_f32_e32 v11, v0, v11
	v_cvt_pk_bf16_f32 v0, v8, v9
	v_cvt_pk_bf16_f32 v1, v10, v11
	ds_write_b64 v241, v[0:1] offset:32
	s_waitcnt vmcnt(14)
; DI unsigned cvt_pk_bf16(float lo, float hi) { unsigned r; asm volatile("v_cvt_pk_bf16_f32 %0, %1, %2" : "=v"(r) : "v"(lo), "v"(hi)); return r; }
; DI float bf_lo(unsigned w) { return __uint_as_float(w << 16); }
; DI float bf_hi(unsigned w) { return __uint_as_float(w & 0xffff0000u); }
; DI float shx(float v, int lane, int mask) { return __int_as_float(__builtin_amdgcn_ds_bpermute((lane ^ mask) << 2, __float_as_int(v))); }
; #define MFMA32(a, b, c) __builtin_amdgcn_mfma_f32_32x32x16_bf16((a), (b), (c), 0, 0, 0)
; template <bool DRY, bool H1>
; DI void intra_phase(LAS unsigned char* lds, const Params& p) {
;     ...
;       for (int t = 0; t < 8; ++t) {
;         if (t < 7) {
; #pragma unroll
;           for (int s = 0; s < 8; ++s) va[(t + 1) & 1][s] = ldg16(vT, vo + (unsigned)(t + 1) * 8192u + 1024u * s);
; #pragma unroll
;           for (int gq = 0; gq < 4; ++gq) { yold[(t + 1) & 1][gq] = *(const u32x2*)((const char*)y + (yo + 64u * (t + 1) + 16u * gq)); if constexpr (H1) yol2[(t + 1) & 1][gq] = *(const u32x2*)((const char*)yb + (yo + 64u * (t + 1) + 16u * gq)); }
;         }
;         f32x16 yt;
; #pragma unroll
;         for (int i = 0; i < 16; ++i) yt[i] = 0.f;
; #pragma unroll
;         for (int s = 0; s < 8; ++s) yt = MFMA32(va[t & 1][s], pf[s], yt);
; #pragma unroll
;         for (int gq = 0; gq < 4; ++gq) {
;           const u32x2 ov = yold[t & 1][gq], o2 = yol2[t & 1][gq];
;           const float v0 = bf_lo(ov.x) + bf_lo(o2.x) + yt[4 * gq], v1 = bf_hi(ov.x) + bf_hi(o2.x) + yt[4 * gq + 1], v2 = bf_lo(ov.y) + bf_lo(o2.y) + yt[4 * gq + 2], v3 = bf_hi(ov.y) + bf_hi(o2.y) + yt[4 * gq + 3];
;           sq2 += v0 * v0 + v1 * v1 + v2 * v2 + v3 * v3;
;           u32x2 a; a.x = cvt_pk_bf16(v0, v1); a.y = cvt_pk_bf16(v2, v3); if (!DRY || v0 == 12345.678f) *(u32x2*)((char*)y + (yo + 64u * t + 16u * gq)) = a;
;         }
;         __builtin_amdgcn_sched_barrier(0);
;       }
;       sq2 += shx(sq2, lane, 32);
;       if (h == 0 && (!DRY || sq2 == 12345.678f)) ss[((size_t)(tb + icol) * 4 + hd) * 16 + wh] = sq2;
	v_lshlrev_b32_e32 v0, 16, v88
	v_add_f32_e32 v0, 0, v0
	v_add_f32_e32 v12, v0, v12
	v_and_b32_e32 v0, 0xffff0000, v88
	v_add_f32_e32 v0, 0, v0
	v_add_f32_e32 v13, v0, v13
	v_lshlrev_b32_e32 v0, 16, v89
	v_add_f32_e32 v0, 0, v0
	v_add_f32_e32 v14, v0, v14
	v_and_b32_e32 v0, 0xffff0000, v89
	v_add_f32_e32 v0, 0, v0
	v_add_f32_e32 v15, v0, v15
	v_cvt_pk_bf16_f32 v0, v12, v13
	v_cvt_pk_bf16_f32 v1, v14, v15
	ds_write_b64 v241, v[0:1] offset:48
	s_waitcnt lgkmcnt(0)
	ds_read_b128 v[244:247], v242
	ds_read_b128 v[248:251], v242 offset:1152
	v_add_u32_e32 v253, 0x10000, v252
	s_waitcnt lgkmcnt(0)
	global_store_dwordx4 v252, v[244:247], s[82:83]
	global_store_dwordx4 v253, v[248:251], s[82:83]
	s_nop 1
	v_mul_f32_e32 v0, v69, v69
	v_fmac_f32_e32 v0, v68, v68
	v_mul_f32_e32 v1, v5, v5
	v_fmac_f32_e32 v0, v2, v2
	v_fmac_f32_e32 v1, v4, v4
	v_fmac_f32_e32 v0, v3, v3
	v_fmac_f32_e32 v1, v6, v6
	v_add_f32_e32 v0, v186, v0
	v_fmac_f32_e32 v1, v7, v7
	v_add_f32_e32 v0, v1, v0
	v_mul_f32_e32 v1, v9, v9
	v_fmac_f32_e32 v1, v8, v8
	v_fmac_f32_e32 v1, v10, v10
	v_fmac_f32_e32 v1, v11, v11
	v_add_f32_e32 v0, v1, v0
	v_mul_f32_e32 v1, v13, v13
	v_fmac_f32_e32 v1, v12, v12
	v_fmac_f32_e32 v1, v14, v14
	v_fmac_f32_e32 v1, v15, v15
	v_add_f32_e32 v68, v1, v0
	s_waitcnt vmcnt(13)
	v_mfma_f32_32x32x16_bf16 v[0:15], v[168:171], v[36:39], 0
	s_waitcnt vmcnt(12)
	v_mfma_f32_32x32x16_bf16 v[0:15], v[172:175], v[32:35], v[0:15]
	s_waitcnt vmcnt(11)
	v_mfma_f32_32x32x16_bf16 v[0:15], v[72:75], v[44:47], v[0:15]
	s_waitcnt vmcnt(10)
	v_mfma_f32_32x32x16_bf16 v[0:15], v[64:67], v[40:43], v[0:15]
	s_waitcnt vmcnt(9)
	v_mfma_f32_32x32x16_bf16 v[0:15], v[48:51], v[16:19], v[0:15]
	s_waitcnt vmcnt(5)
	v_lshlrev_b32_e32 v16, 16, v86
	v_add_f32_e32 v16, 0, v16
	v_mfma_f32_32x32x16_bf16 v[0:15], v[52:55], v[20:23], v[0:15]
	v_mfma_f32_32x32x16_bf16 v[0:15], v[56:59], v[24:27], v[0:15]
	v_mfma_f32_32x32x16_bf16 v[0:15], v[60:63], v[28:31], v[0:15]
	s_nop 11
	v_add_f32_e32 v0, v16, v0
	v_and_b32_e32 v16, 0xffff0000, v86
	v_add_f32_e32 v16, 0, v16
	v_add_f32_e32 v1, v16, v1
	v_lshlrev_b32_e32 v16, 16, v87
	v_add_f32_e32 v16, 0, v16
	v_add_f32_e32 v2, v16, v2
	v_and_b32_e32 v16, 0xffff0000, v87
	v_add_f32_e32 v16, 0, v16
	v_add_f32_e32 v3, v16, v3
	v_mul_f32_e32 v16, v1, v1
	v_fmac_f32_e32 v16, v0, v0
	v_cvt_pk_bf16_f32 v0, v0, v1
	v_cvt_pk_bf16_f32 v1, v2, v3
	v_add_u32_e32 v252, v178, v240
	ds_write_b64 v241, v[0:1]
	s_waitcnt vmcnt(4)
	v_and_b32_e32 v1, 0xffff0000, v84
	v_fmac_f32_e32 v16, v2, v2
	v_lshlrev_b32_e32 v0, 16, v84
	v_add_f32_e32 v1, 0, v1
	v_fmac_f32_e32 v16, v3, v3
	v_add_f32_e32 v0, 0, v0
	v_add_f32_e32 v1, v1, v5
	v_lshlrev_b32_e32 v2, 16, v85
	v_and_b32_e32 v3, 0xffff0000, v85
	v_add_f32_e32 v0, v0, v4
	v_add_f32_e32 v2, 0, v2
	v_add_f32_e32 v3, 0, v3
	v_mul_f32_e32 v4, v1, v1
	v_add_f32_e32 v2, v2, v6
	v_add_f32_e32 v3, v3, v7
	v_fmac_f32_e32 v4, v0, v0
	v_cvt_pk_bf16_f32 v0, v0, v1
	v_cvt_pk_bf16_f32 v1, v2, v3
	ds_write_b64 v241, v[0:1] offset:16
	s_waitcnt vmcnt(3)
	v_and_b32_e32 v1, 0xffff0000, v82
	v_lshlrev_b32_e32 v0, 16, v82
	v_add_f32_e32 v1, 0, v1
	v_fmac_f32_e32 v4, v2, v2
	v_add_f32_e32 v0, 0, v0
	v_add_f32_e32 v1, v1, v9
	v_fmac_f32_e32 v4, v3, v3
	v_add_f32_e32 v0, v0, v8
	v_lshlrev_b32_e32 v2, 16, v83
	v_and_b32_e32 v3, 0xffff0000, v83
	v_mul_f32_e32 v5, v1, v1
	v_add_f32_e32 v2, 0, v2
	v_add_f32_e32 v3, 0, v3
	v_fmac_f32_e32 v5, v0, v0
	v_cvt_pk_bf16_f32 v0, v0, v1
	v_add_f32_e32 v2, v2, v10
	v_add_f32_e32 v3, v3, v11
	v_cvt_pk_bf16_f32 v1, v2, v3
	ds_write_b64 v241, v[0:1] offset:32
	s_waitcnt vmcnt(2)
	v_lshlrev_b32_e32 v0, 16, v80
	v_add_f32_e32 v0, 0, v0
	v_add_f32_e32 v1, v0, v12
	v_and_b32_e32 v0, 0xffff0000, v80
	v_add_f32_e32 v0, 0, v0
	v_fmac_f32_e32 v5, v2, v2
	v_add_f32_e32 v2, v0, v13
	v_lshlrev_b32_e32 v0, 16, v81
	v_add_f32_e32 v0, 0, v0
	v_add_f32_e32 v16, v68, v16
	v_fmac_f32_e32 v5, v3, v3
	v_add_f32_e32 v3, v0, v14
	v_and_b32_e32 v0, 0xffff0000, v81
	v_add_f32_e32 v4, v4, v16
	v_add_f32_e32 v0, 0, v0
	v_add_f32_e32 v4, v5, v4
	v_add_f32_e32 v5, v0, v15
	v_mul_f32_e32 v0, v2, v2
	v_fmac_f32_e32 v0, v1, v1
	v_fmac_f32_e32 v0, v3, v3
	v_fmac_f32_e32 v0, v5, v5
	v_add_f32_e32 v0, v0, v4
	v_cvt_pk_bf16_f32 v2, v1, v2
	v_cvt_pk_bf16_f32 v3, v3, v5
	ds_write_b64 v241, v[2:3] offset:48
	s_waitcnt lgkmcnt(0)
	ds_read_b128 v[244:247], v242
	ds_read_b128 v[248:251], v242 offset:1152
	v_add_u32_e32 v253, 0x10000, v252
	s_waitcnt lgkmcnt(0)
	global_store_dwordx4 v252, v[244:247], s[82:83]
	global_store_dwordx4 v253, v[248:251], s[82:83]
	s_nop 1
	ds_bpermute_b32 v1, v96, v0
	v_readlane_b32 s60, v255, 47
	v_readlane_b32 s61, v255, 48
	s_and_saveexec_b64 s[96:97], s[60:61]
	s_cbranch_execz .LBB0_57
	v_ashrrev_i32_e32 v79, 31, v78
	v_readlane_b32 s60, v255, 45
	s_waitcnt lgkmcnt(0)
	v_add_f32_e32 v2, v0, v1
	v_lshlrev_b64 v[0:1], 8, v[78:79]
	v_readlane_b32 s61, v255, 46
	s_lshl_b32 s94, s94, 6
	s_nop 0
	v_lshl_add_u64 v[0:1], s[60:61], 0, v[0:1]
	v_lshl_add_u64 v[0:1], v[0:1], 0, s[94:95]
	v_lshl_add_u64 v[0:1], v[76:77], 2, v[0:1]
	global_store_dword v[0:1], v2, off
	s_branch .LBB0_57
